# bundle16 + segment boundary: s_setprio 1 issued before a single merged s_waitcnt vmcnt(N) lgkmcnt(0) (two fewer issue slots between LDS data arrival and the barrier)
# speedup vs baseline: 1.0036x; 1.0036x over previous
.LBB0_292:
	s_ashr_i32 s13, s12, 31
	s_lshl_b64 s[14:15], s[12:13], 20
	s_add_u32 s14, s19, s14
	s_addc_u32 s15, s22, s15
	s_and_b64 s[16:17], s[2:3], exec
	s_cselect_b32 s13, s15, s41
	s_cselect_b32 s74, s14, s40
	s_ashr_i32 s11, s10, 31
	s_lshl_b64 s[16:17], s[10:11], 20
	s_add_u32 s16, s23, s16
	s_addc_u32 s17, s28, s17
	s_and_b64 s[54:55], s[2:3], exec
	s_cselect_b32 s11, s17, s43
	s_cselect_b32 s75, s16, s42
	s_add_u32 s40, s40, 0x80080
	s_addc_u32 s41, s41, 0
	s_add_u32 s76, s42, 0x100
	s_addc_u32 s77, s43, 0
	s_mov_b32 s78, -2
	ds_read_b128 v[146:149], v153
	ds_read_b128 v[156:159], v153 offset:1024
	ds_read_b128 v[160:163], v153 offset:2048
	ds_read_b128 v[164:167], v153 offset:3072
	ds_read_b128 v[168:171], v154
	ds_read_b128 v[172:175], v154 offset:1024
	ds_read_b128 v[180:183], v154 offset:2048
	ds_read_b128 v[184:187], v154 offset:3072
	s_add_u32 s42, s40, 0xfff80080
	s_addc_u32 s43, s41, -1
	s_cmp_eq_u32 s78, 28
	s_cselect_b32 s55, s13, s43
	s_cselect_b32 s54, s74, s42
	s_cselect_b32 s43, s11, s77
	s_cselect_b32 s42, s75, s76
	s_add_i32 m0, s35, 0xc000
	ds_read_b128 v[188:191], v155
	ds_read_b128 v[192:195], v155 offset:1024
	ds_read_b128 v[196:199], v155 offset:2048
	ds_read_b128 v[200:203], v155 offset:3072
	ds_read_b128 v[204:207], v155 offset:4096
	ds_read_b128 v[208:211], v155 offset:5120
	ds_read_b128 v[212:215], v155 offset:6144
	ds_read_b128 v[216:219], v155 offset:7168
	global_load_lds_dwordx4 v138, s[40:41]
	s_add_i32 m0, s35, 0xe000
	s_nop 0
	global_load_lds_dwordx4 v140, s[40:41]
	s_setprio 1
	s_waitcnt vmcnt(8) lgkmcnt(0)
	s_barrier
	v_mfma_f32_16x16x32_bf16 v[126:129], v[146:149], v[188:191], 0
	v_mfma_f32_16x16x32_bf16 v[118:121], v[160:163], v[188:191], 0
	v_mfma_f32_16x16x32_bf16 v[110:113], v[146:149], v[196:199], 0
	v_mfma_f32_16x16x32_bf16 v[102:105], v[160:163], v[196:199], 0
	v_mfma_f32_16x16x32_bf16 v[94:97], v[146:149], v[204:207], 0
	v_mfma_f32_16x16x32_bf16 v[86:89], v[160:163], v[204:207], 0
	v_mfma_f32_16x16x32_bf16 v[78:81], v[146:149], v[212:215], 0
	v_mfma_f32_16x16x32_bf16 v[70:73], v[160:163], v[212:215], 0
	v_mfma_f32_16x16x32_bf16 v[126:129], v[156:159], v[192:195], v[126:129]
	v_mfma_f32_16x16x32_bf16 v[118:121], v[164:167], v[192:195], v[118:121]
	v_mfma_f32_16x16x32_bf16 v[110:113], v[156:159], v[200:203], v[110:113]
	v_mfma_f32_16x16x32_bf16 v[102:105], v[164:167], v[200:203], v[102:105]
	v_mfma_f32_16x16x32_bf16 v[94:97], v[156:159], v[208:211], v[94:97]
	v_mfma_f32_16x16x32_bf16 v[86:89], v[164:167], v[208:211], v[86:89]
	v_mfma_f32_16x16x32_bf16 v[78:81], v[156:159], v[216:219], v[78:81]
	v_mfma_f32_16x16x32_bf16 v[70:73], v[164:167], v[216:219], v[70:73]
	s_setprio 0
	s_setprio 1
	v_mfma_f32_16x16x32_bf16 v[122:125], v[168:171], v[188:191], 0
	v_mfma_f32_16x16x32_bf16 v[114:117], v[180:183], v[188:191], 0
	v_mfma_f32_16x16x32_bf16 v[106:109], v[168:171], v[196:199], 0
	v_mfma_f32_16x16x32_bf16 v[98:101], v[180:183], v[196:199], 0
	v_mfma_f32_16x16x32_bf16 v[90:93], v[168:171], v[204:207], 0
	v_mfma_f32_16x16x32_bf16 v[82:85], v[180:183], v[204:207], 0
	v_mfma_f32_16x16x32_bf16 v[74:77], v[168:171], v[212:215], 0
	v_mfma_f32_16x16x32_bf16 v[66:69], v[180:183], v[212:215], 0
	v_mfma_f32_16x16x32_bf16 v[122:125], v[172:175], v[192:195], v[122:125]
	v_mfma_f32_16x16x32_bf16 v[114:117], v[184:187], v[192:195], v[114:117]
	v_mfma_f32_16x16x32_bf16 v[106:109], v[172:175], v[200:203], v[106:109]
	v_mfma_f32_16x16x32_bf16 v[98:101], v[184:187], v[200:203], v[98:101]
	v_mfma_f32_16x16x32_bf16 v[90:93], v[172:175], v[208:211], v[90:93]
	v_mfma_f32_16x16x32_bf16 v[82:85], v[184:187], v[208:211], v[82:85]
	v_mfma_f32_16x16x32_bf16 v[74:77], v[172:175], v[216:219], v[74:77]
	v_mfma_f32_16x16x32_bf16 v[66:69], v[184:187], v[216:219], v[66:69]
	s_barrier
	s_setprio 0
	s_add_i32 s79, s70, s29
	s_add_u32 s98, s42, 0x80
	s_addc_u32 s99, s43, 0
	s_mov_b32 m0, s79
	ds_read_b128 v[188:191], v155 offset:16384
	ds_read_b128 v[192:195], v155 offset:17408
	ds_read_b128 v[196:199], v155 offset:18432
	ds_read_b128 v[200:203], v155 offset:19456
	ds_read_b128 v[204:207], v155 offset:20480
	ds_read_b128 v[208:211], v155 offset:21504
	ds_read_b128 v[212:215], v155 offset:22528
	ds_read_b128 v[216:219], v155 offset:23552
	global_load_lds_dwordx4 v134, s[42:43]
	s_add_i32 m0, s79, 0x2000
	s_add_u32 s80, s42, 0x80000
	s_addc_u32 s81, s43, 0
	s_add_i32 s79, s71, s29
	global_load_lds_dwordx4 v130, s[42:43]
	s_mov_b32 m0, s79
	s_nop 0
	global_load_lds_dwordx4 v134, s[80:81]
	s_add_i32 m0, s79, 0x2000
	s_nop 0
	global_load_lds_dwordx4 v130, s[80:81]
	s_add_u32 s100, s54, 0x80
	s_addc_u32 s101, s55, 0
	s_mov_b32 m0, s35
	s_nop 0
	global_load_lds_dwordx4 v136, s[54:55]
	s_mov_b32 m0, s57
	s_nop 0
	global_load_lds_dwordx4 v132, s[54:55]
	s_setprio 1
	s_waitcnt vmcnt(8) lgkmcnt(0)
	s_barrier
	v_mfma_f32_16x16x32_bf16 v[62:65], v[146:149], v[188:191], 0
	v_mfma_f32_16x16x32_bf16 v[54:57], v[160:163], v[188:191], 0
	v_mfma_f32_16x16x32_bf16 v[46:49], v[146:149], v[196:199], 0
	v_mfma_f32_16x16x32_bf16 v[38:41], v[160:163], v[196:199], 0
	v_mfma_f32_16x16x32_bf16 v[30:33], v[146:149], v[204:207], 0
	v_mfma_f32_16x16x32_bf16 v[22:25], v[160:163], v[204:207], 0
	v_mfma_f32_16x16x32_bf16 v[14:17], v[146:149], v[212:215], 0
	v_mfma_f32_16x16x32_bf16 v[6:9], v[160:163], v[212:215], 0
	v_mfma_f32_16x16x32_bf16 v[62:65], v[156:159], v[192:195], v[62:65]
	v_mfma_f32_16x16x32_bf16 v[54:57], v[164:167], v[192:195], v[54:57]
	v_mfma_f32_16x16x32_bf16 v[46:49], v[156:159], v[200:203], v[46:49]
	v_mfma_f32_16x16x32_bf16 v[38:41], v[164:167], v[200:203], v[38:41]
	v_mfma_f32_16x16x32_bf16 v[30:33], v[156:159], v[208:211], v[30:33]
	v_mfma_f32_16x16x32_bf16 v[22:25], v[164:167], v[208:211], v[22:25]
	v_mfma_f32_16x16x32_bf16 v[14:17], v[156:159], v[216:219], v[14:17]
	v_mfma_f32_16x16x32_bf16 v[6:9], v[164:167], v[216:219], v[6:9]
	s_setprio 0
	s_setprio 1
	v_mfma_f32_16x16x32_bf16 v[58:61], v[168:171], v[188:191], 0
	v_mfma_f32_16x16x32_bf16 v[50:53], v[180:183], v[188:191], 0
	v_mfma_f32_16x16x32_bf16 v[42:45], v[168:171], v[196:199], 0
	v_mfma_f32_16x16x32_bf16 v[34:37], v[180:183], v[196:199], 0
	v_mfma_f32_16x16x32_bf16 v[26:29], v[168:171], v[204:207], 0
	v_mfma_f32_16x16x32_bf16 v[18:21], v[180:183], v[204:207], 0
	v_mfma_f32_16x16x32_bf16 v[10:13], v[168:171], v[212:215], 0
	v_mfma_f32_16x16x32_bf16 v[2:5], v[180:183], v[212:215], 0
	v_mfma_f32_16x16x32_bf16 v[58:61], v[172:175], v[192:195], v[58:61]
	v_mfma_f32_16x16x32_bf16 v[50:53], v[184:187], v[192:195], v[50:53]
	v_mfma_f32_16x16x32_bf16 v[42:45], v[172:175], v[200:203], v[42:45]
	v_mfma_f32_16x16x32_bf16 v[34:37], v[184:187], v[200:203], v[34:37]
	v_mfma_f32_16x16x32_bf16 v[26:29], v[172:175], v[208:211], v[26:29]
	v_mfma_f32_16x16x32_bf16 v[18:21], v[184:187], v[208:211], v[18:21]
	v_mfma_f32_16x16x32_bf16 v[10:13], v[172:175], v[216:219], v[10:13]
	v_mfma_f32_16x16x32_bf16 v[2:5], v[184:187], v[216:219], v[2:5]
	s_barrier
	s_setprio 0
	s_add_i32 s79, 0, 0x18000
	s_add_i32 s80, 0, 0x1c000
	ds_read_b128 v[146:149], v153 offset:32768
	ds_read_b128 v[156:159], v153 offset:33792
	ds_read_b128 v[160:163], v153 offset:34816
	ds_read_b128 v[164:167], v153 offset:35840
	ds_read_b128 v[168:171], v154 offset:32768
	ds_read_b128 v[172:175], v154 offset:33792
	ds_read_b128 v[180:183], v154 offset:34816
	ds_read_b128 v[184:187], v154 offset:35840
	s_add_u32 s54, s54, 0x80000
	s_addc_u32 s55, s55, 0
	s_mov_b32 m0, s58
	ds_read_b128 v[188:191], v155 offset:32768
	ds_read_b128 v[192:195], v155 offset:33792
	ds_read_b128 v[196:199], v155 offset:34816
	ds_read_b128 v[200:203], v155 offset:35840
	ds_read_b128 v[204:207], v155 offset:36864
	ds_read_b128 v[208:211], v155 offset:37888
	ds_read_b128 v[212:215], v155 offset:38912
	ds_read_b128 v[216:219], v155 offset:39936
	global_load_lds_dwordx4 v136, s[54:55]
	s_mov_b32 m0, s59
	s_nop 0
	global_load_lds_dwordx4 v132, s[54:55]
	s_setprio 1
	s_waitcnt vmcnt(8) lgkmcnt(0)
	s_barrier
	v_mfma_f32_16x16x32_bf16 v[126:129], v[146:149], v[188:191], v[126:129]
	v_mfma_f32_16x16x32_bf16 v[118:121], v[160:163], v[188:191], v[118:121]
	v_mfma_f32_16x16x32_bf16 v[110:113], v[146:149], v[196:199], v[110:113]
	v_mfma_f32_16x16x32_bf16 v[102:105], v[160:163], v[196:199], v[102:105]
	v_mfma_f32_16x16x32_bf16 v[94:97], v[146:149], v[204:207], v[94:97]
	v_mfma_f32_16x16x32_bf16 v[86:89], v[160:163], v[204:207], v[86:89]
	v_mfma_f32_16x16x32_bf16 v[78:81], v[146:149], v[212:215], v[78:81]
	v_mfma_f32_16x16x32_bf16 v[70:73], v[160:163], v[212:215], v[70:73]
	v_mfma_f32_16x16x32_bf16 v[126:129], v[156:159], v[192:195], v[126:129]
	v_mfma_f32_16x16x32_bf16 v[118:121], v[164:167], v[192:195], v[118:121]
	v_mfma_f32_16x16x32_bf16 v[110:113], v[156:159], v[200:203], v[110:113]
	v_mfma_f32_16x16x32_bf16 v[102:105], v[164:167], v[200:203], v[102:105]
	v_mfma_f32_16x16x32_bf16 v[94:97], v[156:159], v[208:211], v[94:97]
	v_mfma_f32_16x16x32_bf16 v[86:89], v[164:167], v[208:211], v[86:89]
	v_mfma_f32_16x16x32_bf16 v[78:81], v[156:159], v[216:219], v[78:81]
	v_mfma_f32_16x16x32_bf16 v[70:73], v[164:167], v[216:219], v[70:73]
	s_setprio 0
	s_setprio 1
	v_mfma_f32_16x16x32_bf16 v[122:125], v[168:171], v[188:191], v[122:125]
	v_mfma_f32_16x16x32_bf16 v[114:117], v[180:183], v[188:191], v[114:117]
	v_mfma_f32_16x16x32_bf16 v[106:109], v[168:171], v[196:199], v[106:109]
	v_mfma_f32_16x16x32_bf16 v[98:101], v[180:183], v[196:199], v[98:101]
	v_mfma_f32_16x16x32_bf16 v[90:93], v[168:171], v[204:207], v[90:93]
	v_mfma_f32_16x16x32_bf16 v[82:85], v[180:183], v[204:207], v[82:85]
	v_mfma_f32_16x16x32_bf16 v[74:77], v[168:171], v[212:215], v[74:77]
	v_mfma_f32_16x16x32_bf16 v[66:69], v[180:183], v[212:215], v[66:69]
	v_mfma_f32_16x16x32_bf16 v[122:125], v[172:175], v[192:195], v[122:125]
	v_mfma_f32_16x16x32_bf16 v[114:117], v[184:187], v[192:195], v[114:117]
	v_mfma_f32_16x16x32_bf16 v[106:109], v[172:175], v[200:203], v[106:109]
	v_mfma_f32_16x16x32_bf16 v[98:101], v[184:187], v[200:203], v[98:101]
	v_mfma_f32_16x16x32_bf16 v[90:93], v[172:175], v[208:211], v[90:93]
	v_mfma_f32_16x16x32_bf16 v[82:85], v[184:187], v[208:211], v[82:85]
	v_mfma_f32_16x16x32_bf16 v[74:77], v[172:175], v[216:219], v[74:77]
	v_mfma_f32_16x16x32_bf16 v[66:69], v[184:187], v[216:219], v[66:69]
	s_barrier
	s_setprio 0
	s_add_i32 s54, s79, s29
	s_mov_b32 m0, s54
	ds_read_b128 v[188:191], v155 offset:49152
	ds_read_b128 v[192:195], v155 offset:50176
	ds_read_b128 v[196:199], v155 offset:51200
	ds_read_b128 v[200:203], v155 offset:52224
	ds_read_b128 v[204:207], v155 offset:53248
	ds_read_b128 v[208:211], v155 offset:54272
	ds_read_b128 v[212:215], v155 offset:55296
	ds_read_b128 v[216:219], v155 offset:56320
	global_load_lds_dwordx4 v134, s[98:99]
	s_add_i32 m0, s54, 0x2000
	s_add_u32 s42, s42, 0x80080
	s_addc_u32 s43, s43, 0
	s_add_i32 s54, s80, s29
	global_load_lds_dwordx4 v130, s[98:99]
	s_mov_b32 m0, s54
	s_nop 0
	global_load_lds_dwordx4 v134, s[42:43]
	s_add_i32 m0, s54, 0x2000
	s_nop 0
	global_load_lds_dwordx4 v130, s[42:43]
	s_mov_b32 m0, s64
	s_nop 0
	global_load_lds_dwordx4 v136, s[100:101]
	s_mov_b32 m0, s65
	s_nop 0
	global_load_lds_dwordx4 v132, s[100:101]
	s_setprio 1
	s_waitcnt vmcnt(8) lgkmcnt(0)
	s_barrier
	v_mfma_f32_16x16x32_bf16 v[62:65], v[146:149], v[188:191], v[62:65]
	v_mfma_f32_16x16x32_bf16 v[54:57], v[160:163], v[188:191], v[54:57]
	v_mfma_f32_16x16x32_bf16 v[46:49], v[146:149], v[196:199], v[46:49]
	v_mfma_f32_16x16x32_bf16 v[38:41], v[160:163], v[196:199], v[38:41]
	v_mfma_f32_16x16x32_bf16 v[30:33], v[146:149], v[204:207], v[30:33]
	v_mfma_f32_16x16x32_bf16 v[22:25], v[160:163], v[204:207], v[22:25]
	v_mfma_f32_16x16x32_bf16 v[14:17], v[146:149], v[212:215], v[14:17]
	v_mfma_f32_16x16x32_bf16 v[6:9], v[160:163], v[212:215], v[6:9]
	v_mfma_f32_16x16x32_bf16 v[62:65], v[156:159], v[192:195], v[62:65]
	v_mfma_f32_16x16x32_bf16 v[54:57], v[164:167], v[192:195], v[54:57]
	v_mfma_f32_16x16x32_bf16 v[46:49], v[156:159], v[200:203], v[46:49]
	v_mfma_f32_16x16x32_bf16 v[38:41], v[164:167], v[200:203], v[38:41]
	v_mfma_f32_16x16x32_bf16 v[30:33], v[156:159], v[208:211], v[30:33]
	v_mfma_f32_16x16x32_bf16 v[22:25], v[164:167], v[208:211], v[22:25]
	v_mfma_f32_16x16x32_bf16 v[14:17], v[156:159], v[216:219], v[14:17]
	v_mfma_f32_16x16x32_bf16 v[6:9], v[164:167], v[216:219], v[6:9]
	s_setprio 0
	s_setprio 1
	v_mfma_f32_16x16x32_bf16 v[58:61], v[168:171], v[188:191], v[58:61]
	v_mfma_f32_16x16x32_bf16 v[50:53], v[180:183], v[188:191], v[50:53]
	v_mfma_f32_16x16x32_bf16 v[42:45], v[168:171], v[196:199], v[42:45]
	v_mfma_f32_16x16x32_bf16 v[34:37], v[180:183], v[196:199], v[34:37]
	v_mfma_f32_16x16x32_bf16 v[26:29], v[168:171], v[204:207], v[26:29]
	v_mfma_f32_16x16x32_bf16 v[18:21], v[180:183], v[204:207], v[18:21]
	v_mfma_f32_16x16x32_bf16 v[10:13], v[168:171], v[212:215], v[10:13]
	v_mfma_f32_16x16x32_bf16 v[2:5], v[180:183], v[212:215], v[2:5]
	v_mfma_f32_16x16x32_bf16 v[58:61], v[172:175], v[192:195], v[58:61]
	v_mfma_f32_16x16x32_bf16 v[50:53], v[184:187], v[192:195], v[50:53]
	v_mfma_f32_16x16x32_bf16 v[42:45], v[172:175], v[200:203], v[42:45]
	v_mfma_f32_16x16x32_bf16 v[34:37], v[184:187], v[200:203], v[34:37]
	v_mfma_f32_16x16x32_bf16 v[26:29], v[172:175], v[208:211], v[26:29]
	v_mfma_f32_16x16x32_bf16 v[18:21], v[184:187], v[208:211], v[18:21]
	v_mfma_f32_16x16x32_bf16 v[10:13], v[172:175], v[216:219], v[10:13]
	v_mfma_f32_16x16x32_bf16 v[2:5], v[184:187], v[216:219], v[2:5]
	s_barrier
	s_setprio 0
	s_add_i32 s78, s78, 2
	s_add_u32 s40, s40, 0x100
	s_addc_u32 s41, s41, 0
	s_add_u32 s76, s76, 0x100
	s_addc_u32 s77, s77, 0
	s_cmp_gt_u32 s78, 29
.LBB0_293:
	ds_read_b128 v[146:149], v153
	ds_read_b128 v[156:159], v153 offset:1024
	ds_read_b128 v[160:163], v153 offset:2048
	ds_read_b128 v[164:167], v153 offset:3072
	ds_read_b128 v[168:171], v154
	ds_read_b128 v[172:175], v154 offset:1024
	ds_read_b128 v[180:183], v154 offset:2048
	ds_read_b128 v[184:187], v154 offset:3072
	s_add_u32 s42, s40, 0xfff80080
	s_addc_u32 s43, s41, -1
	s_cmp_eq_u32 s78, 28
	s_cselect_b32 s55, s13, s43
	s_cselect_b32 s54, s74, s42
	s_cselect_b32 s43, s11, s77
	s_cselect_b32 s42, s75, s76
	s_add_i32 m0, s35, 0xc000
	ds_read_b128 v[188:191], v155
	ds_read_b128 v[192:195], v155 offset:1024
	ds_read_b128 v[196:199], v155 offset:2048
	ds_read_b128 v[200:203], v155 offset:3072
	ds_read_b128 v[204:207], v155 offset:4096
	ds_read_b128 v[208:211], v155 offset:5120
	ds_read_b128 v[212:215], v155 offset:6144
	ds_read_b128 v[216:219], v155 offset:7168
	global_load_lds_dwordx4 v138, s[40:41]
	s_add_i32 m0, s35, 0xe000
	s_nop 0
	global_load_lds_dwordx4 v140, s[40:41]
	s_setprio 1
	s_waitcnt vmcnt(8) lgkmcnt(0)
	s_barrier
	v_mfma_f32_16x16x32_bf16 v[126:129], v[146:149], v[188:191], v[126:129]
	v_mfma_f32_16x16x32_bf16 v[118:121], v[160:163], v[188:191], v[118:121]
	v_mfma_f32_16x16x32_bf16 v[110:113], v[146:149], v[196:199], v[110:113]
	v_mfma_f32_16x16x32_bf16 v[102:105], v[160:163], v[196:199], v[102:105]
	v_mfma_f32_16x16x32_bf16 v[94:97], v[146:149], v[204:207], v[94:97]
	v_mfma_f32_16x16x32_bf16 v[86:89], v[160:163], v[204:207], v[86:89]
	v_mfma_f32_16x16x32_bf16 v[78:81], v[146:149], v[212:215], v[78:81]
	v_mfma_f32_16x16x32_bf16 v[70:73], v[160:163], v[212:215], v[70:73]
	v_mfma_f32_16x16x32_bf16 v[126:129], v[156:159], v[192:195], v[126:129]
	v_mfma_f32_16x16x32_bf16 v[118:121], v[164:167], v[192:195], v[118:121]
	v_mfma_f32_16x16x32_bf16 v[110:113], v[156:159], v[200:203], v[110:113]
	v_mfma_f32_16x16x32_bf16 v[102:105], v[164:167], v[200:203], v[102:105]
	v_mfma_f32_16x16x32_bf16 v[94:97], v[156:159], v[208:211], v[94:97]
	v_mfma_f32_16x16x32_bf16 v[86:89], v[164:167], v[208:211], v[86:89]
	v_mfma_f32_16x16x32_bf16 v[78:81], v[156:159], v[216:219], v[78:81]
	v_mfma_f32_16x16x32_bf16 v[70:73], v[164:167], v[216:219], v[70:73]
	s_setprio 0
	s_setprio 1
	v_mfma_f32_16x16x32_bf16 v[122:125], v[168:171], v[188:191], v[122:125]
	v_mfma_f32_16x16x32_bf16 v[114:117], v[180:183], v[188:191], v[114:117]
	v_mfma_f32_16x16x32_bf16 v[106:109], v[168:171], v[196:199], v[106:109]
	v_mfma_f32_16x16x32_bf16 v[98:101], v[180:183], v[196:199], v[98:101]
	v_mfma_f32_16x16x32_bf16 v[90:93], v[168:171], v[204:207], v[90:93]
	v_mfma_f32_16x16x32_bf16 v[82:85], v[180:183], v[204:207], v[82:85]
	v_mfma_f32_16x16x32_bf16 v[74:77], v[168:171], v[212:215], v[74:77]
	v_mfma_f32_16x16x32_bf16 v[66:69], v[180:183], v[212:215], v[66:69]
	v_mfma_f32_16x16x32_bf16 v[122:125], v[172:175], v[192:195], v[122:125]
	v_mfma_f32_16x16x32_bf16 v[114:117], v[184:187], v[192:195], v[114:117]
	v_mfma_f32_16x16x32_bf16 v[106:109], v[172:175], v[200:203], v[106:109]
	v_mfma_f32_16x16x32_bf16 v[98:101], v[184:187], v[200:203], v[98:101]
	v_mfma_f32_16x16x32_bf16 v[90:93], v[172:175], v[208:211], v[90:93]
	v_mfma_f32_16x16x32_bf16 v[82:85], v[184:187], v[208:211], v[82:85]
	v_mfma_f32_16x16x32_bf16 v[74:77], v[172:175], v[216:219], v[74:77]
	v_mfma_f32_16x16x32_bf16 v[66:69], v[184:187], v[216:219], v[66:69]
	s_barrier
	s_setprio 0
	s_add_i32 s79, s70, s29
	s_add_u32 s98, s42, 0x80
	s_addc_u32 s99, s43, 0
	s_mov_b32 m0, s79
	ds_read_b128 v[188:191], v155 offset:16384
	ds_read_b128 v[192:195], v155 offset:17408
	ds_read_b128 v[196:199], v155 offset:18432
	ds_read_b128 v[200:203], v155 offset:19456
	ds_read_b128 v[204:207], v155 offset:20480
	ds_read_b128 v[208:211], v155 offset:21504
	ds_read_b128 v[212:215], v155 offset:22528
	ds_read_b128 v[216:219], v155 offset:23552
	global_load_lds_dwordx4 v134, s[42:43]
	s_add_i32 m0, s79, 0x2000
	s_add_u32 s80, s42, 0x80000
	s_addc_u32 s81, s43, 0
	s_add_i32 s79, s71, s29
	global_load_lds_dwordx4 v130, s[42:43]
	s_mov_b32 m0, s79
	s_nop 0
	global_load_lds_dwordx4 v134, s[80:81]
	s_add_i32 m0, s79, 0x2000
	s_nop 0
	global_load_lds_dwordx4 v130, s[80:81]
	s_add_u32 s100, s54, 0x80
	s_addc_u32 s101, s55, 0
	s_mov_b32 m0, s35
	s_nop 0
	global_load_lds_dwordx4 v136, s[54:55]
	s_mov_b32 m0, s57
	s_nop 0
	global_load_lds_dwordx4 v132, s[54:55]
	s_setprio 1
	s_waitcnt vmcnt(8) lgkmcnt(0)
	s_barrier
	v_mfma_f32_16x16x32_bf16 v[62:65], v[146:149], v[188:191], v[62:65]
	v_mfma_f32_16x16x32_bf16 v[54:57], v[160:163], v[188:191], v[54:57]
	v_mfma_f32_16x16x32_bf16 v[46:49], v[146:149], v[196:199], v[46:49]
	v_mfma_f32_16x16x32_bf16 v[38:41], v[160:163], v[196:199], v[38:41]
	v_mfma_f32_16x16x32_bf16 v[30:33], v[146:149], v[204:207], v[30:33]
	v_mfma_f32_16x16x32_bf16 v[22:25], v[160:163], v[204:207], v[22:25]
	v_mfma_f32_16x16x32_bf16 v[14:17], v[146:149], v[212:215], v[14:17]
	v_mfma_f32_16x16x32_bf16 v[6:9], v[160:163], v[212:215], v[6:9]
	v_mfma_f32_16x16x32_bf16 v[62:65], v[156:159], v[192:195], v[62:65]
	v_mfma_f32_16x16x32_bf16 v[54:57], v[164:167], v[192:195], v[54:57]
	v_mfma_f32_16x16x32_bf16 v[46:49], v[156:159], v[200:203], v[46:49]
	v_mfma_f32_16x16x32_bf16 v[38:41], v[164:167], v[200:203], v[38:41]
	v_mfma_f32_16x16x32_bf16 v[30:33], v[156:159], v[208:211], v[30:33]
	v_mfma_f32_16x16x32_bf16 v[22:25], v[164:167], v[208:211], v[22:25]
	v_mfma_f32_16x16x32_bf16 v[14:17], v[156:159], v[216:219], v[14:17]
	v_mfma_f32_16x16x32_bf16 v[6:9], v[164:167], v[216:219], v[6:9]
	s_setprio 0
	s_setprio 1
	v_mfma_f32_16x16x32_bf16 v[58:61], v[168:171], v[188:191], v[58:61]
	v_mfma_f32_16x16x32_bf16 v[50:53], v[180:183], v[188:191], v[50:53]
	v_mfma_f32_16x16x32_bf16 v[42:45], v[168:171], v[196:199], v[42:45]
	v_mfma_f32_16x16x32_bf16 v[34:37], v[180:183], v[196:199], v[34:37]
	v_mfma_f32_16x16x32_bf16 v[26:29], v[168:171], v[204:207], v[26:29]
	v_mfma_f32_16x16x32_bf16 v[18:21], v[180:183], v[204:207], v[18:21]
	v_mfma_f32_16x16x32_bf16 v[10:13], v[168:171], v[212:215], v[10:13]
	v_mfma_f32_16x16x32_bf16 v[2:5], v[180:183], v[212:215], v[2:5]
	v_mfma_f32_16x16x32_bf16 v[58:61], v[172:175], v[192:195], v[58:61]
	v_mfma_f32_16x16x32_bf16 v[50:53], v[184:187], v[192:195], v[50:53]
	v_mfma_f32_16x16x32_bf16 v[42:45], v[172:175], v[200:203], v[42:45]
	v_mfma_f32_16x16x32_bf16 v[34:37], v[184:187], v[200:203], v[34:37]
	v_mfma_f32_16x16x32_bf16 v[26:29], v[172:175], v[208:211], v[26:29]
	v_mfma_f32_16x16x32_bf16 v[18:21], v[184:187], v[208:211], v[18:21]
	v_mfma_f32_16x16x32_bf16 v[10:13], v[172:175], v[216:219], v[10:13]
	v_mfma_f32_16x16x32_bf16 v[2:5], v[184:187], v[216:219], v[2:5]
	s_barrier
	s_setprio 0
	s_add_i32 s79, 0, 0x18000
	s_add_i32 s80, 0, 0x1c000
	ds_read_b128 v[146:149], v153 offset:32768
	ds_read_b128 v[156:159], v153 offset:33792
	ds_read_b128 v[160:163], v153 offset:34816
	ds_read_b128 v[164:167], v153 offset:35840
	ds_read_b128 v[168:171], v154 offset:32768
	ds_read_b128 v[172:175], v154 offset:33792
	ds_read_b128 v[180:183], v154 offset:34816
	ds_read_b128 v[184:187], v154 offset:35840
	s_add_u32 s54, s54, 0x80000
	s_addc_u32 s55, s55, 0
	s_mov_b32 m0, s58
	ds_read_b128 v[188:191], v155 offset:32768
	ds_read_b128 v[192:195], v155 offset:33792
	ds_read_b128 v[196:199], v155 offset:34816
	ds_read_b128 v[200:203], v155 offset:35840
	ds_read_b128 v[204:207], v155 offset:36864
	ds_read_b128 v[208:211], v155 offset:37888
	ds_read_b128 v[212:215], v155 offset:38912
	ds_read_b128 v[216:219], v155 offset:39936
	global_load_lds_dwordx4 v136, s[54:55]
	s_mov_b32 m0, s59
	s_nop 0
	global_load_lds_dwordx4 v132, s[54:55]
	s_setprio 1
	s_waitcnt vmcnt(8) lgkmcnt(0)
	s_barrier
	v_mfma_f32_16x16x32_bf16 v[126:129], v[146:149], v[188:191], v[126:129]
	v_mfma_f32_16x16x32_bf16 v[118:121], v[160:163], v[188:191], v[118:121]
	v_mfma_f32_16x16x32_bf16 v[110:113], v[146:149], v[196:199], v[110:113]
	v_mfma_f32_16x16x32_bf16 v[102:105], v[160:163], v[196:199], v[102:105]
	v_mfma_f32_16x16x32_bf16 v[94:97], v[146:149], v[204:207], v[94:97]
	v_mfma_f32_16x16x32_bf16 v[86:89], v[160:163], v[204:207], v[86:89]
	v_mfma_f32_16x16x32_bf16 v[78:81], v[146:149], v[212:215], v[78:81]
	v_mfma_f32_16x16x32_bf16 v[70:73], v[160:163], v[212:215], v[70:73]
	v_mfma_f32_16x16x32_bf16 v[126:129], v[156:159], v[192:195], v[126:129]
	v_mfma_f32_16x16x32_bf16 v[118:121], v[164:167], v[192:195], v[118:121]
	v_mfma_f32_16x16x32_bf16 v[110:113], v[156:159], v[200:203], v[110:113]
	v_mfma_f32_16x16x32_bf16 v[102:105], v[164:167], v[200:203], v[102:105]
	v_mfma_f32_16x16x32_bf16 v[94:97], v[156:159], v[208:211], v[94:97]
	v_mfma_f32_16x16x32_bf16 v[86:89], v[164:167], v[208:211], v[86:89]
	v_mfma_f32_16x16x32_bf16 v[78:81], v[156:159], v[216:219], v[78:81]
	v_mfma_f32_16x16x32_bf16 v[70:73], v[164:167], v[216:219], v[70:73]
	s_setprio 0
	s_setprio 1
	v_mfma_f32_16x16x32_bf16 v[122:125], v[168:171], v[188:191], v[122:125]
	v_mfma_f32_16x16x32_bf16 v[114:117], v[180:183], v[188:191], v[114:117]
	v_mfma_f32_16x16x32_bf16 v[106:109], v[168:171], v[196:199], v[106:109]
	v_mfma_f32_16x16x32_bf16 v[98:101], v[180:183], v[196:199], v[98:101]
	v_mfma_f32_16x16x32_bf16 v[90:93], v[168:171], v[204:207], v[90:93]
	v_mfma_f32_16x16x32_bf16 v[82:85], v[180:183], v[204:207], v[82:85]
	v_mfma_f32_16x16x32_bf16 v[74:77], v[168:171], v[212:215], v[74:77]
	v_mfma_f32_16x16x32_bf16 v[66:69], v[180:183], v[212:215], v[66:69]
	v_mfma_f32_16x16x32_bf16 v[122:125], v[172:175], v[192:195], v[122:125]
	v_mfma_f32_16x16x32_bf16 v[114:117], v[184:187], v[192:195], v[114:117]
	v_mfma_f32_16x16x32_bf16 v[106:109], v[172:175], v[200:203], v[106:109]
	v_mfma_f32_16x16x32_bf16 v[98:101], v[184:187], v[200:203], v[98:101]
	v_mfma_f32_16x16x32_bf16 v[90:93], v[172:175], v[208:211], v[90:93]
	v_mfma_f32_16x16x32_bf16 v[82:85], v[184:187], v[208:211], v[82:85]
	v_mfma_f32_16x16x32_bf16 v[74:77], v[172:175], v[216:219], v[74:77]
	v_mfma_f32_16x16x32_bf16 v[66:69], v[184:187], v[216:219], v[66:69]
	s_barrier
	s_setprio 0
	s_add_i32 s54, s79, s29
	s_mov_b32 m0, s54
	ds_read_b128 v[188:191], v155 offset:49152
	ds_read_b128 v[192:195], v155 offset:50176
	ds_read_b128 v[196:199], v155 offset:51200
	ds_read_b128 v[200:203], v155 offset:52224
	ds_read_b128 v[204:207], v155 offset:53248
	ds_read_b128 v[208:211], v155 offset:54272
	ds_read_b128 v[212:215], v155 offset:55296
	ds_read_b128 v[216:219], v155 offset:56320
	global_load_lds_dwordx4 v134, s[98:99]
	s_add_i32 m0, s54, 0x2000
	s_add_u32 s42, s42, 0x80080
	s_addc_u32 s43, s43, 0
	s_add_i32 s54, s80, s29
	global_load_lds_dwordx4 v130, s[98:99]
	s_mov_b32 m0, s54
	s_nop 0
	global_load_lds_dwordx4 v134, s[42:43]
	s_add_i32 m0, s54, 0x2000
	s_nop 0
	global_load_lds_dwordx4 v130, s[42:43]
	s_mov_b32 m0, s64
	s_nop 0
	global_load_lds_dwordx4 v136, s[100:101]
	s_mov_b32 m0, s65
	s_nop 0
	global_load_lds_dwordx4 v132, s[100:101]
	s_add_i32 s78, s78, 2
	s_add_u32 s40, s40, 0x100
	s_addc_u32 s41, s41, 0
	s_add_u32 s76, s76, 0x100
	s_addc_u32 s77, s77, 0
	s_cmp_gt_u32 s78, 29
	s_setprio 1
	s_waitcnt vmcnt(8) lgkmcnt(0)
	s_barrier
	v_mfma_f32_16x16x32_bf16 v[62:65], v[146:149], v[188:191], v[62:65]
	v_mfma_f32_16x16x32_bf16 v[54:57], v[160:163], v[188:191], v[54:57]
	v_mfma_f32_16x16x32_bf16 v[46:49], v[146:149], v[196:199], v[46:49]
	v_mfma_f32_16x16x32_bf16 v[38:41], v[160:163], v[196:199], v[38:41]
	v_mfma_f32_16x16x32_bf16 v[30:33], v[146:149], v[204:207], v[30:33]
	v_mfma_f32_16x16x32_bf16 v[22:25], v[160:163], v[204:207], v[22:25]
	v_mfma_f32_16x16x32_bf16 v[14:17], v[146:149], v[212:215], v[14:17]
	v_mfma_f32_16x16x32_bf16 v[6:9], v[160:163], v[212:215], v[6:9]
	v_mfma_f32_16x16x32_bf16 v[62:65], v[156:159], v[192:195], v[62:65]
	v_mfma_f32_16x16x32_bf16 v[54:57], v[164:167], v[192:195], v[54:57]
	v_mfma_f32_16x16x32_bf16 v[46:49], v[156:159], v[200:203], v[46:49]
	v_mfma_f32_16x16x32_bf16 v[38:41], v[164:167], v[200:203], v[38:41]
	v_mfma_f32_16x16x32_bf16 v[30:33], v[156:159], v[208:211], v[30:33]
	v_mfma_f32_16x16x32_bf16 v[22:25], v[164:167], v[208:211], v[22:25]
	v_mfma_f32_16x16x32_bf16 v[14:17], v[156:159], v[216:219], v[14:17]
	v_mfma_f32_16x16x32_bf16 v[6:9], v[164:167], v[216:219], v[6:9]
	s_setprio 0
	s_setprio 1
	v_mfma_f32_16x16x32_bf16 v[58:61], v[168:171], v[188:191], v[58:61]
	v_mfma_f32_16x16x32_bf16 v[50:53], v[180:183], v[188:191], v[50:53]
	v_mfma_f32_16x16x32_bf16 v[42:45], v[168:171], v[196:199], v[42:45]
	v_mfma_f32_16x16x32_bf16 v[34:37], v[180:183], v[196:199], v[34:37]
	v_mfma_f32_16x16x32_bf16 v[26:29], v[168:171], v[204:207], v[26:29]
	v_mfma_f32_16x16x32_bf16 v[18:21], v[180:183], v[204:207], v[18:21]
	v_mfma_f32_16x16x32_bf16 v[10:13], v[168:171], v[212:215], v[10:13]
	v_mfma_f32_16x16x32_bf16 v[2:5], v[180:183], v[212:215], v[2:5]
	v_mfma_f32_16x16x32_bf16 v[58:61], v[172:175], v[192:195], v[58:61]
	v_mfma_f32_16x16x32_bf16 v[50:53], v[184:187], v[192:195], v[50:53]
	v_mfma_f32_16x16x32_bf16 v[42:45], v[172:175], v[200:203], v[42:45]
	v_mfma_f32_16x16x32_bf16 v[34:37], v[184:187], v[200:203], v[34:37]
	v_mfma_f32_16x16x32_bf16 v[26:29], v[172:175], v[208:211], v[26:29]
	v_mfma_f32_16x16x32_bf16 v[18:21], v[184:187], v[208:211], v[18:21]
	v_mfma_f32_16x16x32_bf16 v[10:13], v[172:175], v[216:219], v[10:13]
	v_mfma_f32_16x16x32_bf16 v[2:5], v[184:187], v[216:219], v[2:5]
	s_barrier
	s_setprio 0
	s_cbranch_scc0 .LBB0_293
	s_and_b64 vcc, exec, s[8:9]
	s_cbranch_vccz .LBB0_296
	s_barrier

.LBB0_378:
	s_add_u32 s12, s58, 0x160080
	s_addc_u32 s13, s59, 0
	s_add_u32 s81, s56, 0x100
	s_addc_u32 s82, s57, 0
	s_mov_b32 s83, -2
	ds_read_b128 v[130:133], v208
	ds_read_b128 v[134:137], v208 offset:1024
	ds_read_b128 v[138:141], v208 offset:2048
	ds_read_b128 v[142:145], v208 offset:3072
	ds_read_b128 v[146:149], v209
	ds_read_b128 v[150:153], v209 offset:1024
	ds_read_b128 v[154:157], v209 offset:2048
	ds_read_b128 v[158:161], v209 offset:3072
	s_add_u32 s56, s12, 0xffea0080
	s_addc_u32 s57, s13, -1
	s_cmpk_eq_i32 s83, 0x54
	s_cselect_b32 s59, s43, s57
	s_cselect_b32 s58, s42, s56
	s_cselect_b32 s57, s55, s82
	s_cselect_b32 s56, s54, s81
	s_add_i32 m0, s31, 0xc000
	ds_read_b128 v[162:165], v210
	ds_read_b128 v[166:169], v210 offset:1024
	ds_read_b128 v[170:173], v210 offset:2048
	ds_read_b128 v[174:177], v210 offset:3072
	ds_read_b128 v[196:199], v210 offset:4096
	ds_read_b128 v[200:203], v210 offset:5120
	ds_read_b128 v[212:215], v210 offset:6144
	ds_read_b128 v[216:219], v210 offset:7168
	global_load_lds_dwordx4 v188, s[12:13]
	s_add_i32 m0, s31, 0xe000
	s_nop 0
	global_load_lds_dwordx4 v190, s[12:13]
	s_setprio 1
	s_waitcnt vmcnt(8) lgkmcnt(0)
	s_barrier
	v_mfma_f32_16x16x32_bf16 v[126:129], v[130:133], v[162:165], 0
	v_mfma_f32_16x16x32_bf16 v[122:125], v[138:141], v[162:165], 0
	v_mfma_f32_16x16x32_bf16 v[110:113], v[130:133], v[170:173], 0
	v_mfma_f32_16x16x32_bf16 v[106:109], v[138:141], v[170:173], 0
	v_mfma_f32_16x16x32_bf16 v[94:97], v[130:133], v[196:199], 0
	v_mfma_f32_16x16x32_bf16 v[90:93], v[138:141], v[196:199], 0
	v_mfma_f32_16x16x32_bf16 v[78:81], v[130:133], v[212:215], 0
	v_mfma_f32_16x16x32_bf16 v[74:77], v[138:141], v[212:215], 0
	v_mfma_f32_16x16x32_bf16 v[126:129], v[134:137], v[166:169], v[126:129]
	v_mfma_f32_16x16x32_bf16 v[122:125], v[142:145], v[166:169], v[122:125]
	v_mfma_f32_16x16x32_bf16 v[110:113], v[134:137], v[174:177], v[110:113]
	v_mfma_f32_16x16x32_bf16 v[106:109], v[142:145], v[174:177], v[106:109]
	v_mfma_f32_16x16x32_bf16 v[94:97], v[134:137], v[200:203], v[94:97]
	v_mfma_f32_16x16x32_bf16 v[90:93], v[142:145], v[200:203], v[90:93]
	v_mfma_f32_16x16x32_bf16 v[78:81], v[134:137], v[216:219], v[78:81]
	v_mfma_f32_16x16x32_bf16 v[74:77], v[142:145], v[216:219], v[74:77]
	s_setprio 0
	s_setprio 1
	v_mfma_f32_16x16x32_bf16 v[118:121], v[146:149], v[162:165], 0
	v_mfma_f32_16x16x32_bf16 v[114:117], v[154:157], v[162:165], 0
	v_mfma_f32_16x16x32_bf16 v[102:105], v[146:149], v[170:173], 0
	v_mfma_f32_16x16x32_bf16 v[98:101], v[154:157], v[170:173], 0
	v_mfma_f32_16x16x32_bf16 v[86:89], v[146:149], v[196:199], 0
	v_mfma_f32_16x16x32_bf16 v[82:85], v[154:157], v[196:199], 0
	v_mfma_f32_16x16x32_bf16 v[70:73], v[146:149], v[212:215], 0
	v_mfma_f32_16x16x32_bf16 v[66:69], v[154:157], v[212:215], 0
	v_mfma_f32_16x16x32_bf16 v[118:121], v[150:153], v[166:169], v[118:121]
	v_mfma_f32_16x16x32_bf16 v[114:117], v[158:161], v[166:169], v[114:117]
	v_mfma_f32_16x16x32_bf16 v[102:105], v[150:153], v[174:177], v[102:105]
	v_mfma_f32_16x16x32_bf16 v[98:101], v[158:161], v[174:177], v[98:101]
	v_mfma_f32_16x16x32_bf16 v[86:89], v[150:153], v[200:203], v[86:89]
	v_mfma_f32_16x16x32_bf16 v[82:85], v[158:161], v[200:203], v[82:85]
	v_mfma_f32_16x16x32_bf16 v[70:73], v[150:153], v[216:219], v[70:73]
	v_mfma_f32_16x16x32_bf16 v[66:69], v[158:161], v[216:219], v[66:69]
	s_barrier
	s_setprio 0
	s_add_i32 s85, s75, s29
	s_add_u32 s98, s56, 0x80
	s_addc_u32 s99, s57, 0
	s_mov_b32 m0, s85
	ds_read_b128 v[162:165], v210 offset:16384
	ds_read_b128 v[166:169], v210 offset:17408
	ds_read_b128 v[170:173], v210 offset:18432
	ds_read_b128 v[174:177], v210 offset:19456
	ds_read_b128 v[196:199], v210 offset:20480
	ds_read_b128 v[200:203], v210 offset:21504
	ds_read_b128 v[212:215], v210 offset:22528
	ds_read_b128 v[216:219], v210 offset:23552
	global_load_lds_dwordx4 v182, s[56:57]
	s_add_i32 m0, s85, 0x2000
	s_add_u32 s88, s56, 0x160000
	s_addc_u32 s89, s57, 0
	s_add_i32 s85, s76, s29
	global_load_lds_dwordx4 v186, s[56:57]
	s_mov_b32 m0, s85
	s_nop 0
	global_load_lds_dwordx4 v182, s[88:89]
	s_add_i32 m0, s85, 0x2000
	s_nop 0
	global_load_lds_dwordx4 v186, s[88:89]
	s_add_u32 s100, s58, 0x80
	s_addc_u32 s101, s59, 0
	s_mov_b32 m0, s31
	s_nop 0
	global_load_lds_dwordx4 v180, s[58:59]
	s_mov_b32 m0, s64
	s_nop 0
	global_load_lds_dwordx4 v184, s[58:59]
	s_setprio 1
	s_waitcnt vmcnt(8) lgkmcnt(0)
	s_barrier
	v_mfma_f32_16x16x32_bf16 v[62:65], v[130:133], v[162:165], 0
	v_mfma_f32_16x16x32_bf16 v[58:61], v[138:141], v[162:165], 0
	v_mfma_f32_16x16x32_bf16 v[46:49], v[130:133], v[170:173], 0
	v_mfma_f32_16x16x32_bf16 v[42:45], v[138:141], v[170:173], 0
	v_mfma_f32_16x16x32_bf16 v[30:33], v[130:133], v[196:199], 0
	v_mfma_f32_16x16x32_bf16 v[26:29], v[138:141], v[196:199], 0
	v_mfma_f32_16x16x32_bf16 v[14:17], v[130:133], v[212:215], 0
	v_mfma_f32_16x16x32_bf16 v[10:13], v[138:141], v[212:215], 0
	v_mfma_f32_16x16x32_bf16 v[62:65], v[134:137], v[166:169], v[62:65]
	v_mfma_f32_16x16x32_bf16 v[58:61], v[142:145], v[166:169], v[58:61]
	v_mfma_f32_16x16x32_bf16 v[46:49], v[134:137], v[174:177], v[46:49]
	v_mfma_f32_16x16x32_bf16 v[42:45], v[142:145], v[174:177], v[42:45]
	v_mfma_f32_16x16x32_bf16 v[30:33], v[134:137], v[200:203], v[30:33]
	v_mfma_f32_16x16x32_bf16 v[26:29], v[142:145], v[200:203], v[26:29]
	v_mfma_f32_16x16x32_bf16 v[14:17], v[134:137], v[216:219], v[14:17]
	v_mfma_f32_16x16x32_bf16 v[10:13], v[142:145], v[216:219], v[10:13]
	s_setprio 0
	s_setprio 1
	v_mfma_f32_16x16x32_bf16 v[54:57], v[146:149], v[162:165], 0
	v_mfma_f32_16x16x32_bf16 v[50:53], v[154:157], v[162:165], 0
	v_mfma_f32_16x16x32_bf16 v[38:41], v[146:149], v[170:173], 0
	v_mfma_f32_16x16x32_bf16 v[34:37], v[154:157], v[170:173], 0
	v_mfma_f32_16x16x32_bf16 v[22:25], v[146:149], v[196:199], 0
	v_mfma_f32_16x16x32_bf16 v[18:21], v[154:157], v[196:199], 0
	v_mfma_f32_16x16x32_bf16 v[6:9], v[146:149], v[212:215], 0
	v_mfma_f32_16x16x32_bf16 v[2:5], v[154:157], v[212:215], 0
	v_mfma_f32_16x16x32_bf16 v[54:57], v[150:153], v[166:169], v[54:57]
	v_mfma_f32_16x16x32_bf16 v[50:53], v[158:161], v[166:169], v[50:53]
	v_mfma_f32_16x16x32_bf16 v[38:41], v[150:153], v[174:177], v[38:41]
	v_mfma_f32_16x16x32_bf16 v[34:37], v[158:161], v[174:177], v[34:37]
	v_mfma_f32_16x16x32_bf16 v[22:25], v[150:153], v[200:203], v[22:25]
	v_mfma_f32_16x16x32_bf16 v[18:21], v[158:161], v[200:203], v[18:21]
	v_mfma_f32_16x16x32_bf16 v[6:9], v[150:153], v[216:219], v[6:9]
	v_mfma_f32_16x16x32_bf16 v[2:5], v[158:161], v[216:219], v[2:5]
	s_barrier
	s_setprio 0
	s_add_i32 s85, 0, 0x18000
	s_add_i32 s87, 0, 0x1c000
	ds_read_b128 v[130:133], v208 offset:32768
	ds_read_b128 v[134:137], v208 offset:33792
	ds_read_b128 v[138:141], v208 offset:34816
	ds_read_b128 v[142:145], v208 offset:35840
	ds_read_b128 v[146:149], v209 offset:32768
	ds_read_b128 v[150:153], v209 offset:33792
	ds_read_b128 v[154:157], v209 offset:34816
	ds_read_b128 v[158:161], v209 offset:35840
	s_add_u32 s58, s58, 0x160000
	s_addc_u32 s59, s59, 0
	s_mov_b32 m0, s65
	ds_read_b128 v[162:165], v210 offset:32768
	ds_read_b128 v[166:169], v210 offset:33792
	ds_read_b128 v[170:173], v210 offset:34816
	ds_read_b128 v[174:177], v210 offset:35840
	ds_read_b128 v[196:199], v210 offset:36864
	ds_read_b128 v[200:203], v210 offset:37888
	ds_read_b128 v[212:215], v210 offset:38912
	ds_read_b128 v[216:219], v210 offset:39936
	global_load_lds_dwordx4 v180, s[58:59]
	s_mov_b32 m0, s66
	s_nop 0
	global_load_lds_dwordx4 v184, s[58:59]
	s_setprio 1
	s_waitcnt vmcnt(8) lgkmcnt(0)
	s_barrier
	v_mfma_f32_16x16x32_bf16 v[126:129], v[130:133], v[162:165], v[126:129]
	v_mfma_f32_16x16x32_bf16 v[122:125], v[138:141], v[162:165], v[122:125]
	v_mfma_f32_16x16x32_bf16 v[110:113], v[130:133], v[170:173], v[110:113]
	v_mfma_f32_16x16x32_bf16 v[106:109], v[138:141], v[170:173], v[106:109]
	v_mfma_f32_16x16x32_bf16 v[94:97], v[130:133], v[196:199], v[94:97]
	v_mfma_f32_16x16x32_bf16 v[90:93], v[138:141], v[196:199], v[90:93]
	v_mfma_f32_16x16x32_bf16 v[78:81], v[130:133], v[212:215], v[78:81]
	v_mfma_f32_16x16x32_bf16 v[74:77], v[138:141], v[212:215], v[74:77]
	v_mfma_f32_16x16x32_bf16 v[126:129], v[134:137], v[166:169], v[126:129]
	v_mfma_f32_16x16x32_bf16 v[122:125], v[142:145], v[166:169], v[122:125]
	v_mfma_f32_16x16x32_bf16 v[110:113], v[134:137], v[174:177], v[110:113]
	v_mfma_f32_16x16x32_bf16 v[106:109], v[142:145], v[174:177], v[106:109]
	v_mfma_f32_16x16x32_bf16 v[94:97], v[134:137], v[200:203], v[94:97]
	v_mfma_f32_16x16x32_bf16 v[90:93], v[142:145], v[200:203], v[90:93]
	v_mfma_f32_16x16x32_bf16 v[78:81], v[134:137], v[216:219], v[78:81]
	v_mfma_f32_16x16x32_bf16 v[74:77], v[142:145], v[216:219], v[74:77]
	s_setprio 0
	s_setprio 1
	v_mfma_f32_16x16x32_bf16 v[118:121], v[146:149], v[162:165], v[118:121]
	v_mfma_f32_16x16x32_bf16 v[114:117], v[154:157], v[162:165], v[114:117]
	v_mfma_f32_16x16x32_bf16 v[102:105], v[146:149], v[170:173], v[102:105]
	v_mfma_f32_16x16x32_bf16 v[98:101], v[154:157], v[170:173], v[98:101]
	v_mfma_f32_16x16x32_bf16 v[86:89], v[146:149], v[196:199], v[86:89]
	v_mfma_f32_16x16x32_bf16 v[82:85], v[154:157], v[196:199], v[82:85]
	v_mfma_f32_16x16x32_bf16 v[70:73], v[146:149], v[212:215], v[70:73]
	v_mfma_f32_16x16x32_bf16 v[66:69], v[154:157], v[212:215], v[66:69]
	v_mfma_f32_16x16x32_bf16 v[118:121], v[150:153], v[166:169], v[118:121]
	v_mfma_f32_16x16x32_bf16 v[114:117], v[158:161], v[166:169], v[114:117]
	v_mfma_f32_16x16x32_bf16 v[102:105], v[150:153], v[174:177], v[102:105]
	v_mfma_f32_16x16x32_bf16 v[98:101], v[158:161], v[174:177], v[98:101]
	v_mfma_f32_16x16x32_bf16 v[86:89], v[150:153], v[200:203], v[86:89]
	v_mfma_f32_16x16x32_bf16 v[82:85], v[158:161], v[200:203], v[82:85]
	v_mfma_f32_16x16x32_bf16 v[70:73], v[150:153], v[216:219], v[70:73]
	v_mfma_f32_16x16x32_bf16 v[66:69], v[158:161], v[216:219], v[66:69]
	s_barrier
	s_setprio 0
	s_add_i32 s58, s85, s29
	s_mov_b32 m0, s58
	ds_read_b128 v[162:165], v210 offset:49152
	ds_read_b128 v[166:169], v210 offset:50176
	ds_read_b128 v[170:173], v210 offset:51200
	ds_read_b128 v[174:177], v210 offset:52224
	ds_read_b128 v[196:199], v210 offset:53248
	ds_read_b128 v[200:203], v210 offset:54272
	ds_read_b128 v[212:215], v210 offset:55296
	ds_read_b128 v[216:219], v210 offset:56320
	global_load_lds_dwordx4 v182, s[98:99]
	s_add_i32 m0, s58, 0x2000
	s_add_u32 s56, s56, 0x160080
	s_addc_u32 s57, s57, 0
	s_add_i32 s58, s87, s29
	global_load_lds_dwordx4 v186, s[98:99]
	s_mov_b32 m0, s58
	s_nop 0
	global_load_lds_dwordx4 v182, s[56:57]
	s_add_i32 m0, s58, 0x2000
	s_nop 0
	global_load_lds_dwordx4 v186, s[56:57]
	s_mov_b32 m0, s71
	s_nop 0
	global_load_lds_dwordx4 v180, s[100:101]
	s_mov_b32 m0, s72
	s_nop 0
	global_load_lds_dwordx4 v184, s[100:101]
	s_setprio 1
	s_waitcnt vmcnt(8) lgkmcnt(0)
	s_barrier
	v_mfma_f32_16x16x32_bf16 v[62:65], v[130:133], v[162:165], v[62:65]
	v_mfma_f32_16x16x32_bf16 v[58:61], v[138:141], v[162:165], v[58:61]
	v_mfma_f32_16x16x32_bf16 v[46:49], v[130:133], v[170:173], v[46:49]
	v_mfma_f32_16x16x32_bf16 v[42:45], v[138:141], v[170:173], v[42:45]
	v_mfma_f32_16x16x32_bf16 v[30:33], v[130:133], v[196:199], v[30:33]
	v_mfma_f32_16x16x32_bf16 v[26:29], v[138:141], v[196:199], v[26:29]
	v_mfma_f32_16x16x32_bf16 v[14:17], v[130:133], v[212:215], v[14:17]
	v_mfma_f32_16x16x32_bf16 v[10:13], v[138:141], v[212:215], v[10:13]
	v_mfma_f32_16x16x32_bf16 v[62:65], v[134:137], v[166:169], v[62:65]
	v_mfma_f32_16x16x32_bf16 v[58:61], v[142:145], v[166:169], v[58:61]
	v_mfma_f32_16x16x32_bf16 v[46:49], v[134:137], v[174:177], v[46:49]
	v_mfma_f32_16x16x32_bf16 v[42:45], v[142:145], v[174:177], v[42:45]
	v_mfma_f32_16x16x32_bf16 v[30:33], v[134:137], v[200:203], v[30:33]
	v_mfma_f32_16x16x32_bf16 v[26:29], v[142:145], v[200:203], v[26:29]
	v_mfma_f32_16x16x32_bf16 v[14:17], v[134:137], v[216:219], v[14:17]
	v_mfma_f32_16x16x32_bf16 v[10:13], v[142:145], v[216:219], v[10:13]
	s_setprio 0
	s_setprio 1
	v_mfma_f32_16x16x32_bf16 v[54:57], v[146:149], v[162:165], v[54:57]
	v_mfma_f32_16x16x32_bf16 v[50:53], v[154:157], v[162:165], v[50:53]
	v_mfma_f32_16x16x32_bf16 v[38:41], v[146:149], v[170:173], v[38:41]
	v_mfma_f32_16x16x32_bf16 v[34:37], v[154:157], v[170:173], v[34:37]
	v_mfma_f32_16x16x32_bf16 v[22:25], v[146:149], v[196:199], v[22:25]
	v_mfma_f32_16x16x32_bf16 v[18:21], v[154:157], v[196:199], v[18:21]
	v_mfma_f32_16x16x32_bf16 v[6:9], v[146:149], v[212:215], v[6:9]
	v_mfma_f32_16x16x32_bf16 v[2:5], v[154:157], v[212:215], v[2:5]
	v_mfma_f32_16x16x32_bf16 v[54:57], v[150:153], v[166:169], v[54:57]
	v_mfma_f32_16x16x32_bf16 v[50:53], v[158:161], v[166:169], v[50:53]
	v_mfma_f32_16x16x32_bf16 v[38:41], v[150:153], v[174:177], v[38:41]
	v_mfma_f32_16x16x32_bf16 v[34:37], v[158:161], v[174:177], v[34:37]
	v_mfma_f32_16x16x32_bf16 v[22:25], v[150:153], v[200:203], v[22:25]
	v_mfma_f32_16x16x32_bf16 v[18:21], v[158:161], v[200:203], v[18:21]
	v_mfma_f32_16x16x32_bf16 v[6:9], v[150:153], v[216:219], v[6:9]
	v_mfma_f32_16x16x32_bf16 v[2:5], v[158:161], v[216:219], v[2:5]
	s_barrier
	s_setprio 0
	s_add_i32 s83, s83, 2
	s_add_u32 s12, s12, 0x100
	s_addc_u32 s13, s13, 0
	s_add_u32 s81, s81, 0x100
	s_addc_u32 s82, s82, 0
	s_cmpk_gt_u32 s83, 0x55
.LBB0_379:
	ds_read_b128 v[130:133], v208
	ds_read_b128 v[134:137], v208 offset:1024
	ds_read_b128 v[138:141], v208 offset:2048
	ds_read_b128 v[142:145], v208 offset:3072
	ds_read_b128 v[146:149], v209
	ds_read_b128 v[150:153], v209 offset:1024
	ds_read_b128 v[154:157], v209 offset:2048
	ds_read_b128 v[158:161], v209 offset:3072
	s_add_u32 s56, s12, 0xffea0080
	s_addc_u32 s57, s13, -1
	s_cmpk_eq_i32 s83, 0x54
	s_cselect_b32 s59, s43, s57
	s_cselect_b32 s58, s42, s56
	s_cselect_b32 s57, s55, s82
	s_cselect_b32 s56, s54, s81
	s_add_i32 m0, s31, 0xc000
	ds_read_b128 v[162:165], v210
	ds_read_b128 v[166:169], v210 offset:1024
	ds_read_b128 v[170:173], v210 offset:2048
	ds_read_b128 v[174:177], v210 offset:3072
	ds_read_b128 v[196:199], v210 offset:4096
	ds_read_b128 v[200:203], v210 offset:5120
	ds_read_b128 v[212:215], v210 offset:6144
	ds_read_b128 v[216:219], v210 offset:7168
	global_load_lds_dwordx4 v188, s[12:13]
	s_add_i32 m0, s31, 0xe000
	s_nop 0
	global_load_lds_dwordx4 v190, s[12:13]
	s_setprio 1
	s_waitcnt vmcnt(8) lgkmcnt(0)
	s_barrier
	v_mfma_f32_16x16x32_bf16 v[126:129], v[130:133], v[162:165], v[126:129]
	v_mfma_f32_16x16x32_bf16 v[122:125], v[138:141], v[162:165], v[122:125]
	v_mfma_f32_16x16x32_bf16 v[110:113], v[130:133], v[170:173], v[110:113]
	v_mfma_f32_16x16x32_bf16 v[106:109], v[138:141], v[170:173], v[106:109]
	v_mfma_f32_16x16x32_bf16 v[94:97], v[130:133], v[196:199], v[94:97]
	v_mfma_f32_16x16x32_bf16 v[90:93], v[138:141], v[196:199], v[90:93]
	v_mfma_f32_16x16x32_bf16 v[78:81], v[130:133], v[212:215], v[78:81]
	v_mfma_f32_16x16x32_bf16 v[74:77], v[138:141], v[212:215], v[74:77]
	v_mfma_f32_16x16x32_bf16 v[126:129], v[134:137], v[166:169], v[126:129]
	v_mfma_f32_16x16x32_bf16 v[122:125], v[142:145], v[166:169], v[122:125]
	v_mfma_f32_16x16x32_bf16 v[110:113], v[134:137], v[174:177], v[110:113]
	v_mfma_f32_16x16x32_bf16 v[106:109], v[142:145], v[174:177], v[106:109]
	v_mfma_f32_16x16x32_bf16 v[94:97], v[134:137], v[200:203], v[94:97]
	v_mfma_f32_16x16x32_bf16 v[90:93], v[142:145], v[200:203], v[90:93]
	v_mfma_f32_16x16x32_bf16 v[78:81], v[134:137], v[216:219], v[78:81]
	v_mfma_f32_16x16x32_bf16 v[74:77], v[142:145], v[216:219], v[74:77]
	s_setprio 0
	s_setprio 1
	v_mfma_f32_16x16x32_bf16 v[118:121], v[146:149], v[162:165], v[118:121]
	v_mfma_f32_16x16x32_bf16 v[114:117], v[154:157], v[162:165], v[114:117]
	v_mfma_f32_16x16x32_bf16 v[102:105], v[146:149], v[170:173], v[102:105]
	v_mfma_f32_16x16x32_bf16 v[98:101], v[154:157], v[170:173], v[98:101]
	v_mfma_f32_16x16x32_bf16 v[86:89], v[146:149], v[196:199], v[86:89]
	v_mfma_f32_16x16x32_bf16 v[82:85], v[154:157], v[196:199], v[82:85]
	v_mfma_f32_16x16x32_bf16 v[70:73], v[146:149], v[212:215], v[70:73]
	v_mfma_f32_16x16x32_bf16 v[66:69], v[154:157], v[212:215], v[66:69]
	v_mfma_f32_16x16x32_bf16 v[118:121], v[150:153], v[166:169], v[118:121]
	v_mfma_f32_16x16x32_bf16 v[114:117], v[158:161], v[166:169], v[114:117]
	v_mfma_f32_16x16x32_bf16 v[102:105], v[150:153], v[174:177], v[102:105]
	v_mfma_f32_16x16x32_bf16 v[98:101], v[158:161], v[174:177], v[98:101]
	v_mfma_f32_16x16x32_bf16 v[86:89], v[150:153], v[200:203], v[86:89]
	v_mfma_f32_16x16x32_bf16 v[82:85], v[158:161], v[200:203], v[82:85]
	v_mfma_f32_16x16x32_bf16 v[70:73], v[150:153], v[216:219], v[70:73]
	v_mfma_f32_16x16x32_bf16 v[66:69], v[158:161], v[216:219], v[66:69]
	s_barrier
	s_setprio 0
	s_add_i32 s85, s75, s29
	s_add_u32 s98, s56, 0x80
	s_addc_u32 s99, s57, 0
	s_mov_b32 m0, s85
	ds_read_b128 v[162:165], v210 offset:16384
	ds_read_b128 v[166:169], v210 offset:17408
	ds_read_b128 v[170:173], v210 offset:18432
	ds_read_b128 v[174:177], v210 offset:19456
	ds_read_b128 v[196:199], v210 offset:20480
	ds_read_b128 v[200:203], v210 offset:21504
	ds_read_b128 v[212:215], v210 offset:22528
	ds_read_b128 v[216:219], v210 offset:23552
	global_load_lds_dwordx4 v182, s[56:57]
	s_add_i32 m0, s85, 0x2000
	s_add_u32 s88, s56, 0x160000
	s_addc_u32 s89, s57, 0
	s_add_i32 s85, s76, s29
	global_load_lds_dwordx4 v186, s[56:57]
	s_mov_b32 m0, s85
	s_nop 0
	global_load_lds_dwordx4 v182, s[88:89]
	s_add_i32 m0, s85, 0x2000
	s_nop 0
	global_load_lds_dwordx4 v186, s[88:89]
	s_add_u32 s100, s58, 0x80
	s_addc_u32 s101, s59, 0
	s_mov_b32 m0, s31
	s_nop 0
	global_load_lds_dwordx4 v180, s[58:59]
	s_mov_b32 m0, s64
	s_nop 0
	global_load_lds_dwordx4 v184, s[58:59]
	s_setprio 1
	s_waitcnt vmcnt(8) lgkmcnt(0)
	s_barrier
	v_mfma_f32_16x16x32_bf16 v[62:65], v[130:133], v[162:165], v[62:65]
	v_mfma_f32_16x16x32_bf16 v[58:61], v[138:141], v[162:165], v[58:61]
	v_mfma_f32_16x16x32_bf16 v[46:49], v[130:133], v[170:173], v[46:49]
	v_mfma_f32_16x16x32_bf16 v[42:45], v[138:141], v[170:173], v[42:45]
	v_mfma_f32_16x16x32_bf16 v[30:33], v[130:133], v[196:199], v[30:33]
	v_mfma_f32_16x16x32_bf16 v[26:29], v[138:141], v[196:199], v[26:29]
	v_mfma_f32_16x16x32_bf16 v[14:17], v[130:133], v[212:215], v[14:17]
	v_mfma_f32_16x16x32_bf16 v[10:13], v[138:141], v[212:215], v[10:13]
	v_mfma_f32_16x16x32_bf16 v[62:65], v[134:137], v[166:169], v[62:65]
	v_mfma_f32_16x16x32_bf16 v[58:61], v[142:145], v[166:169], v[58:61]
	v_mfma_f32_16x16x32_bf16 v[46:49], v[134:137], v[174:177], v[46:49]
	v_mfma_f32_16x16x32_bf16 v[42:45], v[142:145], v[174:177], v[42:45]
	v_mfma_f32_16x16x32_bf16 v[30:33], v[134:137], v[200:203], v[30:33]
	v_mfma_f32_16x16x32_bf16 v[26:29], v[142:145], v[200:203], v[26:29]
	v_mfma_f32_16x16x32_bf16 v[14:17], v[134:137], v[216:219], v[14:17]
	v_mfma_f32_16x16x32_bf16 v[10:13], v[142:145], v[216:219], v[10:13]
	s_setprio 0
	s_setprio 1
	v_mfma_f32_16x16x32_bf16 v[54:57], v[146:149], v[162:165], v[54:57]
	v_mfma_f32_16x16x32_bf16 v[50:53], v[154:157], v[162:165], v[50:53]
	v_mfma_f32_16x16x32_bf16 v[38:41], v[146:149], v[170:173], v[38:41]
	v_mfma_f32_16x16x32_bf16 v[34:37], v[154:157], v[170:173], v[34:37]
	v_mfma_f32_16x16x32_bf16 v[22:25], v[146:149], v[196:199], v[22:25]
	v_mfma_f32_16x16x32_bf16 v[18:21], v[154:157], v[196:199], v[18:21]
	v_mfma_f32_16x16x32_bf16 v[6:9], v[146:149], v[212:215], v[6:9]
	v_mfma_f32_16x16x32_bf16 v[2:5], v[154:157], v[212:215], v[2:5]
	v_mfma_f32_16x16x32_bf16 v[54:57], v[150:153], v[166:169], v[54:57]
	v_mfma_f32_16x16x32_bf16 v[50:53], v[158:161], v[166:169], v[50:53]
	v_mfma_f32_16x16x32_bf16 v[38:41], v[150:153], v[174:177], v[38:41]
	v_mfma_f32_16x16x32_bf16 v[34:37], v[158:161], v[174:177], v[34:37]
	v_mfma_f32_16x16x32_bf16 v[22:25], v[150:153], v[200:203], v[22:25]
	v_mfma_f32_16x16x32_bf16 v[18:21], v[158:161], v[200:203], v[18:21]
	v_mfma_f32_16x16x32_bf16 v[6:9], v[150:153], v[216:219], v[6:9]
	v_mfma_f32_16x16x32_bf16 v[2:5], v[158:161], v[216:219], v[2:5]
	s_barrier
	s_setprio 0
	s_add_i32 s85, 0, 0x18000
	s_add_i32 s87, 0, 0x1c000
	ds_read_b128 v[130:133], v208 offset:32768
	ds_read_b128 v[134:137], v208 offset:33792
	ds_read_b128 v[138:141], v208 offset:34816
	ds_read_b128 v[142:145], v208 offset:35840
	ds_read_b128 v[146:149], v209 offset:32768
	ds_read_b128 v[150:153], v209 offset:33792
	ds_read_b128 v[154:157], v209 offset:34816
	ds_read_b128 v[158:161], v209 offset:35840
	s_add_u32 s58, s58, 0x160000
	s_addc_u32 s59, s59, 0
	s_mov_b32 m0, s65
	ds_read_b128 v[162:165], v210 offset:32768
	ds_read_b128 v[166:169], v210 offset:33792
	ds_read_b128 v[170:173], v210 offset:34816
	ds_read_b128 v[174:177], v210 offset:35840
	ds_read_b128 v[196:199], v210 offset:36864
	ds_read_b128 v[200:203], v210 offset:37888
	ds_read_b128 v[212:215], v210 offset:38912
	ds_read_b128 v[216:219], v210 offset:39936
	global_load_lds_dwordx4 v180, s[58:59]
	v_lshl_add_u64 v[226:227], s[58:59], 0, v[184:185]
	s_mov_b32 m0, s66
	s_nop 0
	global_load_lds_dwordx4 v[226:227], off
	s_setprio 1
	s_waitcnt vmcnt(8) lgkmcnt(0)
	s_barrier
	v_mfma_f32_16x16x32_bf16 v[126:129], v[130:133], v[162:165], v[126:129]
	v_mfma_f32_16x16x32_bf16 v[122:125], v[138:141], v[162:165], v[122:125]
	v_mfma_f32_16x16x32_bf16 v[110:113], v[130:133], v[170:173], v[110:113]
	v_mfma_f32_16x16x32_bf16 v[106:109], v[138:141], v[170:173], v[106:109]
	v_mfma_f32_16x16x32_bf16 v[94:97], v[130:133], v[196:199], v[94:97]
	v_mfma_f32_16x16x32_bf16 v[90:93], v[138:141], v[196:199], v[90:93]
	v_mfma_f32_16x16x32_bf16 v[78:81], v[130:133], v[212:215], v[78:81]
	v_mfma_f32_16x16x32_bf16 v[74:77], v[138:141], v[212:215], v[74:77]
	v_mfma_f32_16x16x32_bf16 v[126:129], v[134:137], v[166:169], v[126:129]
	v_mfma_f32_16x16x32_bf16 v[122:125], v[142:145], v[166:169], v[122:125]
	v_mfma_f32_16x16x32_bf16 v[110:113], v[134:137], v[174:177], v[110:113]
	v_mfma_f32_16x16x32_bf16 v[106:109], v[142:145], v[174:177], v[106:109]
	v_mfma_f32_16x16x32_bf16 v[94:97], v[134:137], v[200:203], v[94:97]
	v_mfma_f32_16x16x32_bf16 v[90:93], v[142:145], v[200:203], v[90:93]
	v_mfma_f32_16x16x32_bf16 v[78:81], v[134:137], v[216:219], v[78:81]
	v_mfma_f32_16x16x32_bf16 v[74:77], v[142:145], v[216:219], v[74:77]
	s_setprio 0
	s_setprio 1
	v_mfma_f32_16x16x32_bf16 v[118:121], v[146:149], v[162:165], v[118:121]
	v_mfma_f32_16x16x32_bf16 v[114:117], v[154:157], v[162:165], v[114:117]
	v_mfma_f32_16x16x32_bf16 v[102:105], v[146:149], v[170:173], v[102:105]
	v_mfma_f32_16x16x32_bf16 v[98:101], v[154:157], v[170:173], v[98:101]
	v_mfma_f32_16x16x32_bf16 v[86:89], v[146:149], v[196:199], v[86:89]
	v_mfma_f32_16x16x32_bf16 v[82:85], v[154:157], v[196:199], v[82:85]
	v_mfma_f32_16x16x32_bf16 v[70:73], v[146:149], v[212:215], v[70:73]
	v_mfma_f32_16x16x32_bf16 v[66:69], v[154:157], v[212:215], v[66:69]
	v_mfma_f32_16x16x32_bf16 v[118:121], v[150:153], v[166:169], v[118:121]
	v_mfma_f32_16x16x32_bf16 v[114:117], v[158:161], v[166:169], v[114:117]
	v_mfma_f32_16x16x32_bf16 v[102:105], v[150:153], v[174:177], v[102:105]
	v_mfma_f32_16x16x32_bf16 v[98:101], v[158:161], v[174:177], v[98:101]
	v_mfma_f32_16x16x32_bf16 v[86:89], v[150:153], v[200:203], v[86:89]
	v_mfma_f32_16x16x32_bf16 v[82:85], v[158:161], v[200:203], v[82:85]
	v_mfma_f32_16x16x32_bf16 v[70:73], v[150:153], v[216:219], v[70:73]
	v_mfma_f32_16x16x32_bf16 v[66:69], v[158:161], v[216:219], v[66:69]
	s_barrier
	s_setprio 0
	s_add_i32 s58, s85, s29
	s_mov_b32 m0, s58
	ds_read_b128 v[162:165], v210 offset:49152
	ds_read_b128 v[166:169], v210 offset:50176
	ds_read_b128 v[170:173], v210 offset:51200
	ds_read_b128 v[174:177], v210 offset:52224
	ds_read_b128 v[196:199], v210 offset:53248
	ds_read_b128 v[200:203], v210 offset:54272
	ds_read_b128 v[212:215], v210 offset:55296
	ds_read_b128 v[216:219], v210 offset:56320
	global_load_lds_dwordx4 v182, s[98:99]
	s_add_i32 m0, s58, 0x2000
	s_add_u32 s56, s56, 0x160080
	s_addc_u32 s57, s57, 0
	s_add_i32 s58, s87, s29
	global_load_lds_dwordx4 v186, s[98:99]
	s_mov_b32 m0, s58
	s_nop 0
	global_load_lds_dwordx4 v182, s[56:57]
	s_add_i32 m0, s58, 0x2000
	s_nop 0
	global_load_lds_dwordx4 v186, s[56:57]
	s_mov_b32 m0, s71
	s_nop 0
	global_load_lds_dwordx4 v180, s[100:101]
	s_mov_b32 m0, s72
	s_nop 0
	global_load_lds_dwordx4 v184, s[100:101]
	s_add_i32 s83, s83, 2
	s_add_u32 s12, s12, 0x100
	s_addc_u32 s13, s13, 0
	s_add_u32 s81, s81, 0x100
	s_addc_u32 s82, s82, 0
	s_cmpk_gt_u32 s83, 0x55
	s_setprio 1
	s_waitcnt vmcnt(8) lgkmcnt(0)
	s_barrier
	v_mfma_f32_16x16x32_bf16 v[62:65], v[130:133], v[162:165], v[62:65]
	v_mfma_f32_16x16x32_bf16 v[58:61], v[138:141], v[162:165], v[58:61]
	v_mfma_f32_16x16x32_bf16 v[46:49], v[130:133], v[170:173], v[46:49]
	v_mfma_f32_16x16x32_bf16 v[42:45], v[138:141], v[170:173], v[42:45]
	v_mfma_f32_16x16x32_bf16 v[30:33], v[130:133], v[196:199], v[30:33]
	v_mfma_f32_16x16x32_bf16 v[26:29], v[138:141], v[196:199], v[26:29]
	v_mfma_f32_16x16x32_bf16 v[14:17], v[130:133], v[212:215], v[14:17]
	v_mfma_f32_16x16x32_bf16 v[10:13], v[138:141], v[212:215], v[10:13]
	v_mfma_f32_16x16x32_bf16 v[62:65], v[134:137], v[166:169], v[62:65]
	v_mfma_f32_16x16x32_bf16 v[58:61], v[142:145], v[166:169], v[58:61]
	v_mfma_f32_16x16x32_bf16 v[46:49], v[134:137], v[174:177], v[46:49]
	v_mfma_f32_16x16x32_bf16 v[42:45], v[142:145], v[174:177], v[42:45]
	v_mfma_f32_16x16x32_bf16 v[30:33], v[134:137], v[200:203], v[30:33]
	v_mfma_f32_16x16x32_bf16 v[26:29], v[142:145], v[200:203], v[26:29]
	v_mfma_f32_16x16x32_bf16 v[14:17], v[134:137], v[216:219], v[14:17]
	v_mfma_f32_16x16x32_bf16 v[10:13], v[142:145], v[216:219], v[10:13]
	s_setprio 0
	s_setprio 1
	v_mfma_f32_16x16x32_bf16 v[54:57], v[146:149], v[162:165], v[54:57]
	v_mfma_f32_16x16x32_bf16 v[50:53], v[154:157], v[162:165], v[50:53]
	v_mfma_f32_16x16x32_bf16 v[38:41], v[146:149], v[170:173], v[38:41]
	v_mfma_f32_16x16x32_bf16 v[34:37], v[154:157], v[170:173], v[34:37]
	v_mfma_f32_16x16x32_bf16 v[22:25], v[146:149], v[196:199], v[22:25]
	v_mfma_f32_16x16x32_bf16 v[18:21], v[154:157], v[196:199], v[18:21]
	v_mfma_f32_16x16x32_bf16 v[6:9], v[146:149], v[212:215], v[6:9]
	v_mfma_f32_16x16x32_bf16 v[2:5], v[154:157], v[212:215], v[2:5]
	v_mfma_f32_16x16x32_bf16 v[54:57], v[150:153], v[166:169], v[54:57]
	v_mfma_f32_16x16x32_bf16 v[50:53], v[158:161], v[166:169], v[50:53]
	v_mfma_f32_16x16x32_bf16 v[38:41], v[150:153], v[174:177], v[38:41]
	v_mfma_f32_16x16x32_bf16 v[34:37], v[158:161], v[174:177], v[34:37]
	v_mfma_f32_16x16x32_bf16 v[22:25], v[150:153], v[200:203], v[22:25]
	v_mfma_f32_16x16x32_bf16 v[18:21], v[158:161], v[200:203], v[18:21]
	v_mfma_f32_16x16x32_bf16 v[6:9], v[150:153], v[216:219], v[6:9]
	v_mfma_f32_16x16x32_bf16 v[2:5], v[158:161], v[216:219], v[2:5]
	s_barrier
	s_setprio 0
	s_cbranch_scc0 .LBB0_379
	s_and_b64 vcc, exec, s[34:35]
	s_cbranch_vccz .LBB0_382
	s_barrier

.LBB0_468:
	s_ashr_i32 s11, s10, 31
	s_lshl_b64 s[70:71], s[10:11], 20
	s_add_u32 s70, s89, s70
	s_addc_u32 s71, s90, s71
	s_and_b64 s[72:73], s[4:5], exec
	s_cselect_b32 s11, s71, s1
	s_cselect_b32 s76, s70, s0
	s_ashr_i32 s69, s68, 31
	s_lshl_b64 s[72:73], s[68:69], 20
	s_add_u32 s72, s91, s72
	s_addc_u32 s73, s92, s73
	s_and_b64 s[74:75], s[4:5], exec
	s_cselect_b32 s69, s73, s9
	s_cselect_b32 s77, s72, s8
	s_add_u32 s0, s0, 0x80080
	s_addc_u32 s1, s1, 0
	s_add_u32 s78, s8, 0x100
	s_addc_u32 s79, s9, 0
	s_mov_b32 s80, -2
	ds_read_b128 v[78:81], v204
	ds_read_b128 v[138:141], v204 offset:1024
	ds_read_b128 v[142:145], v204 offset:2048
	ds_read_b128 v[146:149], v204 offset:3072
	ds_read_b128 v[170:173], v205
	ds_read_b128 v[174:177], v205 offset:1024
	ds_read_b128 v[180:183], v205 offset:2048
	ds_read_b128 v[210:213], v205 offset:3072
	s_add_u32 s8, s0, 0xfff80080
	s_addc_u32 s9, s1, -1
	s_cmp_eq_u32 s80, 28
	s_cselect_b32 s75, s11, s9
	s_cselect_b32 s74, s76, s8
	s_cselect_b32 s9, s69, s79
	s_cselect_b32 s8, s77, s78
	s_add_i32 m0, s94, 0xc000
	ds_read_b128 v[214:217], v206
	ds_read_b128 v[218:221], v206 offset:1024
	ds_read_b128 v[222:225], v206 offset:2048
	ds_read_b128 v[226:229], v206 offset:3072
	ds_read_b128 v[230:233], v206 offset:4096
	ds_read_b128 v[234:237], v206 offset:5120
	ds_read_b128 v[238:241], v206 offset:6144
	ds_read_b128 v[242:245], v206 offset:7168
	global_load_lds_dwordx4 v162, s[0:1]
	s_add_i32 m0, s94, 0xe000
	s_nop 0
	global_load_lds_dwordx4 v164, s[0:1]
	s_setprio 1
	s_waitcnt vmcnt(8) lgkmcnt(0)
	s_barrier
	v_mfma_f32_16x16x32_bf16 v[66:69], v[78:81], v[214:217], 0
	v_mfma_f32_16x16x32_bf16 v[62:65], v[142:145], v[214:217], 0
	v_mfma_f32_16x16x32_bf16 v[58:61], v[78:81], v[222:225], 0
	v_mfma_f32_16x16x32_bf16 v[54:57], v[142:145], v[222:225], 0
	v_mfma_f32_16x16x32_bf16 v[46:49], v[78:81], v[230:233], 0
	v_mfma_f32_16x16x32_bf16 v[42:45], v[142:145], v[230:233], 0
	v_mfma_f32_16x16x32_bf16 v[38:41], v[78:81], v[238:241], 0
	v_mfma_f32_16x16x32_bf16 v[34:37], v[142:145], v[238:241], 0
	v_mfma_f32_16x16x32_bf16 v[66:69], v[138:141], v[218:221], v[66:69]
	v_mfma_f32_16x16x32_bf16 v[62:65], v[146:149], v[218:221], v[62:65]
	v_mfma_f32_16x16x32_bf16 v[58:61], v[138:141], v[226:229], v[58:61]
	v_mfma_f32_16x16x32_bf16 v[54:57], v[146:149], v[226:229], v[54:57]
	v_mfma_f32_16x16x32_bf16 v[46:49], v[138:141], v[234:237], v[46:49]
	v_mfma_f32_16x16x32_bf16 v[42:45], v[146:149], v[234:237], v[42:45]
	v_mfma_f32_16x16x32_bf16 v[38:41], v[138:141], v[242:245], v[38:41]
	v_mfma_f32_16x16x32_bf16 v[34:37], v[146:149], v[242:245], v[34:37]
	s_setprio 0
	s_setprio 1
	v_mfma_f32_16x16x32_bf16 v[134:137], v[170:173], v[214:217], 0
	v_mfma_f32_16x16x32_bf16 v[130:133], v[180:183], v[214:217], 0
	v_mfma_f32_16x16x32_bf16 v[126:129], v[170:173], v[222:225], 0
	v_mfma_f32_16x16x32_bf16 v[122:125], v[180:183], v[222:225], 0
	v_mfma_f32_16x16x32_bf16 v[118:121], v[170:173], v[230:233], 0
	v_mfma_f32_16x16x32_bf16 v[114:117], v[180:183], v[230:233], 0
	v_mfma_f32_16x16x32_bf16 v[110:113], v[170:173], v[238:241], 0
	v_mfma_f32_16x16x32_bf16 v[106:109], v[180:183], v[238:241], 0
	v_mfma_f32_16x16x32_bf16 v[134:137], v[174:177], v[218:221], v[134:137]
	v_mfma_f32_16x16x32_bf16 v[130:133], v[210:213], v[218:221], v[130:133]
	v_mfma_f32_16x16x32_bf16 v[126:129], v[174:177], v[226:229], v[126:129]
	v_mfma_f32_16x16x32_bf16 v[122:125], v[210:213], v[226:229], v[122:125]
	v_mfma_f32_16x16x32_bf16 v[118:121], v[174:177], v[234:237], v[118:121]
	v_mfma_f32_16x16x32_bf16 v[114:117], v[210:213], v[234:237], v[114:117]
	v_mfma_f32_16x16x32_bf16 v[110:113], v[174:177], v[242:245], v[110:113]
	v_mfma_f32_16x16x32_bf16 v[106:109], v[210:213], v[242:245], v[106:109]
	s_barrier
	s_setprio 0
	s_add_i32 s81, s53, s93
	s_add_u32 s98, s8, 0x80
	s_addc_u32 s99, s9, 0
	s_mov_b32 m0, s81
	ds_read_b128 v[214:217], v206 offset:16384
	ds_read_b128 v[218:221], v206 offset:17408
	ds_read_b128 v[222:225], v206 offset:18432
	ds_read_b128 v[226:229], v206 offset:19456
	ds_read_b128 v[230:233], v206 offset:20480
	ds_read_b128 v[234:237], v206 offset:21504
	ds_read_b128 v[238:241], v206 offset:22528
	ds_read_b128 v[242:245], v206 offset:23552
	global_load_lds_dwordx4 v152, s[8:9]
	s_add_i32 m0, s81, 0x2000
	s_add_u32 s82, s8, 0x80000
	s_addc_u32 s83, s9, 0
	s_add_i32 s81, s54, s93
	global_load_lds_dwordx4 v156, s[8:9]
	s_mov_b32 m0, s81
	s_nop 0
	global_load_lds_dwordx4 v152, s[82:83]
	s_add_i32 m0, s81, 0x2000
	s_nop 0
	global_load_lds_dwordx4 v156, s[82:83]
	s_add_u32 s100, s74, 0x80
	s_addc_u32 s101, s75, 0
	s_mov_b32 m0, s94
	s_nop 0
	global_load_lds_dwordx4 v150, s[74:75]
	s_mov_b32 m0, s95
	s_nop 0
	global_load_lds_dwordx4 v154, s[74:75]
	s_setprio 1
	s_waitcnt vmcnt(8) lgkmcnt(0)
	s_barrier
	v_mfma_f32_16x16x32_bf16 v[30:33], v[78:81], v[214:217], 0
	v_mfma_f32_16x16x32_bf16 v[26:29], v[142:145], v[214:217], 0
	v_mfma_f32_16x16x32_bf16 v[22:25], v[78:81], v[222:225], 0
	v_mfma_f32_16x16x32_bf16 v[18:21], v[142:145], v[222:225], 0
	v_mfma_f32_16x16x32_bf16 v[14:17], v[78:81], v[230:233], 0
	v_mfma_f32_16x16x32_bf16 v[10:13], v[142:145], v[230:233], 0
	v_mfma_f32_16x16x32_bf16 v[6:9], v[78:81], v[238:241], 0
	v_mfma_f32_16x16x32_bf16 v[2:5], v[142:145], v[238:241], 0
	v_mfma_f32_16x16x32_bf16 v[30:33], v[138:141], v[218:221], v[30:33]
	v_mfma_f32_16x16x32_bf16 v[26:29], v[146:149], v[218:221], v[26:29]
	v_mfma_f32_16x16x32_bf16 v[22:25], v[138:141], v[226:229], v[22:25]
	v_mfma_f32_16x16x32_bf16 v[18:21], v[146:149], v[226:229], v[18:21]
	v_mfma_f32_16x16x32_bf16 v[14:17], v[138:141], v[234:237], v[14:17]
	v_mfma_f32_16x16x32_bf16 v[10:13], v[146:149], v[234:237], v[10:13]
	v_mfma_f32_16x16x32_bf16 v[6:9], v[138:141], v[242:245], v[6:9]
	v_mfma_f32_16x16x32_bf16 v[2:5], v[146:149], v[242:245], v[2:5]
	s_setprio 0
	s_setprio 1
	v_mfma_f32_16x16x32_bf16 v[98:101], v[180:183], v[214:217], 0
	v_mfma_f32_16x16x32_bf16 v[94:97], v[170:173], v[222:225], 0
	v_mfma_f32_16x16x32_bf16 v[90:93], v[180:183], v[222:225], 0
	v_mfma_f32_16x16x32_bf16 v[86:89], v[170:173], v[230:233], 0
	v_mfma_f32_16x16x32_bf16 v[82:85], v[180:183], v[230:233], 0
	v_mfma_f32_16x16x32_bf16 v[74:77], v[170:173], v[238:241], 0
	v_mfma_f32_16x16x32_bf16 v[70:73], v[180:183], v[238:241], 0
	v_mfma_f32_16x16x32_bf16 v[78:81], v[170:173], v[214:217], 0
	v_mfma_f32_16x16x32_bf16 v[98:101], v[210:213], v[218:221], v[98:101]
	v_mfma_f32_16x16x32_bf16 v[94:97], v[174:177], v[226:229], v[94:97]
	v_mfma_f32_16x16x32_bf16 v[90:93], v[210:213], v[226:229], v[90:93]
	v_mfma_f32_16x16x32_bf16 v[86:89], v[174:177], v[234:237], v[86:89]
	v_mfma_f32_16x16x32_bf16 v[82:85], v[210:213], v[234:237], v[82:85]
	v_mfma_f32_16x16x32_bf16 v[74:77], v[174:177], v[242:245], v[74:77]
	v_mfma_f32_16x16x32_bf16 v[70:73], v[210:213], v[242:245], v[70:73]
	v_mfma_f32_16x16x32_bf16 v[78:81], v[174:177], v[218:221], v[78:81]
	s_barrier
	s_setprio 0
	s_add_i32 s81, 0, 0x18000
	s_add_i32 s82, 0, 0x1c000
	ds_read_b128 v[102:105], v204 offset:32768
	ds_read_b128 v[138:141], v204 offset:33792
	ds_read_b128 v[142:145], v204 offset:34816
	ds_read_b128 v[146:149], v204 offset:35840
	ds_read_b128 v[170:173], v205 offset:32768
	ds_read_b128 v[174:177], v205 offset:33792
	ds_read_b128 v[180:183], v205 offset:34816
	ds_read_b128 v[210:213], v205 offset:35840
	s_add_u32 s74, s74, 0x80000
	s_addc_u32 s75, s75, 0
	s_mov_b32 m0, s96
	ds_read_b128 v[214:217], v206 offset:32768
	ds_read_b128 v[218:221], v206 offset:33792
	ds_read_b128 v[222:225], v206 offset:34816
	ds_read_b128 v[226:229], v206 offset:35840
	ds_read_b128 v[230:233], v206 offset:36864
	ds_read_b128 v[234:237], v206 offset:37888
	ds_read_b128 v[238:241], v206 offset:38912
	ds_read_b128 v[242:245], v206 offset:39936
	global_load_lds_dwordx4 v150, s[74:75]
	s_mov_b32 m0, s97
	s_nop 0
	global_load_lds_dwordx4 v154, s[74:75]
	s_setprio 1
	s_waitcnt vmcnt(8) lgkmcnt(0)
	s_barrier
	v_mfma_f32_16x16x32_bf16 v[66:69], v[102:105], v[214:217], v[66:69]
	v_mfma_f32_16x16x32_bf16 v[62:65], v[142:145], v[214:217], v[62:65]
	v_mfma_f32_16x16x32_bf16 v[58:61], v[102:105], v[222:225], v[58:61]
	v_mfma_f32_16x16x32_bf16 v[54:57], v[142:145], v[222:225], v[54:57]
	v_mfma_f32_16x16x32_bf16 v[46:49], v[102:105], v[230:233], v[46:49]
	v_mfma_f32_16x16x32_bf16 v[42:45], v[142:145], v[230:233], v[42:45]
	v_mfma_f32_16x16x32_bf16 v[38:41], v[102:105], v[238:241], v[38:41]
	v_mfma_f32_16x16x32_bf16 v[34:37], v[142:145], v[238:241], v[34:37]
	v_mfma_f32_16x16x32_bf16 v[66:69], v[138:141], v[218:221], v[66:69]
	v_mfma_f32_16x16x32_bf16 v[62:65], v[146:149], v[218:221], v[62:65]
	v_mfma_f32_16x16x32_bf16 v[58:61], v[138:141], v[226:229], v[58:61]
	v_mfma_f32_16x16x32_bf16 v[54:57], v[146:149], v[226:229], v[54:57]
	v_mfma_f32_16x16x32_bf16 v[46:49], v[138:141], v[234:237], v[46:49]
	v_mfma_f32_16x16x32_bf16 v[42:45], v[146:149], v[234:237], v[42:45]
	v_mfma_f32_16x16x32_bf16 v[38:41], v[138:141], v[242:245], v[38:41]
	v_mfma_f32_16x16x32_bf16 v[34:37], v[146:149], v[242:245], v[34:37]
	s_setprio 0
	s_setprio 1
	v_mfma_f32_16x16x32_bf16 v[134:137], v[170:173], v[214:217], v[134:137]
	v_mfma_f32_16x16x32_bf16 v[130:133], v[180:183], v[214:217], v[130:133]
	v_mfma_f32_16x16x32_bf16 v[126:129], v[170:173], v[222:225], v[126:129]
	v_mfma_f32_16x16x32_bf16 v[122:125], v[180:183], v[222:225], v[122:125]
	v_mfma_f32_16x16x32_bf16 v[118:121], v[170:173], v[230:233], v[118:121]
	v_mfma_f32_16x16x32_bf16 v[114:117], v[180:183], v[230:233], v[114:117]
	v_mfma_f32_16x16x32_bf16 v[110:113], v[170:173], v[238:241], v[110:113]
	v_mfma_f32_16x16x32_bf16 v[106:109], v[180:183], v[238:241], v[106:109]
	v_mfma_f32_16x16x32_bf16 v[134:137], v[174:177], v[218:221], v[134:137]
	v_mfma_f32_16x16x32_bf16 v[130:133], v[210:213], v[218:221], v[130:133]
	v_mfma_f32_16x16x32_bf16 v[126:129], v[174:177], v[226:229], v[126:129]
	v_mfma_f32_16x16x32_bf16 v[122:125], v[210:213], v[226:229], v[122:125]
	v_mfma_f32_16x16x32_bf16 v[118:121], v[174:177], v[234:237], v[118:121]
	v_mfma_f32_16x16x32_bf16 v[114:117], v[210:213], v[234:237], v[114:117]
	v_mfma_f32_16x16x32_bf16 v[110:113], v[174:177], v[242:245], v[110:113]
	v_mfma_f32_16x16x32_bf16 v[106:109], v[210:213], v[242:245], v[106:109]
	s_barrier
	s_setprio 0
	s_add_i32 s74, s81, s93
	s_mov_b32 m0, s74
	ds_read_b128 v[214:217], v206 offset:49152
	ds_read_b128 v[218:221], v206 offset:50176
	ds_read_b128 v[222:225], v206 offset:51200
	ds_read_b128 v[226:229], v206 offset:52224
	ds_read_b128 v[230:233], v206 offset:53248
	ds_read_b128 v[234:237], v206 offset:54272
	ds_read_b128 v[238:241], v206 offset:55296
	ds_read_b128 v[242:245], v206 offset:56320
	global_load_lds_dwordx4 v152, s[98:99]
	s_add_i32 m0, s74, 0x2000
	s_add_u32 s8, s8, 0x80080
	s_addc_u32 s9, s9, 0
	s_add_i32 s74, s82, s93
	global_load_lds_dwordx4 v156, s[98:99]
	s_mov_b32 m0, s74
	s_nop 0
	global_load_lds_dwordx4 v152, s[8:9]
	s_add_i32 m0, s74, 0x2000
	s_nop 0
	global_load_lds_dwordx4 v156, s[8:9]
	s_mov_b32 m0, s85
	s_nop 0
	global_load_lds_dwordx4 v150, s[100:101]
	s_mov_b32 m0, s18
	s_nop 0
	global_load_lds_dwordx4 v154, s[100:101]
	s_setprio 1
	s_waitcnt vmcnt(8) lgkmcnt(0)
	s_barrier
	v_mfma_f32_16x16x32_bf16 v[30:33], v[102:105], v[214:217], v[30:33]
	v_mfma_f32_16x16x32_bf16 v[26:29], v[142:145], v[214:217], v[26:29]
	v_mfma_f32_16x16x32_bf16 v[22:25], v[102:105], v[222:225], v[22:25]
	v_mfma_f32_16x16x32_bf16 v[18:21], v[142:145], v[222:225], v[18:21]
	v_mfma_f32_16x16x32_bf16 v[14:17], v[102:105], v[230:233], v[14:17]
	v_mfma_f32_16x16x32_bf16 v[10:13], v[142:145], v[230:233], v[10:13]
	v_mfma_f32_16x16x32_bf16 v[6:9], v[102:105], v[238:241], v[6:9]
	v_mfma_f32_16x16x32_bf16 v[2:5], v[142:145], v[238:241], v[2:5]
	v_mfma_f32_16x16x32_bf16 v[30:33], v[138:141], v[218:221], v[30:33]
	v_mfma_f32_16x16x32_bf16 v[26:29], v[146:149], v[218:221], v[26:29]
	v_mfma_f32_16x16x32_bf16 v[22:25], v[138:141], v[226:229], v[22:25]
	v_mfma_f32_16x16x32_bf16 v[18:21], v[146:149], v[226:229], v[18:21]
	v_mfma_f32_16x16x32_bf16 v[14:17], v[138:141], v[234:237], v[14:17]
	v_mfma_f32_16x16x32_bf16 v[10:13], v[146:149], v[234:237], v[10:13]
	v_mfma_f32_16x16x32_bf16 v[6:9], v[138:141], v[242:245], v[6:9]
	v_mfma_f32_16x16x32_bf16 v[2:5], v[146:149], v[242:245], v[2:5]
	s_setprio 0
	s_setprio 1
	v_mfma_f32_16x16x32_bf16 v[78:81], v[170:173], v[214:217], v[78:81]
	v_mfma_f32_16x16x32_bf16 v[102:105], v[174:177], v[218:221], v[78:81]
	v_mfma_f32_16x16x32_bf16 v[78:81], v[180:183], v[214:217], v[98:101]
	v_mfma_f32_16x16x32_bf16 v[98:101], v[210:213], v[218:221], v[78:81]
	v_mfma_f32_16x16x32_bf16 v[78:81], v[170:173], v[222:225], v[94:97]
	v_mfma_f32_16x16x32_bf16 v[94:97], v[174:177], v[226:229], v[78:81]
	v_mfma_f32_16x16x32_bf16 v[78:81], v[180:183], v[222:225], v[90:93]
	v_mfma_f32_16x16x32_bf16 v[90:93], v[210:213], v[226:229], v[78:81]
	v_mfma_f32_16x16x32_bf16 v[78:81], v[170:173], v[230:233], v[86:89]
	v_mfma_f32_16x16x32_bf16 v[86:89], v[174:177], v[234:237], v[78:81]
	v_mfma_f32_16x16x32_bf16 v[78:81], v[180:183], v[230:233], v[82:85]
	v_mfma_f32_16x16x32_bf16 v[74:77], v[170:173], v[238:241], v[74:77]
	v_mfma_f32_16x16x32_bf16 v[70:73], v[180:183], v[238:241], v[70:73]
	v_mfma_f32_16x16x32_bf16 v[82:85], v[210:213], v[234:237], v[78:81]
	v_mfma_f32_16x16x32_bf16 v[74:77], v[174:177], v[242:245], v[74:77]
	v_mfma_f32_16x16x32_bf16 v[70:73], v[210:213], v[242:245], v[70:73]
	s_barrier
	s_setprio 0
	s_add_i32 s80, s80, 2
	s_add_u32 s0, s0, 0x100
	s_addc_u32 s1, s1, 0
	s_add_u32 s78, s78, 0x100
	s_addc_u32 s79, s79, 0
	s_cmp_gt_u32 s80, 29
.LBB0_469:
	ds_read_b128 v[78:81], v204
	ds_read_b128 v[138:141], v204 offset:1024
	ds_read_b128 v[142:145], v204 offset:2048
	ds_read_b128 v[146:149], v204 offset:3072
	ds_read_b128 v[170:173], v205
	ds_read_b128 v[174:177], v205 offset:1024
	ds_read_b128 v[180:183], v205 offset:2048
	ds_read_b128 v[210:213], v205 offset:3072
	s_add_u32 s8, s0, 0xfff80080
	s_addc_u32 s9, s1, -1
	s_cmp_eq_u32 s80, 28
	s_cselect_b32 s75, s11, s9
	s_cselect_b32 s74, s76, s8
	s_cselect_b32 s9, s69, s79
	s_cselect_b32 s8, s77, s78
	s_add_i32 m0, s94, 0xc000
	ds_read_b128 v[214:217], v206
	ds_read_b128 v[218:221], v206 offset:1024
	ds_read_b128 v[222:225], v206 offset:2048
	ds_read_b128 v[226:229], v206 offset:3072
	ds_read_b128 v[230:233], v206 offset:4096
	ds_read_b128 v[234:237], v206 offset:5120
	ds_read_b128 v[238:241], v206 offset:6144
	ds_read_b128 v[242:245], v206 offset:7168
	global_load_lds_dwordx4 v162, s[0:1]
	s_add_i32 m0, s94, 0xe000
	s_nop 0
	global_load_lds_dwordx4 v164, s[0:1]
	s_setprio 1
	s_waitcnt vmcnt(8) lgkmcnt(0)
	s_barrier
	v_mfma_f32_16x16x32_bf16 v[66:69], v[78:81], v[214:217], v[66:69]
	v_mfma_f32_16x16x32_bf16 v[62:65], v[142:145], v[214:217], v[62:65]
	v_mfma_f32_16x16x32_bf16 v[58:61], v[78:81], v[222:225], v[58:61]
	v_mfma_f32_16x16x32_bf16 v[54:57], v[142:145], v[222:225], v[54:57]
	v_mfma_f32_16x16x32_bf16 v[46:49], v[78:81], v[230:233], v[46:49]
	v_mfma_f32_16x16x32_bf16 v[42:45], v[142:145], v[230:233], v[42:45]
	v_mfma_f32_16x16x32_bf16 v[38:41], v[78:81], v[238:241], v[38:41]
	v_mfma_f32_16x16x32_bf16 v[34:37], v[142:145], v[238:241], v[34:37]
	v_mfma_f32_16x16x32_bf16 v[66:69], v[138:141], v[218:221], v[66:69]
	v_mfma_f32_16x16x32_bf16 v[62:65], v[146:149], v[218:221], v[62:65]
	v_mfma_f32_16x16x32_bf16 v[58:61], v[138:141], v[226:229], v[58:61]
	v_mfma_f32_16x16x32_bf16 v[54:57], v[146:149], v[226:229], v[54:57]
	v_mfma_f32_16x16x32_bf16 v[46:49], v[138:141], v[234:237], v[46:49]
	v_mfma_f32_16x16x32_bf16 v[42:45], v[146:149], v[234:237], v[42:45]
	v_mfma_f32_16x16x32_bf16 v[38:41], v[138:141], v[242:245], v[38:41]
	v_mfma_f32_16x16x32_bf16 v[34:37], v[146:149], v[242:245], v[34:37]
	s_setprio 0
	s_setprio 1
	v_mfma_f32_16x16x32_bf16 v[134:137], v[170:173], v[214:217], v[134:137]
	v_mfma_f32_16x16x32_bf16 v[130:133], v[180:183], v[214:217], v[130:133]
	v_mfma_f32_16x16x32_bf16 v[126:129], v[170:173], v[222:225], v[126:129]
	v_mfma_f32_16x16x32_bf16 v[122:125], v[180:183], v[222:225], v[122:125]
	v_mfma_f32_16x16x32_bf16 v[118:121], v[170:173], v[230:233], v[118:121]
	v_mfma_f32_16x16x32_bf16 v[114:117], v[180:183], v[230:233], v[114:117]
	v_mfma_f32_16x16x32_bf16 v[110:113], v[170:173], v[238:241], v[110:113]
	v_mfma_f32_16x16x32_bf16 v[106:109], v[180:183], v[238:241], v[106:109]
	v_mfma_f32_16x16x32_bf16 v[134:137], v[174:177], v[218:221], v[134:137]
	v_mfma_f32_16x16x32_bf16 v[130:133], v[210:213], v[218:221], v[130:133]
	v_mfma_f32_16x16x32_bf16 v[126:129], v[174:177], v[226:229], v[126:129]
	v_mfma_f32_16x16x32_bf16 v[122:125], v[210:213], v[226:229], v[122:125]
	v_mfma_f32_16x16x32_bf16 v[118:121], v[174:177], v[234:237], v[118:121]
	v_mfma_f32_16x16x32_bf16 v[114:117], v[210:213], v[234:237], v[114:117]
	v_mfma_f32_16x16x32_bf16 v[110:113], v[174:177], v[242:245], v[110:113]
	v_mfma_f32_16x16x32_bf16 v[106:109], v[210:213], v[242:245], v[106:109]
	s_barrier
	s_setprio 0
	s_add_i32 s81, s53, s93
	s_add_u32 s98, s8, 0x80
	s_addc_u32 s99, s9, 0
	s_mov_b32 m0, s81
	ds_read_b128 v[214:217], v206 offset:16384
	ds_read_b128 v[218:221], v206 offset:17408
	ds_read_b128 v[222:225], v206 offset:18432
	ds_read_b128 v[226:229], v206 offset:19456
	ds_read_b128 v[230:233], v206 offset:20480
	ds_read_b128 v[234:237], v206 offset:21504
	ds_read_b128 v[238:241], v206 offset:22528
	ds_read_b128 v[242:245], v206 offset:23552
	global_load_lds_dwordx4 v152, s[8:9]
	s_add_i32 m0, s81, 0x2000
	s_add_u32 s82, s8, 0x80000
	s_addc_u32 s83, s9, 0
	s_add_i32 s81, s54, s93
	global_load_lds_dwordx4 v156, s[8:9]
	s_mov_b32 m0, s81
	s_nop 0
	global_load_lds_dwordx4 v152, s[82:83]
	s_add_i32 m0, s81, 0x2000
	s_nop 0
	global_load_lds_dwordx4 v156, s[82:83]
	s_add_u32 s100, s74, 0x80
	s_addc_u32 s101, s75, 0
	s_mov_b32 m0, s94
	s_nop 0
	global_load_lds_dwordx4 v150, s[74:75]
	s_mov_b32 m0, s95
	s_nop 0
	global_load_lds_dwordx4 v154, s[74:75]
	s_setprio 1
	s_waitcnt vmcnt(8) lgkmcnt(0)
	s_barrier
	v_mfma_f32_16x16x32_bf16 v[30:33], v[78:81], v[214:217], v[30:33]
	v_mfma_f32_16x16x32_bf16 v[26:29], v[142:145], v[214:217], v[26:29]
	v_mfma_f32_16x16x32_bf16 v[22:25], v[78:81], v[222:225], v[22:25]
	v_mfma_f32_16x16x32_bf16 v[18:21], v[142:145], v[222:225], v[18:21]
	v_mfma_f32_16x16x32_bf16 v[14:17], v[78:81], v[230:233], v[14:17]
	v_mfma_f32_16x16x32_bf16 v[10:13], v[142:145], v[230:233], v[10:13]
	v_mfma_f32_16x16x32_bf16 v[6:9], v[78:81], v[238:241], v[6:9]
	v_mfma_f32_16x16x32_bf16 v[2:5], v[142:145], v[238:241], v[2:5]
	v_mfma_f32_16x16x32_bf16 v[30:33], v[138:141], v[218:221], v[30:33]
	v_mfma_f32_16x16x32_bf16 v[26:29], v[146:149], v[218:221], v[26:29]
	v_mfma_f32_16x16x32_bf16 v[22:25], v[138:141], v[226:229], v[22:25]
	v_mfma_f32_16x16x32_bf16 v[18:21], v[146:149], v[226:229], v[18:21]
	v_mfma_f32_16x16x32_bf16 v[14:17], v[138:141], v[234:237], v[14:17]
	v_mfma_f32_16x16x32_bf16 v[10:13], v[146:149], v[234:237], v[10:13]
	v_mfma_f32_16x16x32_bf16 v[6:9], v[138:141], v[242:245], v[6:9]
	v_mfma_f32_16x16x32_bf16 v[2:5], v[146:149], v[242:245], v[2:5]
	s_setprio 0
	s_setprio 1
	v_mfma_f32_16x16x32_bf16 v[98:101], v[180:183], v[214:217], v[98:101]
	v_mfma_f32_16x16x32_bf16 v[94:97], v[170:173], v[222:225], v[94:97]
	v_mfma_f32_16x16x32_bf16 v[90:93], v[180:183], v[222:225], v[90:93]
	v_mfma_f32_16x16x32_bf16 v[86:89], v[170:173], v[230:233], v[86:89]
	v_mfma_f32_16x16x32_bf16 v[82:85], v[180:183], v[230:233], v[82:85]
	v_mfma_f32_16x16x32_bf16 v[74:77], v[170:173], v[238:241], v[74:77]
	v_mfma_f32_16x16x32_bf16 v[70:73], v[180:183], v[238:241], v[70:73]
	v_mfma_f32_16x16x32_bf16 v[78:81], v[170:173], v[214:217], v[102:105]
	v_mfma_f32_16x16x32_bf16 v[98:101], v[210:213], v[218:221], v[98:101]
	v_mfma_f32_16x16x32_bf16 v[94:97], v[174:177], v[226:229], v[94:97]
	v_mfma_f32_16x16x32_bf16 v[90:93], v[210:213], v[226:229], v[90:93]
	v_mfma_f32_16x16x32_bf16 v[86:89], v[174:177], v[234:237], v[86:89]
	v_mfma_f32_16x16x32_bf16 v[82:85], v[210:213], v[234:237], v[82:85]
	v_mfma_f32_16x16x32_bf16 v[74:77], v[174:177], v[242:245], v[74:77]
	v_mfma_f32_16x16x32_bf16 v[70:73], v[210:213], v[242:245], v[70:73]
	v_mfma_f32_16x16x32_bf16 v[78:81], v[174:177], v[218:221], v[78:81]
	s_barrier
	s_setprio 0
	s_add_i32 s81, 0, 0x18000
	s_add_i32 s82, 0, 0x1c000
	ds_read_b128 v[102:105], v204 offset:32768
	ds_read_b128 v[138:141], v204 offset:33792
	ds_read_b128 v[142:145], v204 offset:34816
	ds_read_b128 v[146:149], v204 offset:35840
	ds_read_b128 v[170:173], v205 offset:32768
	ds_read_b128 v[174:177], v205 offset:33792
	ds_read_b128 v[180:183], v205 offset:34816
	ds_read_b128 v[210:213], v205 offset:35840
	s_add_u32 s74, s74, 0x80000
	s_addc_u32 s75, s75, 0
	s_mov_b32 m0, s96
	ds_read_b128 v[214:217], v206 offset:32768
	ds_read_b128 v[218:221], v206 offset:33792
	ds_read_b128 v[222:225], v206 offset:34816
	ds_read_b128 v[226:229], v206 offset:35840
	ds_read_b128 v[230:233], v206 offset:36864
	ds_read_b128 v[234:237], v206 offset:37888
	ds_read_b128 v[238:241], v206 offset:38912
	ds_read_b128 v[242:245], v206 offset:39936
	global_load_lds_dwordx4 v150, s[74:75]
	s_mov_b32 m0, s97
	s_nop 0
	global_load_lds_dwordx4 v154, s[74:75]
	s_setprio 1
	s_waitcnt vmcnt(8) lgkmcnt(0)
	s_barrier
	v_mfma_f32_16x16x32_bf16 v[66:69], v[102:105], v[214:217], v[66:69]
	v_mfma_f32_16x16x32_bf16 v[62:65], v[142:145], v[214:217], v[62:65]
	v_mfma_f32_16x16x32_bf16 v[58:61], v[102:105], v[222:225], v[58:61]
	v_mfma_f32_16x16x32_bf16 v[54:57], v[142:145], v[222:225], v[54:57]
	v_mfma_f32_16x16x32_bf16 v[46:49], v[102:105], v[230:233], v[46:49]
	v_mfma_f32_16x16x32_bf16 v[42:45], v[142:145], v[230:233], v[42:45]
	v_mfma_f32_16x16x32_bf16 v[38:41], v[102:105], v[238:241], v[38:41]
	v_mfma_f32_16x16x32_bf16 v[34:37], v[142:145], v[238:241], v[34:37]
	v_mfma_f32_16x16x32_bf16 v[66:69], v[138:141], v[218:221], v[66:69]
	v_mfma_f32_16x16x32_bf16 v[62:65], v[146:149], v[218:221], v[62:65]
	v_mfma_f32_16x16x32_bf16 v[58:61], v[138:141], v[226:229], v[58:61]
	v_mfma_f32_16x16x32_bf16 v[54:57], v[146:149], v[226:229], v[54:57]
	v_mfma_f32_16x16x32_bf16 v[46:49], v[138:141], v[234:237], v[46:49]
	v_mfma_f32_16x16x32_bf16 v[42:45], v[146:149], v[234:237], v[42:45]
	v_mfma_f32_16x16x32_bf16 v[38:41], v[138:141], v[242:245], v[38:41]
	v_mfma_f32_16x16x32_bf16 v[34:37], v[146:149], v[242:245], v[34:37]
	s_setprio 0
	s_setprio 1
	v_mfma_f32_16x16x32_bf16 v[134:137], v[170:173], v[214:217], v[134:137]
	v_mfma_f32_16x16x32_bf16 v[130:133], v[180:183], v[214:217], v[130:133]
	v_mfma_f32_16x16x32_bf16 v[126:129], v[170:173], v[222:225], v[126:129]
	v_mfma_f32_16x16x32_bf16 v[122:125], v[180:183], v[222:225], v[122:125]
	v_mfma_f32_16x16x32_bf16 v[118:121], v[170:173], v[230:233], v[118:121]
	v_mfma_f32_16x16x32_bf16 v[114:117], v[180:183], v[230:233], v[114:117]
	v_mfma_f32_16x16x32_bf16 v[110:113], v[170:173], v[238:241], v[110:113]
	v_mfma_f32_16x16x32_bf16 v[106:109], v[180:183], v[238:241], v[106:109]
	v_mfma_f32_16x16x32_bf16 v[134:137], v[174:177], v[218:221], v[134:137]
	v_mfma_f32_16x16x32_bf16 v[130:133], v[210:213], v[218:221], v[130:133]
	v_mfma_f32_16x16x32_bf16 v[126:129], v[174:177], v[226:229], v[126:129]
	v_mfma_f32_16x16x32_bf16 v[122:125], v[210:213], v[226:229], v[122:125]
	v_mfma_f32_16x16x32_bf16 v[118:121], v[174:177], v[234:237], v[118:121]
	v_mfma_f32_16x16x32_bf16 v[114:117], v[210:213], v[234:237], v[114:117]
	v_mfma_f32_16x16x32_bf16 v[110:113], v[174:177], v[242:245], v[110:113]
	v_mfma_f32_16x16x32_bf16 v[106:109], v[210:213], v[242:245], v[106:109]
	s_barrier
	s_setprio 0
	s_add_i32 s74, s81, s93
	s_mov_b32 m0, s74
	ds_read_b128 v[214:217], v206 offset:49152
	ds_read_b128 v[218:221], v206 offset:50176
	ds_read_b128 v[222:225], v206 offset:51200
	ds_read_b128 v[226:229], v206 offset:52224
	ds_read_b128 v[230:233], v206 offset:53248
	ds_read_b128 v[234:237], v206 offset:54272
	ds_read_b128 v[238:241], v206 offset:55296
	ds_read_b128 v[242:245], v206 offset:56320
	global_load_lds_dwordx4 v152, s[98:99]
	s_add_i32 m0, s74, 0x2000
	s_add_u32 s8, s8, 0x80080
	s_addc_u32 s9, s9, 0
	s_add_i32 s74, s82, s93
	global_load_lds_dwordx4 v156, s[98:99]
	s_mov_b32 m0, s74
	s_nop 0
	global_load_lds_dwordx4 v152, s[8:9]
	s_add_i32 m0, s74, 0x2000
	s_nop 0
	global_load_lds_dwordx4 v156, s[8:9]
	s_mov_b32 m0, s85
	s_nop 0
	global_load_lds_dwordx4 v150, s[100:101]
	s_mov_b32 m0, s18
	s_nop 0
	global_load_lds_dwordx4 v154, s[100:101]
	s_add_i32 s80, s80, 2
	s_add_u32 s0, s0, 0x100
	s_addc_u32 s1, s1, 0
	s_add_u32 s78, s78, 0x100
	s_addc_u32 s79, s79, 0
	s_cmp_gt_u32 s80, 29
	s_setprio 1
	s_waitcnt vmcnt(8) lgkmcnt(0)
	s_barrier
	v_mfma_f32_16x16x32_bf16 v[30:33], v[102:105], v[214:217], v[30:33]
	v_mfma_f32_16x16x32_bf16 v[26:29], v[142:145], v[214:217], v[26:29]
	v_mfma_f32_16x16x32_bf16 v[22:25], v[102:105], v[222:225], v[22:25]
	v_mfma_f32_16x16x32_bf16 v[18:21], v[142:145], v[222:225], v[18:21]
	v_mfma_f32_16x16x32_bf16 v[14:17], v[102:105], v[230:233], v[14:17]
	v_mfma_f32_16x16x32_bf16 v[10:13], v[142:145], v[230:233], v[10:13]
	v_mfma_f32_16x16x32_bf16 v[6:9], v[102:105], v[238:241], v[6:9]
	v_mfma_f32_16x16x32_bf16 v[2:5], v[142:145], v[238:241], v[2:5]
	v_mfma_f32_16x16x32_bf16 v[30:33], v[138:141], v[218:221], v[30:33]
	v_mfma_f32_16x16x32_bf16 v[26:29], v[146:149], v[218:221], v[26:29]
	v_mfma_f32_16x16x32_bf16 v[22:25], v[138:141], v[226:229], v[22:25]
	v_mfma_f32_16x16x32_bf16 v[18:21], v[146:149], v[226:229], v[18:21]
	v_mfma_f32_16x16x32_bf16 v[14:17], v[138:141], v[234:237], v[14:17]
	v_mfma_f32_16x16x32_bf16 v[10:13], v[146:149], v[234:237], v[10:13]
	v_mfma_f32_16x16x32_bf16 v[6:9], v[138:141], v[242:245], v[6:9]
	v_mfma_f32_16x16x32_bf16 v[2:5], v[146:149], v[242:245], v[2:5]
	s_setprio 0
	s_setprio 1
	v_mfma_f32_16x16x32_bf16 v[78:81], v[170:173], v[214:217], v[78:81]
	v_mfma_f32_16x16x32_bf16 v[102:105], v[174:177], v[218:221], v[78:81]
	v_mfma_f32_16x16x32_bf16 v[78:81], v[180:183], v[214:217], v[98:101]
	v_mfma_f32_16x16x32_bf16 v[98:101], v[210:213], v[218:221], v[78:81]
	v_mfma_f32_16x16x32_bf16 v[78:81], v[170:173], v[222:225], v[94:97]
	v_mfma_f32_16x16x32_bf16 v[94:97], v[174:177], v[226:229], v[78:81]
	v_mfma_f32_16x16x32_bf16 v[78:81], v[180:183], v[222:225], v[90:93]
	v_mfma_f32_16x16x32_bf16 v[90:93], v[210:213], v[226:229], v[78:81]
	v_mfma_f32_16x16x32_bf16 v[78:81], v[170:173], v[230:233], v[86:89]
	v_mfma_f32_16x16x32_bf16 v[86:89], v[174:177], v[234:237], v[78:81]
	v_mfma_f32_16x16x32_bf16 v[78:81], v[180:183], v[230:233], v[82:85]
	v_mfma_f32_16x16x32_bf16 v[74:77], v[170:173], v[238:241], v[74:77]
	v_mfma_f32_16x16x32_bf16 v[70:73], v[180:183], v[238:241], v[70:73]
	v_mfma_f32_16x16x32_bf16 v[82:85], v[210:213], v[234:237], v[78:81]
	v_mfma_f32_16x16x32_bf16 v[74:77], v[174:177], v[242:245], v[74:77]
	v_mfma_f32_16x16x32_bf16 v[70:73], v[210:213], v[242:245], v[70:73]
	s_barrier
	s_setprio 0
	s_cbranch_scc0 .LBB0_469
	s_and_b64 vcc, exec, s[58:59]
	s_cbranch_vccz .LBB0_472
	s_barrier

.LBB0_700:
	s_ashr_i32 s37, s36, 31
	s_lshl_b64 s[40:41], s[36:37], 20
	s_add_u32 s40, s18, s40
	s_addc_u32 s41, s19, s41
	s_and_b64 s[42:43], s[16:17], exec
	s_cselect_b32 s37, s41, s55
	s_cselect_b32 s75, s40, s54
	s_ashr_i32 s35, s34, 31
	s_lshl_b64 s[42:43], s[34:35], 20
	s_add_u32 s42, s28, s42
	s_addc_u32 s43, s29, s43
	s_and_b64 s[58:59], s[16:17], exec
	s_cselect_b32 s35, s43, s57
	s_cselect_b32 s76, s42, s56
	s_add_u32 s54, s54, 0x80080
	s_addc_u32 s55, s55, 0
	s_add_u32 s77, s56, 0x100
	s_addc_u32 s78, s57, 0
	s_mov_b32 s79, -2
	ds_read_b128 v[144:147], v141
	ds_read_b128 v[158:161], v141 offset:1024
	ds_read_b128 v[162:165], v141 offset:2048
	ds_read_b128 v[166:169], v141 offset:3072
	ds_read_b128 v[170:173], v142
	ds_read_b128 v[174:177], v142 offset:1024
	ds_read_b128 v[180:183], v142 offset:2048
	ds_read_b128 v[190:193], v142 offset:3072
	s_add_u32 s56, s54, 0xfff80080
	s_addc_u32 s57, s55, -1
	s_cmp_eq_u32 s79, 28
	s_cselect_b32 s59, s37, s57
	s_cselect_b32 s58, s75, s56
	s_cselect_b32 s57, s35, s78
	s_cselect_b32 s56, s76, s77
	s_add_i32 m0, s53, 0xc000
	ds_read_b128 v[194:197], v143
	ds_read_b128 v[198:201], v143 offset:1024
	ds_read_b128 v[202:205], v143 offset:2048
	ds_read_b128 v[206:209], v143 offset:3072
	ds_read_b128 v[210:213], v143 offset:4096
	ds_read_b128 v[214:217], v143 offset:5120
	ds_read_b128 v[218:221], v143 offset:6144
	ds_read_b128 v[222:225], v143 offset:7168
	global_load_lds_dwordx4 v130, s[54:55]
	s_add_i32 m0, s53, 0xe000
	s_nop 0
	global_load_lds_dwordx4 v132, s[54:55]
	s_setprio 1
	s_waitcnt vmcnt(8) lgkmcnt(0)
	s_barrier
	v_mfma_f32_16x16x32_bf16 v[126:129], v[144:147], v[194:197], 0
	v_mfma_f32_16x16x32_bf16 v[122:125], v[162:165], v[194:197], 0
	v_mfma_f32_16x16x32_bf16 v[114:117], v[144:147], v[202:205], 0
	v_mfma_f32_16x16x32_bf16 v[106:109], v[162:165], v[202:205], 0
	v_mfma_f32_16x16x32_bf16 v[98:101], v[144:147], v[210:213], 0
	v_mfma_f32_16x16x32_bf16 v[90:93], v[162:165], v[210:213], 0
	v_mfma_f32_16x16x32_bf16 v[82:85], v[144:147], v[218:221], 0
	v_mfma_f32_16x16x32_bf16 v[74:77], v[162:165], v[218:221], 0
	v_mfma_f32_16x16x32_bf16 v[126:129], v[158:161], v[198:201], v[126:129]
	v_mfma_f32_16x16x32_bf16 v[122:125], v[166:169], v[198:201], v[122:125]
	v_mfma_f32_16x16x32_bf16 v[114:117], v[158:161], v[206:209], v[114:117]
	v_mfma_f32_16x16x32_bf16 v[106:109], v[166:169], v[206:209], v[106:109]
	v_mfma_f32_16x16x32_bf16 v[98:101], v[158:161], v[214:217], v[98:101]
	v_mfma_f32_16x16x32_bf16 v[90:93], v[166:169], v[214:217], v[90:93]
	v_mfma_f32_16x16x32_bf16 v[82:85], v[158:161], v[222:225], v[82:85]
	v_mfma_f32_16x16x32_bf16 v[74:77], v[166:169], v[222:225], v[74:77]
	s_setprio 0
	s_setprio 1
	v_mfma_f32_16x16x32_bf16 v[118:121], v[170:173], v[194:197], 0
	v_mfma_f32_16x16x32_bf16 v[110:113], v[180:183], v[194:197], 0
	v_mfma_f32_16x16x32_bf16 v[102:105], v[170:173], v[202:205], 0
	v_mfma_f32_16x16x32_bf16 v[94:97], v[180:183], v[202:205], 0
	v_mfma_f32_16x16x32_bf16 v[86:89], v[170:173], v[210:213], 0
	v_mfma_f32_16x16x32_bf16 v[78:81], v[180:183], v[210:213], 0
	v_mfma_f32_16x16x32_bf16 v[70:73], v[170:173], v[218:221], 0
	v_mfma_f32_16x16x32_bf16 v[66:69], v[180:183], v[218:221], 0
	v_mfma_f32_16x16x32_bf16 v[118:121], v[174:177], v[198:201], v[118:121]
	v_mfma_f32_16x16x32_bf16 v[110:113], v[190:193], v[198:201], v[110:113]
	v_mfma_f32_16x16x32_bf16 v[102:105], v[174:177], v[206:209], v[102:105]
	v_mfma_f32_16x16x32_bf16 v[94:97], v[190:193], v[206:209], v[94:97]
	v_mfma_f32_16x16x32_bf16 v[86:89], v[174:177], v[214:217], v[86:89]
	v_mfma_f32_16x16x32_bf16 v[78:81], v[190:193], v[214:217], v[78:81]
	v_mfma_f32_16x16x32_bf16 v[70:73], v[174:177], v[222:225], v[70:73]
	v_mfma_f32_16x16x32_bf16 v[66:69], v[190:193], v[222:225], v[66:69]
	s_barrier
	s_setprio 0
	s_add_i32 s80, s68, s60
	s_add_u32 s98, s56, 0x80
	s_addc_u32 s99, s57, 0
	s_mov_b32 m0, s80
	ds_read_b128 v[194:197], v143 offset:16384
	ds_read_b128 v[198:201], v143 offset:17408
	ds_read_b128 v[202:205], v143 offset:18432
	ds_read_b128 v[206:209], v143 offset:19456
	ds_read_b128 v[210:213], v143 offset:20480
	ds_read_b128 v[214:217], v143 offset:21504
	ds_read_b128 v[218:221], v143 offset:22528
	ds_read_b128 v[222:225], v143 offset:23552
	global_load_lds_dwordx4 v152, s[56:57]
	s_add_i32 m0, s80, 0x2000
	s_add_u32 s80, s56, 0x80000
	s_addc_u32 s81, s57, 0
	s_add_i32 s82, s69, s60
	global_load_lds_dwordx4 v156, s[56:57]
	s_mov_b32 m0, s82
	s_nop 0
	global_load_lds_dwordx4 v152, s[80:81]
	s_add_i32 m0, s82, 0x2000
	s_nop 0
	global_load_lds_dwordx4 v156, s[80:81]
	s_add_u32 s100, s58, 0x80
	s_addc_u32 s101, s59, 0
	s_mov_b32 m0, s53
	s_nop 0
	global_load_lds_dwordx4 v150, s[58:59]
	s_mov_b32 m0, s61
	s_nop 0
	global_load_lds_dwordx4 v154, s[58:59]
	s_setprio 1
	s_waitcnt vmcnt(8) lgkmcnt(0)
	s_barrier
	v_mfma_f32_16x16x32_bf16 v[62:65], v[144:147], v[194:197], 0
	v_mfma_f32_16x16x32_bf16 v[58:61], v[162:165], v[194:197], 0
	v_mfma_f32_16x16x32_bf16 v[50:53], v[144:147], v[202:205], 0
	v_mfma_f32_16x16x32_bf16 v[42:45], v[162:165], v[202:205], 0
	v_mfma_f32_16x16x32_bf16 v[34:37], v[144:147], v[210:213], 0
	v_mfma_f32_16x16x32_bf16 v[26:29], v[162:165], v[210:213], 0
	v_mfma_f32_16x16x32_bf16 v[18:21], v[144:147], v[218:221], 0
	v_mfma_f32_16x16x32_bf16 v[10:13], v[162:165], v[218:221], 0
	v_mfma_f32_16x16x32_bf16 v[62:65], v[158:161], v[198:201], v[62:65]
	v_mfma_f32_16x16x32_bf16 v[58:61], v[166:169], v[198:201], v[58:61]
	v_mfma_f32_16x16x32_bf16 v[50:53], v[158:161], v[206:209], v[50:53]
	v_mfma_f32_16x16x32_bf16 v[42:45], v[166:169], v[206:209], v[42:45]
	v_mfma_f32_16x16x32_bf16 v[34:37], v[158:161], v[214:217], v[34:37]
	v_mfma_f32_16x16x32_bf16 v[26:29], v[166:169], v[214:217], v[26:29]
	v_mfma_f32_16x16x32_bf16 v[18:21], v[158:161], v[222:225], v[18:21]
	v_mfma_f32_16x16x32_bf16 v[10:13], v[166:169], v[222:225], v[10:13]
	s_setprio 0
	s_setprio 1
	v_mfma_f32_16x16x32_bf16 v[54:57], v[170:173], v[194:197], 0
	v_mfma_f32_16x16x32_bf16 v[46:49], v[180:183], v[194:197], 0
	v_mfma_f32_16x16x32_bf16 v[38:41], v[170:173], v[202:205], 0
	v_mfma_f32_16x16x32_bf16 v[30:33], v[180:183], v[202:205], 0
	v_mfma_f32_16x16x32_bf16 v[22:25], v[170:173], v[210:213], 0
	v_mfma_f32_16x16x32_bf16 v[14:17], v[180:183], v[210:213], 0
	v_mfma_f32_16x16x32_bf16 v[6:9], v[170:173], v[218:221], 0
	v_mfma_f32_16x16x32_bf16 v[2:5], v[180:183], v[218:221], 0
	v_mfma_f32_16x16x32_bf16 v[54:57], v[174:177], v[198:201], v[54:57]
	v_mfma_f32_16x16x32_bf16 v[46:49], v[190:193], v[198:201], v[46:49]
	v_mfma_f32_16x16x32_bf16 v[38:41], v[174:177], v[206:209], v[38:41]
	v_mfma_f32_16x16x32_bf16 v[30:33], v[190:193], v[206:209], v[30:33]
	v_mfma_f32_16x16x32_bf16 v[22:25], v[174:177], v[214:217], v[22:25]
	v_mfma_f32_16x16x32_bf16 v[14:17], v[190:193], v[214:217], v[14:17]
	v_mfma_f32_16x16x32_bf16 v[6:9], v[174:177], v[222:225], v[6:9]
	v_mfma_f32_16x16x32_bf16 v[2:5], v[190:193], v[222:225], v[2:5]
	s_barrier
	s_setprio 0
	s_add_i32 s80, 0, 0x18000
	s_add_i32 s81, 0, 0x1c000
	ds_read_b128 v[144:147], v141 offset:32768
	ds_read_b128 v[158:161], v141 offset:33792
	ds_read_b128 v[162:165], v141 offset:34816
	ds_read_b128 v[166:169], v141 offset:35840
	ds_read_b128 v[170:173], v142 offset:32768
	ds_read_b128 v[174:177], v142 offset:33792
	ds_read_b128 v[180:183], v142 offset:34816
	ds_read_b128 v[190:193], v142 offset:35840
	s_add_u32 s58, s58, 0x80000
	s_addc_u32 s59, s59, 0
	s_mov_b32 m0, s62
	ds_read_b128 v[194:197], v143 offset:32768
	ds_read_b128 v[198:201], v143 offset:33792
	ds_read_b128 v[202:205], v143 offset:34816
	ds_read_b128 v[206:209], v143 offset:35840
	ds_read_b128 v[210:213], v143 offset:36864
	ds_read_b128 v[214:217], v143 offset:37888
	ds_read_b128 v[218:221], v143 offset:38912
	ds_read_b128 v[222:225], v143 offset:39936
	global_load_lds_dwordx4 v150, s[58:59]
	s_mov_b32 m0, s63
	s_nop 0
	global_load_lds_dwordx4 v154, s[58:59]
	s_setprio 1
	s_waitcnt vmcnt(8) lgkmcnt(0)
	s_barrier
	v_mfma_f32_16x16x32_bf16 v[126:129], v[144:147], v[194:197], v[126:129]
	v_mfma_f32_16x16x32_bf16 v[122:125], v[162:165], v[194:197], v[122:125]
	v_mfma_f32_16x16x32_bf16 v[114:117], v[144:147], v[202:205], v[114:117]
	v_mfma_f32_16x16x32_bf16 v[106:109], v[162:165], v[202:205], v[106:109]
	v_mfma_f32_16x16x32_bf16 v[98:101], v[144:147], v[210:213], v[98:101]
	v_mfma_f32_16x16x32_bf16 v[90:93], v[162:165], v[210:213], v[90:93]
	v_mfma_f32_16x16x32_bf16 v[82:85], v[144:147], v[218:221], v[82:85]
	v_mfma_f32_16x16x32_bf16 v[74:77], v[162:165], v[218:221], v[74:77]
	v_mfma_f32_16x16x32_bf16 v[126:129], v[158:161], v[198:201], v[126:129]
	v_mfma_f32_16x16x32_bf16 v[122:125], v[166:169], v[198:201], v[122:125]
	v_mfma_f32_16x16x32_bf16 v[114:117], v[158:161], v[206:209], v[114:117]
	v_mfma_f32_16x16x32_bf16 v[106:109], v[166:169], v[206:209], v[106:109]
	v_mfma_f32_16x16x32_bf16 v[98:101], v[158:161], v[214:217], v[98:101]
	v_mfma_f32_16x16x32_bf16 v[90:93], v[166:169], v[214:217], v[90:93]
	v_mfma_f32_16x16x32_bf16 v[82:85], v[158:161], v[222:225], v[82:85]
	v_mfma_f32_16x16x32_bf16 v[74:77], v[166:169], v[222:225], v[74:77]
	s_setprio 0
	s_setprio 1
	v_mfma_f32_16x16x32_bf16 v[118:121], v[170:173], v[194:197], v[118:121]
	v_mfma_f32_16x16x32_bf16 v[110:113], v[180:183], v[194:197], v[110:113]
	v_mfma_f32_16x16x32_bf16 v[102:105], v[170:173], v[202:205], v[102:105]
	v_mfma_f32_16x16x32_bf16 v[94:97], v[180:183], v[202:205], v[94:97]
	v_mfma_f32_16x16x32_bf16 v[86:89], v[170:173], v[210:213], v[86:89]
	v_mfma_f32_16x16x32_bf16 v[78:81], v[180:183], v[210:213], v[78:81]
	v_mfma_f32_16x16x32_bf16 v[70:73], v[170:173], v[218:221], v[70:73]
	v_mfma_f32_16x16x32_bf16 v[66:69], v[180:183], v[218:221], v[66:69]
	v_mfma_f32_16x16x32_bf16 v[118:121], v[174:177], v[198:201], v[118:121]
	v_mfma_f32_16x16x32_bf16 v[110:113], v[190:193], v[198:201], v[110:113]
	v_mfma_f32_16x16x32_bf16 v[102:105], v[174:177], v[206:209], v[102:105]
	v_mfma_f32_16x16x32_bf16 v[94:97], v[190:193], v[206:209], v[94:97]
	v_mfma_f32_16x16x32_bf16 v[86:89], v[174:177], v[214:217], v[86:89]
	v_mfma_f32_16x16x32_bf16 v[78:81], v[190:193], v[214:217], v[78:81]
	v_mfma_f32_16x16x32_bf16 v[70:73], v[174:177], v[222:225], v[70:73]
	v_mfma_f32_16x16x32_bf16 v[66:69], v[190:193], v[222:225], v[66:69]
	s_barrier
	s_setprio 0
	s_add_i32 s58, s80, s60
	s_mov_b32 m0, s58
	ds_read_b128 v[194:197], v143 offset:49152
	ds_read_b128 v[198:201], v143 offset:50176
	ds_read_b128 v[202:205], v143 offset:51200
	ds_read_b128 v[206:209], v143 offset:52224
	ds_read_b128 v[210:213], v143 offset:53248
	ds_read_b128 v[214:217], v143 offset:54272
	ds_read_b128 v[218:221], v143 offset:55296
	ds_read_b128 v[222:225], v143 offset:56320
	global_load_lds_dwordx4 v152, s[98:99]
	s_add_i32 m0, s58, 0x2000
	s_add_u32 s56, s56, 0x80080
	s_addc_u32 s57, s57, 0
	s_add_i32 s58, s81, s60
	global_load_lds_dwordx4 v156, s[98:99]
	s_mov_b32 m0, s58
	s_nop 0
	global_load_lds_dwordx4 v152, s[56:57]
	s_add_i32 m0, s58, 0x2000
	s_nop 0
	global_load_lds_dwordx4 v156, s[56:57]
	s_mov_b32 m0, s65
	s_nop 0
	global_load_lds_dwordx4 v150, s[100:101]
	s_mov_b32 m0, s66
	s_nop 0
	global_load_lds_dwordx4 v154, s[100:101]
	s_setprio 1
	s_waitcnt vmcnt(8) lgkmcnt(0)
	s_barrier
	v_mfma_f32_16x16x32_bf16 v[62:65], v[144:147], v[194:197], v[62:65]
	v_mfma_f32_16x16x32_bf16 v[58:61], v[162:165], v[194:197], v[58:61]
	v_mfma_f32_16x16x32_bf16 v[50:53], v[144:147], v[202:205], v[50:53]
	v_mfma_f32_16x16x32_bf16 v[42:45], v[162:165], v[202:205], v[42:45]
	v_mfma_f32_16x16x32_bf16 v[34:37], v[144:147], v[210:213], v[34:37]
	v_mfma_f32_16x16x32_bf16 v[26:29], v[162:165], v[210:213], v[26:29]
	v_mfma_f32_16x16x32_bf16 v[18:21], v[144:147], v[218:221], v[18:21]
	v_mfma_f32_16x16x32_bf16 v[10:13], v[162:165], v[218:221], v[10:13]
	v_mfma_f32_16x16x32_bf16 v[62:65], v[158:161], v[198:201], v[62:65]
	v_mfma_f32_16x16x32_bf16 v[58:61], v[166:169], v[198:201], v[58:61]
	v_mfma_f32_16x16x32_bf16 v[50:53], v[158:161], v[206:209], v[50:53]
	v_mfma_f32_16x16x32_bf16 v[42:45], v[166:169], v[206:209], v[42:45]
	v_mfma_f32_16x16x32_bf16 v[34:37], v[158:161], v[214:217], v[34:37]
	v_mfma_f32_16x16x32_bf16 v[26:29], v[166:169], v[214:217], v[26:29]
	v_mfma_f32_16x16x32_bf16 v[18:21], v[158:161], v[222:225], v[18:21]
	v_mfma_f32_16x16x32_bf16 v[10:13], v[166:169], v[222:225], v[10:13]
	s_setprio 0
	s_setprio 1
	v_mfma_f32_16x16x32_bf16 v[54:57], v[170:173], v[194:197], v[54:57]
	v_mfma_f32_16x16x32_bf16 v[46:49], v[180:183], v[194:197], v[46:49]
	v_mfma_f32_16x16x32_bf16 v[38:41], v[170:173], v[202:205], v[38:41]
	v_mfma_f32_16x16x32_bf16 v[30:33], v[180:183], v[202:205], v[30:33]
	v_mfma_f32_16x16x32_bf16 v[22:25], v[170:173], v[210:213], v[22:25]
	v_mfma_f32_16x16x32_bf16 v[14:17], v[180:183], v[210:213], v[14:17]
	v_mfma_f32_16x16x32_bf16 v[6:9], v[170:173], v[218:221], v[6:9]
	v_mfma_f32_16x16x32_bf16 v[2:5], v[180:183], v[218:221], v[2:5]
	v_mfma_f32_16x16x32_bf16 v[54:57], v[174:177], v[198:201], v[54:57]
	v_mfma_f32_16x16x32_bf16 v[46:49], v[190:193], v[198:201], v[46:49]
	v_mfma_f32_16x16x32_bf16 v[38:41], v[174:177], v[206:209], v[38:41]
	v_mfma_f32_16x16x32_bf16 v[30:33], v[190:193], v[206:209], v[30:33]
	v_mfma_f32_16x16x32_bf16 v[22:25], v[174:177], v[214:217], v[22:25]
	v_mfma_f32_16x16x32_bf16 v[14:17], v[190:193], v[214:217], v[14:17]
	v_mfma_f32_16x16x32_bf16 v[6:9], v[174:177], v[222:225], v[6:9]
	v_mfma_f32_16x16x32_bf16 v[2:5], v[190:193], v[222:225], v[2:5]
	s_barrier
	s_setprio 0
	s_add_i32 s79, s79, 2
	s_add_u32 s54, s54, 0x100
	s_addc_u32 s55, s55, 0
	s_add_u32 s77, s77, 0x100
	s_addc_u32 s78, s78, 0
	s_cmp_gt_u32 s79, 29
.LBB0_701:
	ds_read_b128 v[144:147], v141
	ds_read_b128 v[158:161], v141 offset:1024
	ds_read_b128 v[162:165], v141 offset:2048
	ds_read_b128 v[166:169], v141 offset:3072
	ds_read_b128 v[170:173], v142
	ds_read_b128 v[174:177], v142 offset:1024
	ds_read_b128 v[180:183], v142 offset:2048
	ds_read_b128 v[190:193], v142 offset:3072
	s_add_u32 s56, s54, 0xfff80080
	s_addc_u32 s57, s55, -1
	s_cmp_eq_u32 s79, 28
	s_cselect_b32 s59, s37, s57
	s_cselect_b32 s58, s75, s56
	s_cselect_b32 s57, s35, s78
	s_cselect_b32 s56, s76, s77
	s_add_i32 m0, s53, 0xc000
	ds_read_b128 v[194:197], v143
	ds_read_b128 v[198:201], v143 offset:1024
	ds_read_b128 v[202:205], v143 offset:2048
	ds_read_b128 v[206:209], v143 offset:3072
	ds_read_b128 v[210:213], v143 offset:4096
	ds_read_b128 v[214:217], v143 offset:5120
	ds_read_b128 v[218:221], v143 offset:6144
	ds_read_b128 v[222:225], v143 offset:7168
	global_load_lds_dwordx4 v130, s[54:55]
	s_add_i32 m0, s53, 0xe000
	s_nop 0
	global_load_lds_dwordx4 v132, s[54:55]
	s_setprio 1
	s_waitcnt vmcnt(8) lgkmcnt(0)
	s_barrier
	v_mfma_f32_16x16x32_bf16 v[126:129], v[144:147], v[194:197], v[126:129]
	v_mfma_f32_16x16x32_bf16 v[122:125], v[162:165], v[194:197], v[122:125]
	v_mfma_f32_16x16x32_bf16 v[114:117], v[144:147], v[202:205], v[114:117]
	v_mfma_f32_16x16x32_bf16 v[106:109], v[162:165], v[202:205], v[106:109]
	v_mfma_f32_16x16x32_bf16 v[98:101], v[144:147], v[210:213], v[98:101]
	v_mfma_f32_16x16x32_bf16 v[90:93], v[162:165], v[210:213], v[90:93]
	v_mfma_f32_16x16x32_bf16 v[82:85], v[144:147], v[218:221], v[82:85]
	v_mfma_f32_16x16x32_bf16 v[74:77], v[162:165], v[218:221], v[74:77]
	v_mfma_f32_16x16x32_bf16 v[126:129], v[158:161], v[198:201], v[126:129]
	v_mfma_f32_16x16x32_bf16 v[122:125], v[166:169], v[198:201], v[122:125]
	v_mfma_f32_16x16x32_bf16 v[114:117], v[158:161], v[206:209], v[114:117]
	v_mfma_f32_16x16x32_bf16 v[106:109], v[166:169], v[206:209], v[106:109]
	v_mfma_f32_16x16x32_bf16 v[98:101], v[158:161], v[214:217], v[98:101]
	v_mfma_f32_16x16x32_bf16 v[90:93], v[166:169], v[214:217], v[90:93]
	v_mfma_f32_16x16x32_bf16 v[82:85], v[158:161], v[222:225], v[82:85]
	v_mfma_f32_16x16x32_bf16 v[74:77], v[166:169], v[222:225], v[74:77]
	s_setprio 0
	s_setprio 1
	v_mfma_f32_16x16x32_bf16 v[118:121], v[170:173], v[194:197], v[118:121]
	v_mfma_f32_16x16x32_bf16 v[110:113], v[180:183], v[194:197], v[110:113]
	v_mfma_f32_16x16x32_bf16 v[102:105], v[170:173], v[202:205], v[102:105]
	v_mfma_f32_16x16x32_bf16 v[94:97], v[180:183], v[202:205], v[94:97]
	v_mfma_f32_16x16x32_bf16 v[86:89], v[170:173], v[210:213], v[86:89]
	v_mfma_f32_16x16x32_bf16 v[78:81], v[180:183], v[210:213], v[78:81]
	v_mfma_f32_16x16x32_bf16 v[70:73], v[170:173], v[218:221], v[70:73]
	v_mfma_f32_16x16x32_bf16 v[66:69], v[180:183], v[218:221], v[66:69]
	v_mfma_f32_16x16x32_bf16 v[118:121], v[174:177], v[198:201], v[118:121]
	v_mfma_f32_16x16x32_bf16 v[110:113], v[190:193], v[198:201], v[110:113]
	v_mfma_f32_16x16x32_bf16 v[102:105], v[174:177], v[206:209], v[102:105]
	v_mfma_f32_16x16x32_bf16 v[94:97], v[190:193], v[206:209], v[94:97]
	v_mfma_f32_16x16x32_bf16 v[86:89], v[174:177], v[214:217], v[86:89]
	v_mfma_f32_16x16x32_bf16 v[78:81], v[190:193], v[214:217], v[78:81]
	v_mfma_f32_16x16x32_bf16 v[70:73], v[174:177], v[222:225], v[70:73]
	v_mfma_f32_16x16x32_bf16 v[66:69], v[190:193], v[222:225], v[66:69]
	s_barrier
	s_setprio 0
	s_add_i32 s80, s68, s60
	s_add_u32 s98, s56, 0x80
	s_addc_u32 s99, s57, 0
	s_mov_b32 m0, s80
	ds_read_b128 v[194:197], v143 offset:16384
	ds_read_b128 v[198:201], v143 offset:17408
	ds_read_b128 v[202:205], v143 offset:18432
	ds_read_b128 v[206:209], v143 offset:19456
	ds_read_b128 v[210:213], v143 offset:20480
	ds_read_b128 v[214:217], v143 offset:21504
	ds_read_b128 v[218:221], v143 offset:22528
	ds_read_b128 v[222:225], v143 offset:23552
	global_load_lds_dwordx4 v152, s[56:57]
	s_add_i32 m0, s80, 0x2000
	s_add_u32 s80, s56, 0x80000
	s_addc_u32 s81, s57, 0
	s_add_i32 s82, s69, s60
	global_load_lds_dwordx4 v156, s[56:57]
	s_mov_b32 m0, s82
	s_nop 0
	global_load_lds_dwordx4 v152, s[80:81]
	s_add_i32 m0, s82, 0x2000
	s_nop 0
	global_load_lds_dwordx4 v156, s[80:81]
	s_add_u32 s100, s58, 0x80
	s_addc_u32 s101, s59, 0
	s_mov_b32 m0, s53
	s_nop 0
	global_load_lds_dwordx4 v150, s[58:59]
	s_mov_b32 m0, s61
	s_nop 0
	global_load_lds_dwordx4 v154, s[58:59]
	s_setprio 1
	s_waitcnt vmcnt(8) lgkmcnt(0)
	s_barrier
	v_mfma_f32_16x16x32_bf16 v[62:65], v[144:147], v[194:197], v[62:65]
	v_mfma_f32_16x16x32_bf16 v[58:61], v[162:165], v[194:197], v[58:61]
	v_mfma_f32_16x16x32_bf16 v[50:53], v[144:147], v[202:205], v[50:53]
	v_mfma_f32_16x16x32_bf16 v[42:45], v[162:165], v[202:205], v[42:45]
	v_mfma_f32_16x16x32_bf16 v[34:37], v[144:147], v[210:213], v[34:37]
	v_mfma_f32_16x16x32_bf16 v[26:29], v[162:165], v[210:213], v[26:29]
	v_mfma_f32_16x16x32_bf16 v[18:21], v[144:147], v[218:221], v[18:21]
	v_mfma_f32_16x16x32_bf16 v[10:13], v[162:165], v[218:221], v[10:13]
	v_mfma_f32_16x16x32_bf16 v[62:65], v[158:161], v[198:201], v[62:65]
	v_mfma_f32_16x16x32_bf16 v[58:61], v[166:169], v[198:201], v[58:61]
	v_mfma_f32_16x16x32_bf16 v[50:53], v[158:161], v[206:209], v[50:53]
	v_mfma_f32_16x16x32_bf16 v[42:45], v[166:169], v[206:209], v[42:45]
	v_mfma_f32_16x16x32_bf16 v[34:37], v[158:161], v[214:217], v[34:37]
	v_mfma_f32_16x16x32_bf16 v[26:29], v[166:169], v[214:217], v[26:29]
	v_mfma_f32_16x16x32_bf16 v[18:21], v[158:161], v[222:225], v[18:21]
	v_mfma_f32_16x16x32_bf16 v[10:13], v[166:169], v[222:225], v[10:13]
	s_setprio 0
	s_setprio 1
	v_mfma_f32_16x16x32_bf16 v[54:57], v[170:173], v[194:197], v[54:57]
	v_mfma_f32_16x16x32_bf16 v[46:49], v[180:183], v[194:197], v[46:49]
	v_mfma_f32_16x16x32_bf16 v[38:41], v[170:173], v[202:205], v[38:41]
	v_mfma_f32_16x16x32_bf16 v[30:33], v[180:183], v[202:205], v[30:33]
	v_mfma_f32_16x16x32_bf16 v[22:25], v[170:173], v[210:213], v[22:25]
	v_mfma_f32_16x16x32_bf16 v[14:17], v[180:183], v[210:213], v[14:17]
	v_mfma_f32_16x16x32_bf16 v[6:9], v[170:173], v[218:221], v[6:9]
	v_mfma_f32_16x16x32_bf16 v[2:5], v[180:183], v[218:221], v[2:5]
	v_mfma_f32_16x16x32_bf16 v[54:57], v[174:177], v[198:201], v[54:57]
	v_mfma_f32_16x16x32_bf16 v[46:49], v[190:193], v[198:201], v[46:49]
	v_mfma_f32_16x16x32_bf16 v[38:41], v[174:177], v[206:209], v[38:41]
	v_mfma_f32_16x16x32_bf16 v[30:33], v[190:193], v[206:209], v[30:33]
	v_mfma_f32_16x16x32_bf16 v[22:25], v[174:177], v[214:217], v[22:25]
	v_mfma_f32_16x16x32_bf16 v[14:17], v[190:193], v[214:217], v[14:17]
	v_mfma_f32_16x16x32_bf16 v[6:9], v[174:177], v[222:225], v[6:9]
	v_mfma_f32_16x16x32_bf16 v[2:5], v[190:193], v[222:225], v[2:5]
	s_barrier
	s_setprio 0
	s_add_i32 s80, 0, 0x18000
	s_add_i32 s81, 0, 0x1c000
	ds_read_b128 v[144:147], v141 offset:32768
	ds_read_b128 v[158:161], v141 offset:33792
	ds_read_b128 v[162:165], v141 offset:34816
	ds_read_b128 v[166:169], v141 offset:35840
	ds_read_b128 v[170:173], v142 offset:32768
	ds_read_b128 v[174:177], v142 offset:33792
	ds_read_b128 v[180:183], v142 offset:34816
	ds_read_b128 v[190:193], v142 offset:35840
	s_add_u32 s58, s58, 0x80000
	s_addc_u32 s59, s59, 0
	s_mov_b32 m0, s62
	ds_read_b128 v[194:197], v143 offset:32768
	ds_read_b128 v[198:201], v143 offset:33792
	ds_read_b128 v[202:205], v143 offset:34816
	ds_read_b128 v[206:209], v143 offset:35840
	ds_read_b128 v[210:213], v143 offset:36864
	ds_read_b128 v[214:217], v143 offset:37888
	ds_read_b128 v[218:221], v143 offset:38912
	ds_read_b128 v[222:225], v143 offset:39936
	global_load_lds_dwordx4 v150, s[58:59]
	s_mov_b32 m0, s63
	s_nop 0
	global_load_lds_dwordx4 v154, s[58:59]
	s_setprio 1
	s_waitcnt vmcnt(8) lgkmcnt(0)
	s_barrier
	v_mfma_f32_16x16x32_bf16 v[126:129], v[144:147], v[194:197], v[126:129]
	v_mfma_f32_16x16x32_bf16 v[122:125], v[162:165], v[194:197], v[122:125]
	v_mfma_f32_16x16x32_bf16 v[114:117], v[144:147], v[202:205], v[114:117]
	v_mfma_f32_16x16x32_bf16 v[106:109], v[162:165], v[202:205], v[106:109]
	v_mfma_f32_16x16x32_bf16 v[98:101], v[144:147], v[210:213], v[98:101]
	v_mfma_f32_16x16x32_bf16 v[90:93], v[162:165], v[210:213], v[90:93]
	v_mfma_f32_16x16x32_bf16 v[82:85], v[144:147], v[218:221], v[82:85]
	v_mfma_f32_16x16x32_bf16 v[74:77], v[162:165], v[218:221], v[74:77]
	v_mfma_f32_16x16x32_bf16 v[126:129], v[158:161], v[198:201], v[126:129]
	v_mfma_f32_16x16x32_bf16 v[122:125], v[166:169], v[198:201], v[122:125]
	v_mfma_f32_16x16x32_bf16 v[114:117], v[158:161], v[206:209], v[114:117]
	v_mfma_f32_16x16x32_bf16 v[106:109], v[166:169], v[206:209], v[106:109]
	v_mfma_f32_16x16x32_bf16 v[98:101], v[158:161], v[214:217], v[98:101]
	v_mfma_f32_16x16x32_bf16 v[90:93], v[166:169], v[214:217], v[90:93]
	v_mfma_f32_16x16x32_bf16 v[82:85], v[158:161], v[222:225], v[82:85]
	v_mfma_f32_16x16x32_bf16 v[74:77], v[166:169], v[222:225], v[74:77]
	s_setprio 0
	s_setprio 1
	v_mfma_f32_16x16x32_bf16 v[118:121], v[170:173], v[194:197], v[118:121]
	v_mfma_f32_16x16x32_bf16 v[110:113], v[180:183], v[194:197], v[110:113]
	v_mfma_f32_16x16x32_bf16 v[102:105], v[170:173], v[202:205], v[102:105]
	v_mfma_f32_16x16x32_bf16 v[94:97], v[180:183], v[202:205], v[94:97]
	v_mfma_f32_16x16x32_bf16 v[86:89], v[170:173], v[210:213], v[86:89]
	v_mfma_f32_16x16x32_bf16 v[78:81], v[180:183], v[210:213], v[78:81]
	v_mfma_f32_16x16x32_bf16 v[70:73], v[170:173], v[218:221], v[70:73]
	v_mfma_f32_16x16x32_bf16 v[66:69], v[180:183], v[218:221], v[66:69]
	v_mfma_f32_16x16x32_bf16 v[118:121], v[174:177], v[198:201], v[118:121]
	v_mfma_f32_16x16x32_bf16 v[110:113], v[190:193], v[198:201], v[110:113]
	v_mfma_f32_16x16x32_bf16 v[102:105], v[174:177], v[206:209], v[102:105]
	v_mfma_f32_16x16x32_bf16 v[94:97], v[190:193], v[206:209], v[94:97]
	v_mfma_f32_16x16x32_bf16 v[86:89], v[174:177], v[214:217], v[86:89]
	v_mfma_f32_16x16x32_bf16 v[78:81], v[190:193], v[214:217], v[78:81]
	v_mfma_f32_16x16x32_bf16 v[70:73], v[174:177], v[222:225], v[70:73]
	v_mfma_f32_16x16x32_bf16 v[66:69], v[190:193], v[222:225], v[66:69]
	s_barrier
	s_setprio 0
	s_add_i32 s58, s80, s60
	s_mov_b32 m0, s58
	ds_read_b128 v[194:197], v143 offset:49152
	ds_read_b128 v[198:201], v143 offset:50176
	ds_read_b128 v[202:205], v143 offset:51200
	ds_read_b128 v[206:209], v143 offset:52224
	ds_read_b128 v[210:213], v143 offset:53248
	ds_read_b128 v[214:217], v143 offset:54272
	ds_read_b128 v[218:221], v143 offset:55296
	ds_read_b128 v[222:225], v143 offset:56320
	global_load_lds_dwordx4 v152, s[98:99]
	s_add_i32 m0, s58, 0x2000
	s_add_u32 s56, s56, 0x80080
	s_addc_u32 s57, s57, 0
	s_add_i32 s58, s81, s60
	global_load_lds_dwordx4 v156, s[98:99]
	s_mov_b32 m0, s58
	s_nop 0
	global_load_lds_dwordx4 v152, s[56:57]
	s_add_i32 m0, s58, 0x2000
	s_nop 0
	global_load_lds_dwordx4 v156, s[56:57]
	s_mov_b32 m0, s65
	s_nop 0
	global_load_lds_dwordx4 v150, s[100:101]
	s_mov_b32 m0, s66
	s_nop 0
	global_load_lds_dwordx4 v154, s[100:101]
	s_add_i32 s79, s79, 2
	s_add_u32 s54, s54, 0x100
	s_addc_u32 s55, s55, 0
	s_add_u32 s77, s77, 0x100
	s_addc_u32 s78, s78, 0
	s_cmp_gt_u32 s79, 29
	s_setprio 1
	s_waitcnt vmcnt(8) lgkmcnt(0)
	s_barrier
	v_mfma_f32_16x16x32_bf16 v[62:65], v[144:147], v[194:197], v[62:65]
	v_mfma_f32_16x16x32_bf16 v[58:61], v[162:165], v[194:197], v[58:61]
	v_mfma_f32_16x16x32_bf16 v[50:53], v[144:147], v[202:205], v[50:53]
	v_mfma_f32_16x16x32_bf16 v[42:45], v[162:165], v[202:205], v[42:45]
	v_mfma_f32_16x16x32_bf16 v[34:37], v[144:147], v[210:213], v[34:37]
	v_mfma_f32_16x16x32_bf16 v[26:29], v[162:165], v[210:213], v[26:29]
	v_mfma_f32_16x16x32_bf16 v[18:21], v[144:147], v[218:221], v[18:21]
	v_mfma_f32_16x16x32_bf16 v[10:13], v[162:165], v[218:221], v[10:13]
	v_mfma_f32_16x16x32_bf16 v[62:65], v[158:161], v[198:201], v[62:65]
	v_mfma_f32_16x16x32_bf16 v[58:61], v[166:169], v[198:201], v[58:61]
	v_mfma_f32_16x16x32_bf16 v[50:53], v[158:161], v[206:209], v[50:53]
	v_mfma_f32_16x16x32_bf16 v[42:45], v[166:169], v[206:209], v[42:45]
	v_mfma_f32_16x16x32_bf16 v[34:37], v[158:161], v[214:217], v[34:37]
	v_mfma_f32_16x16x32_bf16 v[26:29], v[166:169], v[214:217], v[26:29]
	v_mfma_f32_16x16x32_bf16 v[18:21], v[158:161], v[222:225], v[18:21]
	v_mfma_f32_16x16x32_bf16 v[10:13], v[166:169], v[222:225], v[10:13]
	s_setprio 0
	s_setprio 1
	v_mfma_f32_16x16x32_bf16 v[54:57], v[170:173], v[194:197], v[54:57]
	v_mfma_f32_16x16x32_bf16 v[46:49], v[180:183], v[194:197], v[46:49]
	v_mfma_f32_16x16x32_bf16 v[38:41], v[170:173], v[202:205], v[38:41]
	v_mfma_f32_16x16x32_bf16 v[30:33], v[180:183], v[202:205], v[30:33]
	v_mfma_f32_16x16x32_bf16 v[22:25], v[170:173], v[210:213], v[22:25]
	v_mfma_f32_16x16x32_bf16 v[14:17], v[180:183], v[210:213], v[14:17]
	v_mfma_f32_16x16x32_bf16 v[6:9], v[170:173], v[218:221], v[6:9]
	v_mfma_f32_16x16x32_bf16 v[2:5], v[180:183], v[218:221], v[2:5]
	v_mfma_f32_16x16x32_bf16 v[54:57], v[174:177], v[198:201], v[54:57]
	v_mfma_f32_16x16x32_bf16 v[46:49], v[190:193], v[198:201], v[46:49]
	v_mfma_f32_16x16x32_bf16 v[38:41], v[174:177], v[206:209], v[38:41]
	v_mfma_f32_16x16x32_bf16 v[30:33], v[190:193], v[206:209], v[30:33]
	v_mfma_f32_16x16x32_bf16 v[22:25], v[174:177], v[214:217], v[22:25]
	v_mfma_f32_16x16x32_bf16 v[14:17], v[190:193], v[214:217], v[14:17]
	v_mfma_f32_16x16x32_bf16 v[6:9], v[174:177], v[222:225], v[6:9]
	v_mfma_f32_16x16x32_bf16 v[2:5], v[190:193], v[222:225], v[2:5]
	s_barrier
	s_setprio 0
	s_cbranch_scc0 .LBB0_701
	s_and_b64 vcc, exec, s[6:7]
	s_cbranch_vccz .LBB0_704
	s_barrier

.LBB0_724:
	s_ashr_i32 s37, s36, 31
	s_lshl_b64 s[40:41], s[36:37], 20
	s_add_u32 s40, s31, s40
	s_addc_u32 s41, s60, s41
	s_and_b64 s[42:43], s[16:17], exec
	s_cselect_b32 s37, s41, s55
	s_cselect_b32 s76, s40, s54
	s_ashr_i32 s35, s34, 31
	s_lshl_b64 s[42:43], s[34:35], 20
	s_add_u32 s42, s18, s42
	s_addc_u32 s43, s19, s43
	s_and_b64 s[58:59], s[16:17], exec
	s_cselect_b32 s35, s43, s57
	s_cselect_b32 s77, s42, s56
	s_add_u32 s54, s54, 0x80080
	s_addc_u32 s55, s55, 0
	s_add_u32 s78, s56, 0x100
	s_addc_u32 s79, s57, 0
	s_mov_b32 s80, -2
	ds_read_b128 v[142:145], v139
	ds_read_b128 v[146:149], v139 offset:1024
	ds_read_b128 v[158:161], v139 offset:2048
	ds_read_b128 v[162:165], v139 offset:3072
	ds_read_b128 v[166:169], v140
	ds_read_b128 v[170:173], v140 offset:1024
	ds_read_b128 v[174:177], v140 offset:2048
	ds_read_b128 v[180:183], v140 offset:3072
	s_add_u32 s56, s54, 0xfff80080
	s_addc_u32 s57, s55, -1
	s_cmp_eq_u32 s80, 28
	s_cselect_b32 s59, s37, s57
	s_cselect_b32 s58, s76, s56
	s_cselect_b32 s57, s35, s79
	s_cselect_b32 s56, s77, s78
	s_add_i32 m0, s53, 0xc000
	ds_read_b128 v[184:187], v141
	ds_read_b128 v[188:191], v141 offset:1024
	ds_read_b128 v[192:195], v141 offset:2048
	ds_read_b128 v[196:199], v141 offset:3072
	ds_read_b128 v[200:203], v141 offset:4096
	ds_read_b128 v[204:207], v141 offset:5120
	ds_read_b128 v[208:211], v141 offset:6144
	ds_read_b128 v[212:215], v141 offset:7168
	global_load_lds_dwordx4 v130, s[54:55]
	s_add_i32 m0, s53, 0xe000
	s_nop 0
	global_load_lds_dwordx4 v132, s[54:55]
	s_setprio 1
	s_waitcnt vmcnt(8) lgkmcnt(0)
	s_barrier
	v_mfma_f32_16x16x32_bf16 v[126:129], v[142:145], v[184:187], 0
	v_mfma_f32_16x16x32_bf16 v[122:125], v[158:161], v[184:187], 0
	v_mfma_f32_16x16x32_bf16 v[114:117], v[142:145], v[192:195], 0
	v_mfma_f32_16x16x32_bf16 v[106:109], v[158:161], v[192:195], 0
	v_mfma_f32_16x16x32_bf16 v[98:101], v[142:145], v[200:203], 0
	v_mfma_f32_16x16x32_bf16 v[90:93], v[158:161], v[200:203], 0
	v_mfma_f32_16x16x32_bf16 v[82:85], v[142:145], v[208:211], 0
	v_mfma_f32_16x16x32_bf16 v[74:77], v[158:161], v[208:211], 0
	v_mfma_f32_16x16x32_bf16 v[126:129], v[146:149], v[188:191], v[126:129]
	v_mfma_f32_16x16x32_bf16 v[122:125], v[162:165], v[188:191], v[122:125]
	v_mfma_f32_16x16x32_bf16 v[114:117], v[146:149], v[196:199], v[114:117]
	v_mfma_f32_16x16x32_bf16 v[106:109], v[162:165], v[196:199], v[106:109]
	v_mfma_f32_16x16x32_bf16 v[98:101], v[146:149], v[204:207], v[98:101]
	v_mfma_f32_16x16x32_bf16 v[90:93], v[162:165], v[204:207], v[90:93]
	v_mfma_f32_16x16x32_bf16 v[82:85], v[146:149], v[212:215], v[82:85]
	v_mfma_f32_16x16x32_bf16 v[74:77], v[162:165], v[212:215], v[74:77]
	s_setprio 0
	s_setprio 1
	v_mfma_f32_16x16x32_bf16 v[118:121], v[166:169], v[184:187], 0
	v_mfma_f32_16x16x32_bf16 v[110:113], v[174:177], v[184:187], 0
	v_mfma_f32_16x16x32_bf16 v[102:105], v[166:169], v[192:195], 0
	v_mfma_f32_16x16x32_bf16 v[94:97], v[174:177], v[192:195], 0
	v_mfma_f32_16x16x32_bf16 v[86:89], v[166:169], v[200:203], 0
	v_mfma_f32_16x16x32_bf16 v[78:81], v[174:177], v[200:203], 0
	v_mfma_f32_16x16x32_bf16 v[70:73], v[166:169], v[208:211], 0
	v_mfma_f32_16x16x32_bf16 v[66:69], v[174:177], v[208:211], 0
	v_mfma_f32_16x16x32_bf16 v[118:121], v[170:173], v[188:191], v[118:121]
	v_mfma_f32_16x16x32_bf16 v[110:113], v[180:183], v[188:191], v[110:113]
	v_mfma_f32_16x16x32_bf16 v[102:105], v[170:173], v[196:199], v[102:105]
	v_mfma_f32_16x16x32_bf16 v[94:97], v[180:183], v[196:199], v[94:97]
	v_mfma_f32_16x16x32_bf16 v[86:89], v[170:173], v[204:207], v[86:89]
	v_mfma_f32_16x16x32_bf16 v[78:81], v[180:183], v[204:207], v[78:81]
	v_mfma_f32_16x16x32_bf16 v[70:73], v[170:173], v[212:215], v[70:73]
	v_mfma_f32_16x16x32_bf16 v[66:69], v[180:183], v[212:215], v[66:69]
	s_barrier
	s_setprio 0
	s_add_i32 s81, s69, s61
	s_add_u32 s98, s56, 0x80
	s_addc_u32 s99, s57, 0
	s_mov_b32 m0, s81
	ds_read_b128 v[184:187], v141 offset:16384
	ds_read_b128 v[188:191], v141 offset:17408
	ds_read_b128 v[192:195], v141 offset:18432
	ds_read_b128 v[196:199], v141 offset:19456
	ds_read_b128 v[200:203], v141 offset:20480
	ds_read_b128 v[204:207], v141 offset:21504
	ds_read_b128 v[208:211], v141 offset:22528
	ds_read_b128 v[212:215], v141 offset:23552
	global_load_lds_dwordx4 v152, s[56:57]
	s_add_i32 m0, s81, 0x2000
	s_add_u32 s82, s56, 0x80000
	s_addc_u32 s83, s57, 0
	s_add_i32 s81, s70, s61
	global_load_lds_dwordx4 v156, s[56:57]
	s_mov_b32 m0, s81
	s_nop 0
	global_load_lds_dwordx4 v152, s[82:83]
	s_add_i32 m0, s81, 0x2000
	s_nop 0
	global_load_lds_dwordx4 v156, s[82:83]
	s_add_u32 s100, s58, 0x80
	s_addc_u32 s101, s59, 0
	s_mov_b32 m0, s53
	s_nop 0
	global_load_lds_dwordx4 v150, s[58:59]
	s_mov_b32 m0, s62
	s_nop 0
	global_load_lds_dwordx4 v154, s[58:59]
	s_setprio 1
	s_waitcnt vmcnt(8) lgkmcnt(0)
	s_barrier
	v_mfma_f32_16x16x32_bf16 v[62:65], v[142:145], v[184:187], 0
	v_mfma_f32_16x16x32_bf16 v[58:61], v[158:161], v[184:187], 0
	v_mfma_f32_16x16x32_bf16 v[50:53], v[142:145], v[192:195], 0
	v_mfma_f32_16x16x32_bf16 v[42:45], v[158:161], v[192:195], 0
	v_mfma_f32_16x16x32_bf16 v[34:37], v[142:145], v[200:203], 0
	v_mfma_f32_16x16x32_bf16 v[26:29], v[158:161], v[200:203], 0
	v_mfma_f32_16x16x32_bf16 v[18:21], v[142:145], v[208:211], 0
	v_mfma_f32_16x16x32_bf16 v[10:13], v[158:161], v[208:211], 0
	v_mfma_f32_16x16x32_bf16 v[62:65], v[146:149], v[188:191], v[62:65]
	v_mfma_f32_16x16x32_bf16 v[58:61], v[162:165], v[188:191], v[58:61]
	v_mfma_f32_16x16x32_bf16 v[50:53], v[146:149], v[196:199], v[50:53]
	v_mfma_f32_16x16x32_bf16 v[42:45], v[162:165], v[196:199], v[42:45]
	v_mfma_f32_16x16x32_bf16 v[34:37], v[146:149], v[204:207], v[34:37]
	v_mfma_f32_16x16x32_bf16 v[26:29], v[162:165], v[204:207], v[26:29]
	v_mfma_f32_16x16x32_bf16 v[18:21], v[146:149], v[212:215], v[18:21]
	v_mfma_f32_16x16x32_bf16 v[10:13], v[162:165], v[212:215], v[10:13]
	s_setprio 0
	s_setprio 1
	v_mfma_f32_16x16x32_bf16 v[54:57], v[166:169], v[184:187], 0
	v_mfma_f32_16x16x32_bf16 v[46:49], v[174:177], v[184:187], 0
	v_mfma_f32_16x16x32_bf16 v[38:41], v[166:169], v[192:195], 0
	v_mfma_f32_16x16x32_bf16 v[30:33], v[174:177], v[192:195], 0
	v_mfma_f32_16x16x32_bf16 v[22:25], v[166:169], v[200:203], 0
	v_mfma_f32_16x16x32_bf16 v[14:17], v[174:177], v[200:203], 0
	v_mfma_f32_16x16x32_bf16 v[6:9], v[166:169], v[208:211], 0
	v_mfma_f32_16x16x32_bf16 v[2:5], v[174:177], v[208:211], 0
	v_mfma_f32_16x16x32_bf16 v[54:57], v[170:173], v[188:191], v[54:57]
	v_mfma_f32_16x16x32_bf16 v[46:49], v[180:183], v[188:191], v[46:49]
	v_mfma_f32_16x16x32_bf16 v[38:41], v[170:173], v[196:199], v[38:41]
	v_mfma_f32_16x16x32_bf16 v[30:33], v[180:183], v[196:199], v[30:33]
	v_mfma_f32_16x16x32_bf16 v[22:25], v[170:173], v[204:207], v[22:25]
	v_mfma_f32_16x16x32_bf16 v[14:17], v[180:183], v[204:207], v[14:17]
	v_mfma_f32_16x16x32_bf16 v[6:9], v[170:173], v[212:215], v[6:9]
	v_mfma_f32_16x16x32_bf16 v[2:5], v[180:183], v[212:215], v[2:5]
	s_barrier
	s_setprio 0
	s_add_i32 s81, 0, 0x18000
	s_add_i32 s82, 0, 0x1c000
	ds_read_b128 v[142:145], v139 offset:32768
	ds_read_b128 v[146:149], v139 offset:33792
	ds_read_b128 v[158:161], v139 offset:34816
	ds_read_b128 v[162:165], v139 offset:35840
	ds_read_b128 v[166:169], v140 offset:32768
	ds_read_b128 v[170:173], v140 offset:33792
	ds_read_b128 v[174:177], v140 offset:34816
	ds_read_b128 v[180:183], v140 offset:35840
	s_add_u32 s58, s58, 0x80000
	s_addc_u32 s59, s59, 0
	s_mov_b32 m0, s63
	ds_read_b128 v[184:187], v141 offset:32768
	ds_read_b128 v[188:191], v141 offset:33792
	ds_read_b128 v[192:195], v141 offset:34816
	ds_read_b128 v[196:199], v141 offset:35840
	ds_read_b128 v[200:203], v141 offset:36864
	ds_read_b128 v[204:207], v141 offset:37888
	ds_read_b128 v[208:211], v141 offset:38912
	ds_read_b128 v[212:215], v141 offset:39936
	global_load_lds_dwordx4 v150, s[58:59]
	s_mov_b32 m0, s64
	s_nop 0
	global_load_lds_dwordx4 v154, s[58:59]
	s_setprio 1
	s_waitcnt vmcnt(8) lgkmcnt(0)
	s_barrier
	v_mfma_f32_16x16x32_bf16 v[126:129], v[142:145], v[184:187], v[126:129]
	v_mfma_f32_16x16x32_bf16 v[122:125], v[158:161], v[184:187], v[122:125]
	v_mfma_f32_16x16x32_bf16 v[114:117], v[142:145], v[192:195], v[114:117]
	v_mfma_f32_16x16x32_bf16 v[106:109], v[158:161], v[192:195], v[106:109]
	v_mfma_f32_16x16x32_bf16 v[98:101], v[142:145], v[200:203], v[98:101]
	v_mfma_f32_16x16x32_bf16 v[90:93], v[158:161], v[200:203], v[90:93]
	v_mfma_f32_16x16x32_bf16 v[82:85], v[142:145], v[208:211], v[82:85]
	v_mfma_f32_16x16x32_bf16 v[74:77], v[158:161], v[208:211], v[74:77]
	v_mfma_f32_16x16x32_bf16 v[126:129], v[146:149], v[188:191], v[126:129]
	v_mfma_f32_16x16x32_bf16 v[122:125], v[162:165], v[188:191], v[122:125]
	v_mfma_f32_16x16x32_bf16 v[114:117], v[146:149], v[196:199], v[114:117]
	v_mfma_f32_16x16x32_bf16 v[106:109], v[162:165], v[196:199], v[106:109]
	v_mfma_f32_16x16x32_bf16 v[98:101], v[146:149], v[204:207], v[98:101]
	v_mfma_f32_16x16x32_bf16 v[90:93], v[162:165], v[204:207], v[90:93]
	v_mfma_f32_16x16x32_bf16 v[82:85], v[146:149], v[212:215], v[82:85]
	v_mfma_f32_16x16x32_bf16 v[74:77], v[162:165], v[212:215], v[74:77]
	s_setprio 0
	s_setprio 1
	v_mfma_f32_16x16x32_bf16 v[118:121], v[166:169], v[184:187], v[118:121]
	v_mfma_f32_16x16x32_bf16 v[110:113], v[174:177], v[184:187], v[110:113]
	v_mfma_f32_16x16x32_bf16 v[102:105], v[166:169], v[192:195], v[102:105]
	v_mfma_f32_16x16x32_bf16 v[94:97], v[174:177], v[192:195], v[94:97]
	v_mfma_f32_16x16x32_bf16 v[86:89], v[166:169], v[200:203], v[86:89]
	v_mfma_f32_16x16x32_bf16 v[78:81], v[174:177], v[200:203], v[78:81]
	v_mfma_f32_16x16x32_bf16 v[70:73], v[166:169], v[208:211], v[70:73]
	v_mfma_f32_16x16x32_bf16 v[66:69], v[174:177], v[208:211], v[66:69]
	v_mfma_f32_16x16x32_bf16 v[118:121], v[170:173], v[188:191], v[118:121]
	v_mfma_f32_16x16x32_bf16 v[110:113], v[180:183], v[188:191], v[110:113]
	v_mfma_f32_16x16x32_bf16 v[102:105], v[170:173], v[196:199], v[102:105]
	v_mfma_f32_16x16x32_bf16 v[94:97], v[180:183], v[196:199], v[94:97]
	v_mfma_f32_16x16x32_bf16 v[86:89], v[170:173], v[204:207], v[86:89]
	v_mfma_f32_16x16x32_bf16 v[78:81], v[180:183], v[204:207], v[78:81]
	v_mfma_f32_16x16x32_bf16 v[70:73], v[170:173], v[212:215], v[70:73]
	v_mfma_f32_16x16x32_bf16 v[66:69], v[180:183], v[212:215], v[66:69]
	s_barrier
	s_setprio 0
	s_add_i32 s58, s81, s61
	s_mov_b32 m0, s58
	ds_read_b128 v[184:187], v141 offset:49152
	ds_read_b128 v[188:191], v141 offset:50176
	ds_read_b128 v[192:195], v141 offset:51200
	ds_read_b128 v[196:199], v141 offset:52224
	ds_read_b128 v[200:203], v141 offset:53248
	ds_read_b128 v[204:207], v141 offset:54272
	ds_read_b128 v[208:211], v141 offset:55296
	ds_read_b128 v[212:215], v141 offset:56320
	global_load_lds_dwordx4 v152, s[98:99]
	s_add_i32 m0, s58, 0x2000
	s_add_u32 s56, s56, 0x80080
	s_addc_u32 s57, s57, 0
	s_add_i32 s58, s82, s61
	global_load_lds_dwordx4 v156, s[98:99]
	s_mov_b32 m0, s58
	s_nop 0
	global_load_lds_dwordx4 v152, s[56:57]
	s_add_i32 m0, s58, 0x2000
	s_nop 0
	global_load_lds_dwordx4 v156, s[56:57]
	s_mov_b32 m0, s66
	s_nop 0
	global_load_lds_dwordx4 v150, s[100:101]
	s_mov_b32 m0, s67
	s_nop 0
	global_load_lds_dwordx4 v154, s[100:101]
	s_setprio 1
	s_waitcnt vmcnt(8) lgkmcnt(0)
	s_barrier
	v_mfma_f32_16x16x32_bf16 v[62:65], v[142:145], v[184:187], v[62:65]
	v_mfma_f32_16x16x32_bf16 v[58:61], v[158:161], v[184:187], v[58:61]
	v_mfma_f32_16x16x32_bf16 v[50:53], v[142:145], v[192:195], v[50:53]
	v_mfma_f32_16x16x32_bf16 v[42:45], v[158:161], v[192:195], v[42:45]
	v_mfma_f32_16x16x32_bf16 v[34:37], v[142:145], v[200:203], v[34:37]
	v_mfma_f32_16x16x32_bf16 v[26:29], v[158:161], v[200:203], v[26:29]
	v_mfma_f32_16x16x32_bf16 v[18:21], v[142:145], v[208:211], v[18:21]
	v_mfma_f32_16x16x32_bf16 v[10:13], v[158:161], v[208:211], v[10:13]
	v_mfma_f32_16x16x32_bf16 v[62:65], v[146:149], v[188:191], v[62:65]
	v_mfma_f32_16x16x32_bf16 v[58:61], v[162:165], v[188:191], v[58:61]
	v_mfma_f32_16x16x32_bf16 v[50:53], v[146:149], v[196:199], v[50:53]
	v_mfma_f32_16x16x32_bf16 v[42:45], v[162:165], v[196:199], v[42:45]
	v_mfma_f32_16x16x32_bf16 v[34:37], v[146:149], v[204:207], v[34:37]
	v_mfma_f32_16x16x32_bf16 v[26:29], v[162:165], v[204:207], v[26:29]
	v_mfma_f32_16x16x32_bf16 v[18:21], v[146:149], v[212:215], v[18:21]
	v_mfma_f32_16x16x32_bf16 v[10:13], v[162:165], v[212:215], v[10:13]
	s_setprio 0
	s_setprio 1
	v_mfma_f32_16x16x32_bf16 v[54:57], v[166:169], v[184:187], v[54:57]
	v_mfma_f32_16x16x32_bf16 v[46:49], v[174:177], v[184:187], v[46:49]
	v_mfma_f32_16x16x32_bf16 v[38:41], v[166:169], v[192:195], v[38:41]
	v_mfma_f32_16x16x32_bf16 v[30:33], v[174:177], v[192:195], v[30:33]
	v_mfma_f32_16x16x32_bf16 v[22:25], v[166:169], v[200:203], v[22:25]
	v_mfma_f32_16x16x32_bf16 v[14:17], v[174:177], v[200:203], v[14:17]
	v_mfma_f32_16x16x32_bf16 v[6:9], v[166:169], v[208:211], v[6:9]
	v_mfma_f32_16x16x32_bf16 v[2:5], v[174:177], v[208:211], v[2:5]
	v_mfma_f32_16x16x32_bf16 v[54:57], v[170:173], v[188:191], v[54:57]
	v_mfma_f32_16x16x32_bf16 v[46:49], v[180:183], v[188:191], v[46:49]
	v_mfma_f32_16x16x32_bf16 v[38:41], v[170:173], v[196:199], v[38:41]
	v_mfma_f32_16x16x32_bf16 v[30:33], v[180:183], v[196:199], v[30:33]
	v_mfma_f32_16x16x32_bf16 v[22:25], v[170:173], v[204:207], v[22:25]
	v_mfma_f32_16x16x32_bf16 v[14:17], v[180:183], v[204:207], v[14:17]
	v_mfma_f32_16x16x32_bf16 v[6:9], v[170:173], v[212:215], v[6:9]
	v_mfma_f32_16x16x32_bf16 v[2:5], v[180:183], v[212:215], v[2:5]
	s_barrier
	s_setprio 0
	s_add_i32 s80, s80, 2
	s_add_u32 s54, s54, 0x100
	s_addc_u32 s55, s55, 0
	s_add_u32 s78, s78, 0x100
	s_addc_u32 s79, s79, 0
	s_cmp_gt_u32 s80, 29
.LBB0_725:
	ds_read_b128 v[142:145], v139
	ds_read_b128 v[146:149], v139 offset:1024
	ds_read_b128 v[158:161], v139 offset:2048
	ds_read_b128 v[162:165], v139 offset:3072
	ds_read_b128 v[166:169], v140
	ds_read_b128 v[170:173], v140 offset:1024
	ds_read_b128 v[174:177], v140 offset:2048
	ds_read_b128 v[180:183], v140 offset:3072
	s_add_u32 s56, s54, 0xfff80080
	s_addc_u32 s57, s55, -1
	s_cmp_eq_u32 s80, 28
	s_cselect_b32 s59, s37, s57
	s_cselect_b32 s58, s76, s56
	s_cselect_b32 s57, s35, s79
	s_cselect_b32 s56, s77, s78
	s_add_i32 m0, s53, 0xc000
	ds_read_b128 v[184:187], v141
	ds_read_b128 v[188:191], v141 offset:1024
	ds_read_b128 v[192:195], v141 offset:2048
	ds_read_b128 v[196:199], v141 offset:3072
	ds_read_b128 v[200:203], v141 offset:4096
	ds_read_b128 v[204:207], v141 offset:5120
	ds_read_b128 v[208:211], v141 offset:6144
	ds_read_b128 v[212:215], v141 offset:7168
	global_load_lds_dwordx4 v130, s[54:55]
	s_add_i32 m0, s53, 0xe000
	s_nop 0
	global_load_lds_dwordx4 v132, s[54:55]
	s_setprio 1
	s_waitcnt vmcnt(8) lgkmcnt(0)
	s_barrier
	v_mfma_f32_16x16x32_bf16 v[126:129], v[142:145], v[184:187], v[126:129]
	v_mfma_f32_16x16x32_bf16 v[122:125], v[158:161], v[184:187], v[122:125]
	v_mfma_f32_16x16x32_bf16 v[114:117], v[142:145], v[192:195], v[114:117]
	v_mfma_f32_16x16x32_bf16 v[106:109], v[158:161], v[192:195], v[106:109]
	v_mfma_f32_16x16x32_bf16 v[98:101], v[142:145], v[200:203], v[98:101]
	v_mfma_f32_16x16x32_bf16 v[90:93], v[158:161], v[200:203], v[90:93]
	v_mfma_f32_16x16x32_bf16 v[82:85], v[142:145], v[208:211], v[82:85]
	v_mfma_f32_16x16x32_bf16 v[74:77], v[158:161], v[208:211], v[74:77]
	v_mfma_f32_16x16x32_bf16 v[126:129], v[146:149], v[188:191], v[126:129]
	v_mfma_f32_16x16x32_bf16 v[122:125], v[162:165], v[188:191], v[122:125]
	v_mfma_f32_16x16x32_bf16 v[114:117], v[146:149], v[196:199], v[114:117]
	v_mfma_f32_16x16x32_bf16 v[106:109], v[162:165], v[196:199], v[106:109]
	v_mfma_f32_16x16x32_bf16 v[98:101], v[146:149], v[204:207], v[98:101]
	v_mfma_f32_16x16x32_bf16 v[90:93], v[162:165], v[204:207], v[90:93]
	v_mfma_f32_16x16x32_bf16 v[82:85], v[146:149], v[212:215], v[82:85]
	v_mfma_f32_16x16x32_bf16 v[74:77], v[162:165], v[212:215], v[74:77]
	s_setprio 0
	s_setprio 1
	v_mfma_f32_16x16x32_bf16 v[118:121], v[166:169], v[184:187], v[118:121]
	v_mfma_f32_16x16x32_bf16 v[110:113], v[174:177], v[184:187], v[110:113]
	v_mfma_f32_16x16x32_bf16 v[102:105], v[166:169], v[192:195], v[102:105]
	v_mfma_f32_16x16x32_bf16 v[94:97], v[174:177], v[192:195], v[94:97]
	v_mfma_f32_16x16x32_bf16 v[86:89], v[166:169], v[200:203], v[86:89]
	v_mfma_f32_16x16x32_bf16 v[78:81], v[174:177], v[200:203], v[78:81]
	v_mfma_f32_16x16x32_bf16 v[70:73], v[166:169], v[208:211], v[70:73]
	v_mfma_f32_16x16x32_bf16 v[66:69], v[174:177], v[208:211], v[66:69]
	v_mfma_f32_16x16x32_bf16 v[118:121], v[170:173], v[188:191], v[118:121]
	v_mfma_f32_16x16x32_bf16 v[110:113], v[180:183], v[188:191], v[110:113]
	v_mfma_f32_16x16x32_bf16 v[102:105], v[170:173], v[196:199], v[102:105]
	v_mfma_f32_16x16x32_bf16 v[94:97], v[180:183], v[196:199], v[94:97]
	v_mfma_f32_16x16x32_bf16 v[86:89], v[170:173], v[204:207], v[86:89]
	v_mfma_f32_16x16x32_bf16 v[78:81], v[180:183], v[204:207], v[78:81]
	v_mfma_f32_16x16x32_bf16 v[70:73], v[170:173], v[212:215], v[70:73]
	v_mfma_f32_16x16x32_bf16 v[66:69], v[180:183], v[212:215], v[66:69]
	s_barrier
	s_setprio 0
	s_add_i32 s81, s69, s61
	s_add_u32 s98, s56, 0x80
	s_addc_u32 s99, s57, 0
	s_mov_b32 m0, s81
	ds_read_b128 v[184:187], v141 offset:16384
	ds_read_b128 v[188:191], v141 offset:17408
	ds_read_b128 v[192:195], v141 offset:18432
	ds_read_b128 v[196:199], v141 offset:19456
	ds_read_b128 v[200:203], v141 offset:20480
	ds_read_b128 v[204:207], v141 offset:21504
	ds_read_b128 v[208:211], v141 offset:22528
	ds_read_b128 v[212:215], v141 offset:23552
	global_load_lds_dwordx4 v152, s[56:57]
	s_add_i32 m0, s81, 0x2000
	s_add_u32 s82, s56, 0x80000
	s_addc_u32 s83, s57, 0
	s_add_i32 s81, s70, s61
	global_load_lds_dwordx4 v156, s[56:57]
	s_mov_b32 m0, s81
	s_nop 0
	global_load_lds_dwordx4 v152, s[82:83]
	s_add_i32 m0, s81, 0x2000
	s_nop 0
	global_load_lds_dwordx4 v156, s[82:83]
	s_add_u32 s100, s58, 0x80
	s_addc_u32 s101, s59, 0
	s_mov_b32 m0, s53
	s_nop 0
	global_load_lds_dwordx4 v150, s[58:59]
	s_mov_b32 m0, s62
	s_nop 0
	global_load_lds_dwordx4 v154, s[58:59]
	s_setprio 1
	s_waitcnt vmcnt(8) lgkmcnt(0)
	s_barrier
	v_mfma_f32_16x16x32_bf16 v[62:65], v[142:145], v[184:187], v[62:65]
	v_mfma_f32_16x16x32_bf16 v[58:61], v[158:161], v[184:187], v[58:61]
	v_mfma_f32_16x16x32_bf16 v[50:53], v[142:145], v[192:195], v[50:53]
	v_mfma_f32_16x16x32_bf16 v[42:45], v[158:161], v[192:195], v[42:45]
	v_mfma_f32_16x16x32_bf16 v[34:37], v[142:145], v[200:203], v[34:37]
	v_mfma_f32_16x16x32_bf16 v[26:29], v[158:161], v[200:203], v[26:29]
	v_mfma_f32_16x16x32_bf16 v[18:21], v[142:145], v[208:211], v[18:21]
	v_mfma_f32_16x16x32_bf16 v[10:13], v[158:161], v[208:211], v[10:13]
	v_mfma_f32_16x16x32_bf16 v[62:65], v[146:149], v[188:191], v[62:65]
	v_mfma_f32_16x16x32_bf16 v[58:61], v[162:165], v[188:191], v[58:61]
	v_mfma_f32_16x16x32_bf16 v[50:53], v[146:149], v[196:199], v[50:53]
	v_mfma_f32_16x16x32_bf16 v[42:45], v[162:165], v[196:199], v[42:45]
	v_mfma_f32_16x16x32_bf16 v[34:37], v[146:149], v[204:207], v[34:37]
	v_mfma_f32_16x16x32_bf16 v[26:29], v[162:165], v[204:207], v[26:29]
	v_mfma_f32_16x16x32_bf16 v[18:21], v[146:149], v[212:215], v[18:21]
	v_mfma_f32_16x16x32_bf16 v[10:13], v[162:165], v[212:215], v[10:13]
	s_setprio 0
	s_setprio 1
	v_mfma_f32_16x16x32_bf16 v[54:57], v[166:169], v[184:187], v[54:57]
	v_mfma_f32_16x16x32_bf16 v[46:49], v[174:177], v[184:187], v[46:49]
	v_mfma_f32_16x16x32_bf16 v[38:41], v[166:169], v[192:195], v[38:41]
	v_mfma_f32_16x16x32_bf16 v[30:33], v[174:177], v[192:195], v[30:33]
	v_mfma_f32_16x16x32_bf16 v[22:25], v[166:169], v[200:203], v[22:25]
	v_mfma_f32_16x16x32_bf16 v[14:17], v[174:177], v[200:203], v[14:17]
	v_mfma_f32_16x16x32_bf16 v[6:9], v[166:169], v[208:211], v[6:9]
	v_mfma_f32_16x16x32_bf16 v[2:5], v[174:177], v[208:211], v[2:5]
	v_mfma_f32_16x16x32_bf16 v[54:57], v[170:173], v[188:191], v[54:57]
	v_mfma_f32_16x16x32_bf16 v[46:49], v[180:183], v[188:191], v[46:49]
	v_mfma_f32_16x16x32_bf16 v[38:41], v[170:173], v[196:199], v[38:41]
	v_mfma_f32_16x16x32_bf16 v[30:33], v[180:183], v[196:199], v[30:33]
	v_mfma_f32_16x16x32_bf16 v[22:25], v[170:173], v[204:207], v[22:25]
	v_mfma_f32_16x16x32_bf16 v[14:17], v[180:183], v[204:207], v[14:17]
	v_mfma_f32_16x16x32_bf16 v[6:9], v[170:173], v[212:215], v[6:9]
	v_mfma_f32_16x16x32_bf16 v[2:5], v[180:183], v[212:215], v[2:5]
	s_barrier
	s_setprio 0
	s_add_i32 s81, 0, 0x18000
	s_add_i32 s82, 0, 0x1c000
	ds_read_b128 v[142:145], v139 offset:32768
	ds_read_b128 v[146:149], v139 offset:33792
	ds_read_b128 v[158:161], v139 offset:34816
	ds_read_b128 v[162:165], v139 offset:35840
	ds_read_b128 v[166:169], v140 offset:32768
	ds_read_b128 v[170:173], v140 offset:33792
	ds_read_b128 v[174:177], v140 offset:34816
	ds_read_b128 v[180:183], v140 offset:35840
	s_add_u32 s58, s58, 0x80000
	s_addc_u32 s59, s59, 0
	s_mov_b32 m0, s63
	ds_read_b128 v[184:187], v141 offset:32768
	ds_read_b128 v[188:191], v141 offset:33792
	ds_read_b128 v[192:195], v141 offset:34816
	ds_read_b128 v[196:199], v141 offset:35840
	ds_read_b128 v[200:203], v141 offset:36864
	ds_read_b128 v[204:207], v141 offset:37888
	ds_read_b128 v[208:211], v141 offset:38912
	ds_read_b128 v[212:215], v141 offset:39936
	global_load_lds_dwordx4 v150, s[58:59]
	s_mov_b32 m0, s64
	s_nop 0
	global_load_lds_dwordx4 v154, s[58:59]
	s_setprio 1
	s_waitcnt vmcnt(8) lgkmcnt(0)
	s_barrier
	v_mfma_f32_16x16x32_bf16 v[126:129], v[142:145], v[184:187], v[126:129]
	v_mfma_f32_16x16x32_bf16 v[122:125], v[158:161], v[184:187], v[122:125]
	v_mfma_f32_16x16x32_bf16 v[114:117], v[142:145], v[192:195], v[114:117]
	v_mfma_f32_16x16x32_bf16 v[106:109], v[158:161], v[192:195], v[106:109]
	v_mfma_f32_16x16x32_bf16 v[98:101], v[142:145], v[200:203], v[98:101]
	v_mfma_f32_16x16x32_bf16 v[90:93], v[158:161], v[200:203], v[90:93]
	v_mfma_f32_16x16x32_bf16 v[82:85], v[142:145], v[208:211], v[82:85]
	v_mfma_f32_16x16x32_bf16 v[74:77], v[158:161], v[208:211], v[74:77]
	v_mfma_f32_16x16x32_bf16 v[126:129], v[146:149], v[188:191], v[126:129]
	v_mfma_f32_16x16x32_bf16 v[122:125], v[162:165], v[188:191], v[122:125]
	v_mfma_f32_16x16x32_bf16 v[114:117], v[146:149], v[196:199], v[114:117]
	v_mfma_f32_16x16x32_bf16 v[106:109], v[162:165], v[196:199], v[106:109]
	v_mfma_f32_16x16x32_bf16 v[98:101], v[146:149], v[204:207], v[98:101]
	v_mfma_f32_16x16x32_bf16 v[90:93], v[162:165], v[204:207], v[90:93]
	v_mfma_f32_16x16x32_bf16 v[82:85], v[146:149], v[212:215], v[82:85]
	v_mfma_f32_16x16x32_bf16 v[74:77], v[162:165], v[212:215], v[74:77]
	s_setprio 0
	s_setprio 1
	v_mfma_f32_16x16x32_bf16 v[118:121], v[166:169], v[184:187], v[118:121]
	v_mfma_f32_16x16x32_bf16 v[110:113], v[174:177], v[184:187], v[110:113]
	v_mfma_f32_16x16x32_bf16 v[102:105], v[166:169], v[192:195], v[102:105]
	v_mfma_f32_16x16x32_bf16 v[94:97], v[174:177], v[192:195], v[94:97]
	v_mfma_f32_16x16x32_bf16 v[86:89], v[166:169], v[200:203], v[86:89]
	v_mfma_f32_16x16x32_bf16 v[78:81], v[174:177], v[200:203], v[78:81]
	v_mfma_f32_16x16x32_bf16 v[70:73], v[166:169], v[208:211], v[70:73]
	v_mfma_f32_16x16x32_bf16 v[66:69], v[174:177], v[208:211], v[66:69]
	v_mfma_f32_16x16x32_bf16 v[118:121], v[170:173], v[188:191], v[118:121]
	v_mfma_f32_16x16x32_bf16 v[110:113], v[180:183], v[188:191], v[110:113]
	v_mfma_f32_16x16x32_bf16 v[102:105], v[170:173], v[196:199], v[102:105]
	v_mfma_f32_16x16x32_bf16 v[94:97], v[180:183], v[196:199], v[94:97]
	v_mfma_f32_16x16x32_bf16 v[86:89], v[170:173], v[204:207], v[86:89]
	v_mfma_f32_16x16x32_bf16 v[78:81], v[180:183], v[204:207], v[78:81]
	v_mfma_f32_16x16x32_bf16 v[70:73], v[170:173], v[212:215], v[70:73]
	v_mfma_f32_16x16x32_bf16 v[66:69], v[180:183], v[212:215], v[66:69]
	s_barrier
	s_setprio 0
	s_add_i32 s58, s81, s61
	s_mov_b32 m0, s58
	ds_read_b128 v[184:187], v141 offset:49152
	ds_read_b128 v[188:191], v141 offset:50176
	ds_read_b128 v[192:195], v141 offset:51200
	ds_read_b128 v[196:199], v141 offset:52224
	ds_read_b128 v[200:203], v141 offset:53248
	ds_read_b128 v[204:207], v141 offset:54272
	ds_read_b128 v[208:211], v141 offset:55296
	ds_read_b128 v[212:215], v141 offset:56320
	global_load_lds_dwordx4 v152, s[98:99]
	s_add_i32 m0, s58, 0x2000
	s_add_u32 s56, s56, 0x80080
	s_addc_u32 s57, s57, 0
	s_add_i32 s58, s82, s61
	global_load_lds_dwordx4 v156, s[98:99]
	s_mov_b32 m0, s58
	s_nop 0
	global_load_lds_dwordx4 v152, s[56:57]
	s_add_i32 m0, s58, 0x2000
	s_nop 0
	global_load_lds_dwordx4 v156, s[56:57]
	s_mov_b32 m0, s66
	s_nop 0
	global_load_lds_dwordx4 v150, s[100:101]
	s_mov_b32 m0, s67
	s_nop 0
	global_load_lds_dwordx4 v154, s[100:101]
	s_add_i32 s80, s80, 2
	s_add_u32 s54, s54, 0x100
	s_addc_u32 s55, s55, 0
	s_add_u32 s78, s78, 0x100
	s_addc_u32 s79, s79, 0
	s_cmp_gt_u32 s80, 29
	s_setprio 1
	s_waitcnt vmcnt(8) lgkmcnt(0)
	s_barrier
	v_mfma_f32_16x16x32_bf16 v[62:65], v[142:145], v[184:187], v[62:65]
	v_mfma_f32_16x16x32_bf16 v[58:61], v[158:161], v[184:187], v[58:61]
	v_mfma_f32_16x16x32_bf16 v[50:53], v[142:145], v[192:195], v[50:53]
	v_mfma_f32_16x16x32_bf16 v[42:45], v[158:161], v[192:195], v[42:45]
	v_mfma_f32_16x16x32_bf16 v[34:37], v[142:145], v[200:203], v[34:37]
	v_mfma_f32_16x16x32_bf16 v[26:29], v[158:161], v[200:203], v[26:29]
	v_mfma_f32_16x16x32_bf16 v[18:21], v[142:145], v[208:211], v[18:21]
	v_mfma_f32_16x16x32_bf16 v[10:13], v[158:161], v[208:211], v[10:13]
	v_mfma_f32_16x16x32_bf16 v[62:65], v[146:149], v[188:191], v[62:65]
	v_mfma_f32_16x16x32_bf16 v[58:61], v[162:165], v[188:191], v[58:61]
	v_mfma_f32_16x16x32_bf16 v[50:53], v[146:149], v[196:199], v[50:53]
	v_mfma_f32_16x16x32_bf16 v[42:45], v[162:165], v[196:199], v[42:45]
	v_mfma_f32_16x16x32_bf16 v[34:37], v[146:149], v[204:207], v[34:37]
	v_mfma_f32_16x16x32_bf16 v[26:29], v[162:165], v[204:207], v[26:29]
	v_mfma_f32_16x16x32_bf16 v[18:21], v[146:149], v[212:215], v[18:21]
	v_mfma_f32_16x16x32_bf16 v[10:13], v[162:165], v[212:215], v[10:13]
	s_setprio 0
	s_setprio 1
	v_mfma_f32_16x16x32_bf16 v[54:57], v[166:169], v[184:187], v[54:57]
	v_mfma_f32_16x16x32_bf16 v[46:49], v[174:177], v[184:187], v[46:49]
	v_mfma_f32_16x16x32_bf16 v[38:41], v[166:169], v[192:195], v[38:41]
	v_mfma_f32_16x16x32_bf16 v[30:33], v[174:177], v[192:195], v[30:33]
	v_mfma_f32_16x16x32_bf16 v[22:25], v[166:169], v[200:203], v[22:25]
	v_mfma_f32_16x16x32_bf16 v[14:17], v[174:177], v[200:203], v[14:17]
	v_mfma_f32_16x16x32_bf16 v[6:9], v[166:169], v[208:211], v[6:9]
	v_mfma_f32_16x16x32_bf16 v[2:5], v[174:177], v[208:211], v[2:5]
	v_mfma_f32_16x16x32_bf16 v[54:57], v[170:173], v[188:191], v[54:57]
	v_mfma_f32_16x16x32_bf16 v[46:49], v[180:183], v[188:191], v[46:49]
	v_mfma_f32_16x16x32_bf16 v[38:41], v[170:173], v[196:199], v[38:41]
	v_mfma_f32_16x16x32_bf16 v[30:33], v[180:183], v[196:199], v[30:33]
	v_mfma_f32_16x16x32_bf16 v[22:25], v[170:173], v[204:207], v[22:25]
	v_mfma_f32_16x16x32_bf16 v[14:17], v[180:183], v[204:207], v[14:17]
	v_mfma_f32_16x16x32_bf16 v[6:9], v[170:173], v[212:215], v[6:9]
	v_mfma_f32_16x16x32_bf16 v[2:5], v[180:183], v[212:215], v[2:5]
	s_barrier
	s_setprio 0
	s_cbranch_scc0 .LBB0_725
	s_and_b64 vcc, exec, s[6:7]
	s_cbranch_vccz .LBB0_728
	s_barrier

.LBB0_1328:
	s_add_u32 s40, s36, s38
	ds_read_b128 v[134:137], v236
	ds_read_b128 v[138:141], v236 offset:1024
	ds_read_b128 v[142:145], v236 offset:2048
	ds_read_b128 v[146:149], v236 offset:3072
	s_addc_u32 s41, s37, s39
	ds_read_b128 v[150:153], v236 offset:16384
	ds_read_b128 v[154:157], v236 offset:17408
	ds_read_b128 v[158:161], v236 offset:18432
	ds_read_b128 v[162:165], v236 offset:19456
	s_add_u32 s40, s40, 0x100
	s_addc_u32 s41, s41, 0
	s_add_u32 s69, s66, s38
	s_addc_u32 s70, s67, s39
	s_cmpk_eq_i32 s38, 0xf00
	s_cselect_b32 s42, s60, s40
	s_cselect_b32 s40, s63, s69
	s_cselect_b32 s43, s17, s41
	s_cselect_b32 s41, s62, s70
	v_lshl_add_u64 v[4:5], v[190:191], 0, s[38:39]
	s_add_i32 m0, s29, 0xc000
	ds_read_b128 v[166:169], v199
	ds_read_b128 v[170:173], v199 offset:1024
	ds_read_b128 v[200:203], v199 offset:2048
	ds_read_b128 v[204:207], v199 offset:3072
	ds_read_b128 v[208:211], v199 offset:4096
	ds_read_b128 v[212:215], v199 offset:5120
	ds_read_b128 v[216:219], v199 offset:6144
	ds_read_b128 v[220:223], v199 offset:7168
	global_load_lds_dwordx4 v[4:5], off
	v_lshl_add_u64 v[4:5], v[192:193], 0, s[38:39]
	s_add_i32 m0, s29, 0xe000
	s_nop 0
	global_load_lds_dwordx4 v[4:5], off
	s_setprio 1
	s_waitcnt vmcnt(8) lgkmcnt(0)
	s_barrier
	v_mfma_f32_16x16x32_bf16 v[130:133], v[134:137], v[166:169], v[130:133]
	v_mfma_f32_16x16x32_bf16 v[126:129], v[142:145], v[166:169], v[126:129]
	v_mfma_f32_16x16x32_bf16 v[114:117], v[134:137], v[200:203], v[114:117]
	v_mfma_f32_16x16x32_bf16 v[110:113], v[142:145], v[200:203], v[110:113]
	v_mfma_f32_16x16x32_bf16 v[98:101], v[134:137], v[208:211], v[98:101]
	v_mfma_f32_16x16x32_bf16 v[94:97], v[142:145], v[208:211], v[94:97]
	v_mfma_f32_16x16x32_bf16 v[82:85], v[134:137], v[216:219], v[82:85]
	v_mfma_f32_16x16x32_bf16 v[78:81], v[142:145], v[216:219], v[78:81]
	v_mfma_f32_16x16x32_bf16 v[130:133], v[138:141], v[170:173], v[130:133]
	v_mfma_f32_16x16x32_bf16 v[126:129], v[146:149], v[170:173], v[126:129]
	v_mfma_f32_16x16x32_bf16 v[114:117], v[138:141], v[204:207], v[114:117]
	v_mfma_f32_16x16x32_bf16 v[110:113], v[146:149], v[204:207], v[110:113]
	v_mfma_f32_16x16x32_bf16 v[98:101], v[138:141], v[212:215], v[98:101]
	v_mfma_f32_16x16x32_bf16 v[94:97], v[146:149], v[212:215], v[94:97]
	v_mfma_f32_16x16x32_bf16 v[82:85], v[138:141], v[220:223], v[82:85]
	v_mfma_f32_16x16x32_bf16 v[78:81], v[146:149], v[220:223], v[78:81]
	s_setprio 0
	s_setprio 1
	v_mfma_f32_16x16x32_bf16 v[122:125], v[150:153], v[166:169], v[122:125]
	v_mfma_f32_16x16x32_bf16 v[118:121], v[158:161], v[166:169], v[118:121]
	v_mfma_f32_16x16x32_bf16 v[106:109], v[150:153], v[200:203], v[106:109]
	v_mfma_f32_16x16x32_bf16 v[102:105], v[158:161], v[200:203], v[102:105]
	v_mfma_f32_16x16x32_bf16 v[90:93], v[150:153], v[208:211], v[90:93]
	v_mfma_f32_16x16x32_bf16 v[86:89], v[158:161], v[208:211], v[86:89]
	v_mfma_f32_16x16x32_bf16 v[74:77], v[150:153], v[216:219], v[74:77]
	v_mfma_f32_16x16x32_bf16 v[70:73], v[158:161], v[216:219], v[70:73]
	v_mfma_f32_16x16x32_bf16 v[122:125], v[154:157], v[170:173], v[122:125]
	v_mfma_f32_16x16x32_bf16 v[118:121], v[162:165], v[170:173], v[118:121]
	v_mfma_f32_16x16x32_bf16 v[106:109], v[154:157], v[204:207], v[106:109]
	v_mfma_f32_16x16x32_bf16 v[102:105], v[162:165], v[204:207], v[102:105]
	v_mfma_f32_16x16x32_bf16 v[90:93], v[154:157], v[212:215], v[90:93]
	v_mfma_f32_16x16x32_bf16 v[86:89], v[162:165], v[212:215], v[86:89]
	v_mfma_f32_16x16x32_bf16 v[74:77], v[154:157], v[220:223], v[74:77]
	v_mfma_f32_16x16x32_bf16 v[70:73], v[162:165], v[220:223], v[70:73]
	s_barrier
	s_setprio 0
	s_add_i32 s69, s58, s28
	s_add_u32 s98, s40, 0x80
	s_addc_u32 s99, s41, 0
	s_mov_b32 m0, s69
	ds_read_b128 v[166:169], v199 offset:16384
	ds_read_b128 v[170:173], v199 offset:17408
	ds_read_b128 v[200:203], v199 offset:18432
	ds_read_b128 v[204:207], v199 offset:19456
	ds_read_b128 v[208:211], v199 offset:20480
	ds_read_b128 v[212:215], v199 offset:21504
	ds_read_b128 v[216:219], v199 offset:22528
	ds_read_b128 v[220:223], v199 offset:23552
	global_load_lds_dwordx4 v176, s[40:41]
	s_add_i32 m0, s69, 0x2000
	s_add_u32 s70, s40, 0x80000
	s_addc_u32 s71, s41, 0
	s_add_i32 s69, s59, s28
	global_load_lds_dwordx4 v180, s[40:41]
	s_mov_b32 m0, s69
	s_add_u32 s100, s42, 0x80
	s_addc_u32 s101, s43, 0
	global_load_lds_dwordx4 v176, s[70:71]
	v_lshl_add_u64 v[4:5], s[70:71], 0, v[180:181]
	s_add_i32 m0, s69, 0x2000
	s_nop 0
	global_load_lds_dwordx4 v[4:5], off
	s_mov_b32 m0, s29
	s_nop 0
	global_load_lds_dwordx4 v174, s[42:43]
	s_mov_b32 m0, s44
	s_nop 0
	global_load_lds_dwordx4 v178, s[42:43]
	s_setprio 1
	s_waitcnt vmcnt(8) lgkmcnt(0)
	s_barrier
	v_mfma_f32_16x16x32_bf16 v[66:69], v[134:137], v[166:169], v[66:69]
	v_mfma_f32_16x16x32_bf16 v[62:65], v[142:145], v[166:169], v[62:65]
	v_mfma_f32_16x16x32_bf16 v[50:53], v[134:137], v[200:203], v[50:53]
	v_mfma_f32_16x16x32_bf16 v[46:49], v[142:145], v[200:203], v[46:49]
	v_mfma_f32_16x16x32_bf16 v[34:37], v[134:137], v[208:211], v[34:37]
	v_mfma_f32_16x16x32_bf16 v[30:33], v[142:145], v[208:211], v[30:33]
	v_mfma_f32_16x16x32_bf16 v[18:21], v[134:137], v[216:219], v[18:21]
	v_mfma_f32_16x16x32_bf16 v[14:17], v[142:145], v[216:219], v[14:17]
	v_mfma_f32_16x16x32_bf16 v[66:69], v[138:141], v[170:173], v[66:69]
	v_mfma_f32_16x16x32_bf16 v[62:65], v[146:149], v[170:173], v[62:65]
	v_mfma_f32_16x16x32_bf16 v[50:53], v[138:141], v[204:207], v[50:53]
	v_mfma_f32_16x16x32_bf16 v[46:49], v[146:149], v[204:207], v[46:49]
	v_mfma_f32_16x16x32_bf16 v[34:37], v[138:141], v[212:215], v[34:37]
	v_mfma_f32_16x16x32_bf16 v[30:33], v[146:149], v[212:215], v[30:33]
	v_mfma_f32_16x16x32_bf16 v[18:21], v[138:141], v[220:223], v[18:21]
	v_mfma_f32_16x16x32_bf16 v[14:17], v[146:149], v[220:223], v[14:17]
	s_setprio 0
	s_setprio 1
	v_mfma_f32_16x16x32_bf16 v[58:61], v[150:153], v[166:169], v[58:61]
	v_mfma_f32_16x16x32_bf16 v[54:57], v[158:161], v[166:169], v[54:57]
	v_mfma_f32_16x16x32_bf16 v[42:45], v[150:153], v[200:203], v[42:45]
	v_mfma_f32_16x16x32_bf16 v[38:41], v[158:161], v[200:203], v[38:41]
	v_mfma_f32_16x16x32_bf16 v[26:29], v[150:153], v[208:211], v[26:29]
	v_mfma_f32_16x16x32_bf16 v[22:25], v[158:161], v[208:211], v[22:25]
	v_mfma_f32_16x16x32_bf16 v[10:13], v[150:153], v[216:219], v[10:13]
	v_mfma_f32_16x16x32_bf16 v[4:7], v[158:161], v[216:219], v[6:9]
	v_mfma_f32_16x16x32_bf16 v[58:61], v[154:157], v[170:173], v[58:61]
	v_mfma_f32_16x16x32_bf16 v[54:57], v[162:165], v[170:173], v[54:57]
	v_mfma_f32_16x16x32_bf16 v[42:45], v[154:157], v[204:207], v[42:45]
	v_mfma_f32_16x16x32_bf16 v[38:41], v[162:165], v[204:207], v[38:41]
	v_mfma_f32_16x16x32_bf16 v[26:29], v[154:157], v[212:215], v[26:29]
	v_mfma_f32_16x16x32_bf16 v[22:25], v[162:165], v[212:215], v[22:25]
	v_mfma_f32_16x16x32_bf16 v[10:13], v[154:157], v[220:223], v[10:13]
	v_mfma_f32_16x16x32_bf16 v[4:7], v[162:165], v[220:223], v[4:7]
	s_barrier
	s_setprio 0
	s_add_i32 s69, 0, 0x18000
	s_add_i32 s70, 0, 0x1c000
	ds_read_b128 v[134:137], v236 offset:32768
	ds_read_b128 v[138:141], v236 offset:33792
	ds_read_b128 v[142:145], v236 offset:34816
	ds_read_b128 v[146:149], v236 offset:35840
	ds_read_b128 v[150:153], v236 offset:49152
	ds_read_b128 v[154:157], v236 offset:50176
	ds_read_b128 v[158:161], v236 offset:51200
	ds_read_b128 v[162:165], v236 offset:52224
	s_add_u32 s42, s42, 0x80000
	s_addc_u32 s43, s43, 0
	s_mov_b32 m0, s45
	ds_read_b128 v[166:169], v199 offset:32768
	ds_read_b128 v[170:173], v199 offset:33792
	ds_read_b128 v[200:203], v199 offset:34816
	ds_read_b128 v[204:207], v199 offset:35840
	ds_read_b128 v[208:211], v199 offset:36864
	ds_read_b128 v[212:215], v199 offset:37888
	ds_read_b128 v[216:219], v199 offset:38912
	ds_read_b128 v[220:223], v199 offset:39936
	global_load_lds_dwordx4 v174, s[42:43]
	s_mov_b32 m0, s46
	s_nop 0
	global_load_lds_dwordx4 v178, s[42:43]
	s_setprio 1
	s_waitcnt vmcnt(8) lgkmcnt(0)
	s_barrier
	v_mfma_f32_16x16x32_bf16 v[130:133], v[134:137], v[166:169], v[130:133]
	v_mfma_f32_16x16x32_bf16 v[126:129], v[142:145], v[166:169], v[126:129]
	v_mfma_f32_16x16x32_bf16 v[114:117], v[134:137], v[200:203], v[114:117]
	v_mfma_f32_16x16x32_bf16 v[110:113], v[142:145], v[200:203], v[110:113]
	v_mfma_f32_16x16x32_bf16 v[98:101], v[134:137], v[208:211], v[98:101]
	v_mfma_f32_16x16x32_bf16 v[94:97], v[142:145], v[208:211], v[94:97]
	v_mfma_f32_16x16x32_bf16 v[82:85], v[134:137], v[216:219], v[82:85]
	v_mfma_f32_16x16x32_bf16 v[78:81], v[142:145], v[216:219], v[78:81]
	v_mfma_f32_16x16x32_bf16 v[130:133], v[138:141], v[170:173], v[130:133]
	v_mfma_f32_16x16x32_bf16 v[126:129], v[146:149], v[170:173], v[126:129]
	v_mfma_f32_16x16x32_bf16 v[114:117], v[138:141], v[204:207], v[114:117]
	v_mfma_f32_16x16x32_bf16 v[110:113], v[146:149], v[204:207], v[110:113]
	v_mfma_f32_16x16x32_bf16 v[98:101], v[138:141], v[212:215], v[98:101]
	v_mfma_f32_16x16x32_bf16 v[94:97], v[146:149], v[212:215], v[94:97]
	v_mfma_f32_16x16x32_bf16 v[82:85], v[138:141], v[220:223], v[82:85]
	v_mfma_f32_16x16x32_bf16 v[78:81], v[146:149], v[220:223], v[78:81]
	s_setprio 0
	s_setprio 1
	v_mfma_f32_16x16x32_bf16 v[122:125], v[150:153], v[166:169], v[122:125]
	v_mfma_f32_16x16x32_bf16 v[118:121], v[158:161], v[166:169], v[118:121]
	v_mfma_f32_16x16x32_bf16 v[106:109], v[150:153], v[200:203], v[106:109]
	v_mfma_f32_16x16x32_bf16 v[102:105], v[158:161], v[200:203], v[102:105]
	v_mfma_f32_16x16x32_bf16 v[90:93], v[150:153], v[208:211], v[90:93]
	v_mfma_f32_16x16x32_bf16 v[86:89], v[158:161], v[208:211], v[86:89]
	v_mfma_f32_16x16x32_bf16 v[74:77], v[150:153], v[216:219], v[74:77]
	v_mfma_f32_16x16x32_bf16 v[70:73], v[158:161], v[216:219], v[70:73]
	v_mfma_f32_16x16x32_bf16 v[122:125], v[154:157], v[170:173], v[122:125]
	v_mfma_f32_16x16x32_bf16 v[118:121], v[162:165], v[170:173], v[118:121]
	v_mfma_f32_16x16x32_bf16 v[106:109], v[154:157], v[204:207], v[106:109]
	v_mfma_f32_16x16x32_bf16 v[102:105], v[162:165], v[204:207], v[102:105]
	v_mfma_f32_16x16x32_bf16 v[90:93], v[154:157], v[212:215], v[90:93]
	v_mfma_f32_16x16x32_bf16 v[86:89], v[162:165], v[212:215], v[86:89]
	v_mfma_f32_16x16x32_bf16 v[74:77], v[154:157], v[220:223], v[74:77]
	v_mfma_f32_16x16x32_bf16 v[70:73], v[162:165], v[220:223], v[70:73]
	s_barrier
	s_setprio 0
	s_add_i32 s42, s69, s28
	s_mov_b32 m0, s42
	ds_read_b128 v[166:169], v199 offset:49152
	ds_read_b128 v[170:173], v199 offset:50176
	ds_read_b128 v[200:203], v199 offset:51200
	ds_read_b128 v[204:207], v199 offset:52224
	ds_read_b128 v[208:211], v199 offset:53248
	ds_read_b128 v[212:215], v199 offset:54272
	ds_read_b128 v[216:219], v199 offset:55296
	ds_read_b128 v[220:223], v199 offset:56320
	global_load_lds_dwordx4 v176, s[98:99]
	s_add_i32 m0, s42, 0x2000
	s_add_u32 s40, s40, 0x80080
	s_addc_u32 s41, s41, 0
	s_add_i32 s42, s70, s28
	global_load_lds_dwordx4 v180, s[98:99]
	s_mov_b32 m0, s42
	s_nop 0
	global_load_lds_dwordx4 v176, s[40:41]
	s_add_i32 m0, s42, 0x2000
	s_nop 0
	global_load_lds_dwordx4 v180, s[40:41]
	s_mov_b32 m0, s53
	s_nop 0
	global_load_lds_dwordx4 v174, s[100:101]
	s_mov_b32 m0, s54
	s_nop 0
	global_load_lds_dwordx4 v178, s[100:101]
	s_setprio 1
	s_waitcnt vmcnt(8) lgkmcnt(0)
	s_barrier
	v_mfma_f32_16x16x32_bf16 v[66:69], v[134:137], v[166:169], v[66:69]
	v_mfma_f32_16x16x32_bf16 v[62:65], v[142:145], v[166:169], v[62:65]
	v_mfma_f32_16x16x32_bf16 v[50:53], v[134:137], v[200:203], v[50:53]
	v_mfma_f32_16x16x32_bf16 v[46:49], v[142:145], v[200:203], v[46:49]
	v_mfma_f32_16x16x32_bf16 v[34:37], v[134:137], v[208:211], v[34:37]
	v_mfma_f32_16x16x32_bf16 v[30:33], v[142:145], v[208:211], v[30:33]
	v_mfma_f32_16x16x32_bf16 v[18:21], v[134:137], v[216:219], v[18:21]
	v_mfma_f32_16x16x32_bf16 v[14:17], v[142:145], v[216:219], v[14:17]
	v_mfma_f32_16x16x32_bf16 v[66:69], v[138:141], v[170:173], v[66:69]
	v_mfma_f32_16x16x32_bf16 v[62:65], v[146:149], v[170:173], v[62:65]
	v_mfma_f32_16x16x32_bf16 v[50:53], v[138:141], v[204:207], v[50:53]
	v_mfma_f32_16x16x32_bf16 v[46:49], v[146:149], v[204:207], v[46:49]
	v_mfma_f32_16x16x32_bf16 v[34:37], v[138:141], v[212:215], v[34:37]
	v_mfma_f32_16x16x32_bf16 v[30:33], v[146:149], v[212:215], v[30:33]
	v_mfma_f32_16x16x32_bf16 v[18:21], v[138:141], v[220:223], v[18:21]
	v_mfma_f32_16x16x32_bf16 v[14:17], v[146:149], v[220:223], v[14:17]
	s_setprio 0
	s_setprio 1
	v_mfma_f32_16x16x32_bf16 v[58:61], v[150:153], v[166:169], v[58:61]
	v_mfma_f32_16x16x32_bf16 v[54:57], v[158:161], v[166:169], v[54:57]
	v_mfma_f32_16x16x32_bf16 v[42:45], v[150:153], v[200:203], v[42:45]
	v_mfma_f32_16x16x32_bf16 v[38:41], v[158:161], v[200:203], v[38:41]
	v_mfma_f32_16x16x32_bf16 v[26:29], v[150:153], v[208:211], v[26:29]
	v_mfma_f32_16x16x32_bf16 v[22:25], v[158:161], v[208:211], v[22:25]
	v_mfma_f32_16x16x32_bf16 v[8:11], v[150:153], v[216:219], v[10:13]
	v_mfma_f32_16x16x32_bf16 v[4:7], v[158:161], v[216:219], v[4:7]
	v_mfma_f32_16x16x32_bf16 v[58:61], v[154:157], v[170:173], v[58:61]
	v_mfma_f32_16x16x32_bf16 v[54:57], v[162:165], v[170:173], v[54:57]
	v_mfma_f32_16x16x32_bf16 v[42:45], v[154:157], v[204:207], v[42:45]
	v_mfma_f32_16x16x32_bf16 v[38:41], v[162:165], v[204:207], v[38:41]
	v_mfma_f32_16x16x32_bf16 v[26:29], v[154:157], v[212:215], v[26:29]
	v_mfma_f32_16x16x32_bf16 v[22:25], v[162:165], v[212:215], v[22:25]
	v_mfma_f32_16x16x32_bf16 v[10:13], v[154:157], v[220:223], v[8:11]
	v_mfma_f32_16x16x32_bf16 v[6:9], v[162:165], v[220:223], v[4:7]
	s_barrier
	s_setprio 0
	s_add_i32 s40, s68, 2
	s_add_u32 s38, s38, 0x100
	s_addc_u32 s39, s39, 0
	s_cmp_gt_u32 s68, 29
	s_cbranch_scc1 .LBB0_1330
	s_mov_b32 s68, s40
	s_and_b32 s40, s68, 14
	s_cmp_eq_u32 s40, 8
	s_mov_b64 s[40:41], -1
	s_cbranch_scc0 .LBB0_1325
	s_branch .LBB0_1326

.LBB0_1407:
	s_ashr_i32 s39, s38, 31
	s_lshl_b64 s[40:41], s[38:39], 20
	s_add_u32 s40, s22, s40
	s_addc_u32 s41, s23, s41
	s_and_b64 s[42:43], s[10:11], exec
	s_cselect_b32 s39, s41, s47
	s_cselect_b32 s66, s40, s46
	s_ashr_i32 s37, s36, 31
	s_lshl_b64 s[42:43], s[36:37], 20
	s_add_u32 s42, s28, s42
	s_addc_u32 s43, s29, s43
	s_and_b64 s[52:53], s[10:11], exec
	s_cselect_b32 s37, s43, s49
	s_cselect_b32 s67, s42, s48
	s_add_u32 s46, s46, 0x80080
	s_addc_u32 s47, s47, 0
	s_add_u32 s68, s48, 0x100
	s_addc_u32 s69, s49, 0
	s_mov_b32 s70, -2
	ds_read_b128 v[130:133], v183
	ds_read_b128 v[134:137], v183 offset:1024
	ds_read_b128 v[138:141], v183 offset:2048
	ds_read_b128 v[142:145], v183 offset:3072
	ds_read_b128 v[162:165], v184
	ds_read_b128 v[166:169], v184 offset:1024
	ds_read_b128 v[170:173], v184 offset:2048
	ds_read_b128 v[174:177], v184 offset:3072
	s_add_u32 s48, s46, 0xfff80080
	s_addc_u32 s49, s47, -1
	s_cmp_eq_u32 s70, 28
	s_cselect_b32 s53, s39, s49
	s_cselect_b32 s52, s66, s48
	s_cselect_b32 s49, s37, s69
	s_cselect_b32 s48, s67, s68
	s_add_i32 m0, s45, 0xc000
	ds_read_b128 v[188:191], v185
	ds_read_b128 v[192:195], v185 offset:1024
	ds_read_b128 v[196:199], v185 offset:2048
	ds_read_b128 v[200:203], v185 offset:3072
	ds_read_b128 v[204:207], v185 offset:4096
	ds_read_b128 v[208:211], v185 offset:5120
	ds_read_b128 v[212:215], v185 offset:6144
	ds_read_b128 v[216:219], v185 offset:7168
	global_load_lds_dwordx4 v154, s[46:47]
	s_add_i32 m0, s45, 0xe000
	s_nop 0
	global_load_lds_dwordx4 v156, s[46:47]
	s_setprio 1
	s_waitcnt vmcnt(8) lgkmcnt(0)
	s_barrier
	v_mfma_f32_16x16x32_bf16 v[126:129], v[130:133], v[188:191], 0
	v_mfma_f32_16x16x32_bf16 v[122:125], v[138:141], v[188:191], 0
	v_mfma_f32_16x16x32_bf16 v[110:113], v[130:133], v[196:199], 0
	v_mfma_f32_16x16x32_bf16 v[106:109], v[138:141], v[196:199], 0
	v_mfma_f32_16x16x32_bf16 v[94:97], v[130:133], v[204:207], 0
	v_mfma_f32_16x16x32_bf16 v[90:93], v[138:141], v[204:207], 0
	v_mfma_f32_16x16x32_bf16 v[78:81], v[130:133], v[212:215], 0
	v_mfma_f32_16x16x32_bf16 v[74:77], v[138:141], v[212:215], 0
	v_mfma_f32_16x16x32_bf16 v[126:129], v[134:137], v[192:195], v[126:129]
	v_mfma_f32_16x16x32_bf16 v[122:125], v[142:145], v[192:195], v[122:125]
	v_mfma_f32_16x16x32_bf16 v[110:113], v[134:137], v[200:203], v[110:113]
	v_mfma_f32_16x16x32_bf16 v[106:109], v[142:145], v[200:203], v[106:109]
	v_mfma_f32_16x16x32_bf16 v[94:97], v[134:137], v[208:211], v[94:97]
	v_mfma_f32_16x16x32_bf16 v[90:93], v[142:145], v[208:211], v[90:93]
	v_mfma_f32_16x16x32_bf16 v[78:81], v[134:137], v[216:219], v[78:81]
	v_mfma_f32_16x16x32_bf16 v[74:77], v[142:145], v[216:219], v[74:77]
	s_setprio 0
	s_setprio 1
	v_mfma_f32_16x16x32_bf16 v[118:121], v[162:165], v[188:191], 0
	v_mfma_f32_16x16x32_bf16 v[114:117], v[170:173], v[188:191], 0
	v_mfma_f32_16x16x32_bf16 v[102:105], v[162:165], v[196:199], 0
	v_mfma_f32_16x16x32_bf16 v[98:101], v[170:173], v[196:199], 0
	v_mfma_f32_16x16x32_bf16 v[86:89], v[162:165], v[204:207], 0
	v_mfma_f32_16x16x32_bf16 v[82:85], v[170:173], v[204:207], 0
	v_mfma_f32_16x16x32_bf16 v[70:73], v[162:165], v[212:215], 0
	v_mfma_f32_16x16x32_bf16 v[66:69], v[170:173], v[212:215], 0
	v_mfma_f32_16x16x32_bf16 v[118:121], v[166:169], v[192:195], v[118:121]
	v_mfma_f32_16x16x32_bf16 v[114:117], v[174:177], v[192:195], v[114:117]
	v_mfma_f32_16x16x32_bf16 v[102:105], v[166:169], v[200:203], v[102:105]
	v_mfma_f32_16x16x32_bf16 v[98:101], v[174:177], v[200:203], v[98:101]
	v_mfma_f32_16x16x32_bf16 v[86:89], v[166:169], v[208:211], v[86:89]
	v_mfma_f32_16x16x32_bf16 v[82:85], v[174:177], v[208:211], v[82:85]
	v_mfma_f32_16x16x32_bf16 v[70:73], v[166:169], v[216:219], v[70:73]
	v_mfma_f32_16x16x32_bf16 v[66:69], v[174:177], v[216:219], v[66:69]
	s_barrier
	s_setprio 0
	s_add_i32 s71, s63, s54
	s_add_u32 s98, s48, 0x80
	s_addc_u32 s99, s49, 0
	s_mov_b32 m0, s71
	ds_read_b128 v[188:191], v185 offset:16384
	ds_read_b128 v[192:195], v185 offset:17408
	ds_read_b128 v[196:199], v185 offset:18432
	ds_read_b128 v[200:203], v185 offset:19456
	ds_read_b128 v[204:207], v185 offset:20480
	ds_read_b128 v[208:211], v185 offset:21504
	ds_read_b128 v[212:215], v185 offset:22528
	ds_read_b128 v[216:219], v185 offset:23552
	global_load_lds_dwordx4 v148, s[48:49]
	s_add_i32 m0, s71, 0x2000
	s_add_u32 s72, s48, 0x80000
	s_addc_u32 s73, s49, 0
	s_add_i32 s71, s64, s54
	global_load_lds_dwordx4 v152, s[48:49]
	s_mov_b32 m0, s71
	s_nop 0
	global_load_lds_dwordx4 v148, s[72:73]
	s_add_i32 m0, s71, 0x2000
	s_nop 0
	global_load_lds_dwordx4 v152, s[72:73]
	s_add_u32 s100, s52, 0x80
	s_addc_u32 s101, s53, 0
	s_mov_b32 m0, s45
	s_nop 0
	global_load_lds_dwordx4 v146, s[52:53]
	s_mov_b32 m0, s55
	s_nop 0
	global_load_lds_dwordx4 v150, s[52:53]
	s_setprio 1
	s_waitcnt vmcnt(8) lgkmcnt(0)
	s_barrier
	v_mfma_f32_16x16x32_bf16 v[62:65], v[130:133], v[188:191], 0
	v_mfma_f32_16x16x32_bf16 v[58:61], v[138:141], v[188:191], 0
	v_mfma_f32_16x16x32_bf16 v[46:49], v[130:133], v[196:199], 0
	v_mfma_f32_16x16x32_bf16 v[42:45], v[138:141], v[196:199], 0
	v_mfma_f32_16x16x32_bf16 v[30:33], v[130:133], v[204:207], 0
	v_mfma_f32_16x16x32_bf16 v[26:29], v[138:141], v[204:207], 0
	v_mfma_f32_16x16x32_bf16 v[14:17], v[130:133], v[212:215], 0
	v_mfma_f32_16x16x32_bf16 v[10:13], v[138:141], v[212:215], 0
	v_mfma_f32_16x16x32_bf16 v[62:65], v[134:137], v[192:195], v[62:65]
	v_mfma_f32_16x16x32_bf16 v[58:61], v[142:145], v[192:195], v[58:61]
	v_mfma_f32_16x16x32_bf16 v[46:49], v[134:137], v[200:203], v[46:49]
	v_mfma_f32_16x16x32_bf16 v[42:45], v[142:145], v[200:203], v[42:45]
	v_mfma_f32_16x16x32_bf16 v[30:33], v[134:137], v[208:211], v[30:33]
	v_mfma_f32_16x16x32_bf16 v[26:29], v[142:145], v[208:211], v[26:29]
	v_mfma_f32_16x16x32_bf16 v[14:17], v[134:137], v[216:219], v[14:17]
	v_mfma_f32_16x16x32_bf16 v[10:13], v[142:145], v[216:219], v[10:13]
	s_setprio 0
	s_setprio 1
	v_mfma_f32_16x16x32_bf16 v[54:57], v[162:165], v[188:191], 0
	v_mfma_f32_16x16x32_bf16 v[50:53], v[170:173], v[188:191], 0
	v_mfma_f32_16x16x32_bf16 v[38:41], v[162:165], v[196:199], 0
	v_mfma_f32_16x16x32_bf16 v[34:37], v[170:173], v[196:199], 0
	v_mfma_f32_16x16x32_bf16 v[22:25], v[162:165], v[204:207], 0
	v_mfma_f32_16x16x32_bf16 v[18:21], v[170:173], v[204:207], 0
	v_mfma_f32_16x16x32_bf16 v[6:9], v[162:165], v[212:215], 0
	v_mfma_f32_16x16x32_bf16 v[2:5], v[170:173], v[212:215], 0
	v_mfma_f32_16x16x32_bf16 v[54:57], v[166:169], v[192:195], v[54:57]
	v_mfma_f32_16x16x32_bf16 v[50:53], v[174:177], v[192:195], v[50:53]
	v_mfma_f32_16x16x32_bf16 v[38:41], v[166:169], v[200:203], v[38:41]
	v_mfma_f32_16x16x32_bf16 v[34:37], v[174:177], v[200:203], v[34:37]
	v_mfma_f32_16x16x32_bf16 v[22:25], v[166:169], v[208:211], v[22:25]
	v_mfma_f32_16x16x32_bf16 v[18:21], v[174:177], v[208:211], v[18:21]
	v_mfma_f32_16x16x32_bf16 v[6:9], v[166:169], v[216:219], v[6:9]
	v_mfma_f32_16x16x32_bf16 v[2:5], v[174:177], v[216:219], v[2:5]
	s_barrier
	s_setprio 0
	s_add_i32 s71, 0, 0x18000
	s_add_i32 s72, 0, 0x1c000
	ds_read_b128 v[130:133], v183 offset:32768
	ds_read_b128 v[134:137], v183 offset:33792
	ds_read_b128 v[138:141], v183 offset:34816
	ds_read_b128 v[142:145], v183 offset:35840
	ds_read_b128 v[162:165], v184 offset:32768
	ds_read_b128 v[166:169], v184 offset:33792
	ds_read_b128 v[170:173], v184 offset:34816
	ds_read_b128 v[174:177], v184 offset:35840
	s_add_u32 s52, s52, 0x80000
	s_addc_u32 s53, s53, 0
	s_mov_b32 m0, s56
	ds_read_b128 v[188:191], v185 offset:32768
	ds_read_b128 v[192:195], v185 offset:33792
	ds_read_b128 v[196:199], v185 offset:34816
	ds_read_b128 v[200:203], v185 offset:35840
	ds_read_b128 v[204:207], v185 offset:36864
	ds_read_b128 v[208:211], v185 offset:37888
	ds_read_b128 v[212:215], v185 offset:38912
	ds_read_b128 v[216:219], v185 offset:39936
	global_load_lds_dwordx4 v146, s[52:53]
	s_mov_b32 m0, s57
	s_nop 0
	global_load_lds_dwordx4 v150, s[52:53]
	s_setprio 1
	s_waitcnt vmcnt(8) lgkmcnt(0)
	s_barrier
	v_mfma_f32_16x16x32_bf16 v[126:129], v[130:133], v[188:191], v[126:129]
	v_mfma_f32_16x16x32_bf16 v[122:125], v[138:141], v[188:191], v[122:125]
	v_mfma_f32_16x16x32_bf16 v[110:113], v[130:133], v[196:199], v[110:113]
	v_mfma_f32_16x16x32_bf16 v[106:109], v[138:141], v[196:199], v[106:109]
	v_mfma_f32_16x16x32_bf16 v[94:97], v[130:133], v[204:207], v[94:97]
	v_mfma_f32_16x16x32_bf16 v[90:93], v[138:141], v[204:207], v[90:93]
	v_mfma_f32_16x16x32_bf16 v[78:81], v[130:133], v[212:215], v[78:81]
	v_mfma_f32_16x16x32_bf16 v[74:77], v[138:141], v[212:215], v[74:77]
	v_mfma_f32_16x16x32_bf16 v[126:129], v[134:137], v[192:195], v[126:129]
	v_mfma_f32_16x16x32_bf16 v[122:125], v[142:145], v[192:195], v[122:125]
	v_mfma_f32_16x16x32_bf16 v[110:113], v[134:137], v[200:203], v[110:113]
	v_mfma_f32_16x16x32_bf16 v[106:109], v[142:145], v[200:203], v[106:109]
	v_mfma_f32_16x16x32_bf16 v[94:97], v[134:137], v[208:211], v[94:97]
	v_mfma_f32_16x16x32_bf16 v[90:93], v[142:145], v[208:211], v[90:93]
	v_mfma_f32_16x16x32_bf16 v[78:81], v[134:137], v[216:219], v[78:81]
	v_mfma_f32_16x16x32_bf16 v[74:77], v[142:145], v[216:219], v[74:77]
	s_setprio 0
	s_setprio 1
	v_mfma_f32_16x16x32_bf16 v[118:121], v[162:165], v[188:191], v[118:121]
	v_mfma_f32_16x16x32_bf16 v[114:117], v[170:173], v[188:191], v[114:117]
	v_mfma_f32_16x16x32_bf16 v[102:105], v[162:165], v[196:199], v[102:105]
	v_mfma_f32_16x16x32_bf16 v[98:101], v[170:173], v[196:199], v[98:101]
	v_mfma_f32_16x16x32_bf16 v[86:89], v[162:165], v[204:207], v[86:89]
	v_mfma_f32_16x16x32_bf16 v[82:85], v[170:173], v[204:207], v[82:85]
	v_mfma_f32_16x16x32_bf16 v[70:73], v[162:165], v[212:215], v[70:73]
	v_mfma_f32_16x16x32_bf16 v[66:69], v[170:173], v[212:215], v[66:69]
	v_mfma_f32_16x16x32_bf16 v[118:121], v[166:169], v[192:195], v[118:121]
	v_mfma_f32_16x16x32_bf16 v[114:117], v[174:177], v[192:195], v[114:117]
	v_mfma_f32_16x16x32_bf16 v[102:105], v[166:169], v[200:203], v[102:105]
	v_mfma_f32_16x16x32_bf16 v[98:101], v[174:177], v[200:203], v[98:101]
	v_mfma_f32_16x16x32_bf16 v[86:89], v[166:169], v[208:211], v[86:89]
	v_mfma_f32_16x16x32_bf16 v[82:85], v[174:177], v[208:211], v[82:85]
	v_mfma_f32_16x16x32_bf16 v[70:73], v[166:169], v[216:219], v[70:73]
	v_mfma_f32_16x16x32_bf16 v[66:69], v[174:177], v[216:219], v[66:69]
	s_barrier
	s_setprio 0
	s_add_i32 s52, s71, s54
	s_mov_b32 m0, s52
	ds_read_b128 v[188:191], v185 offset:49152
	ds_read_b128 v[192:195], v185 offset:50176
	ds_read_b128 v[196:199], v185 offset:51200
	ds_read_b128 v[200:203], v185 offset:52224
	ds_read_b128 v[204:207], v185 offset:53248
	ds_read_b128 v[208:211], v185 offset:54272
	ds_read_b128 v[212:215], v185 offset:55296
	ds_read_b128 v[216:219], v185 offset:56320
	global_load_lds_dwordx4 v148, s[98:99]
	s_add_i32 m0, s52, 0x2000
	s_add_u32 s48, s48, 0x80080
	s_addc_u32 s49, s49, 0
	s_add_i32 s52, s72, s54
	global_load_lds_dwordx4 v152, s[98:99]
	s_mov_b32 m0, s52
	s_nop 0
	global_load_lds_dwordx4 v148, s[48:49]
	s_add_i32 m0, s52, 0x2000
	s_nop 0
	global_load_lds_dwordx4 v152, s[48:49]
	s_mov_b32 m0, s60
	s_nop 0
	global_load_lds_dwordx4 v146, s[100:101]
	s_mov_b32 m0, s61
	s_nop 0
	global_load_lds_dwordx4 v150, s[100:101]
	s_setprio 1
	s_waitcnt vmcnt(8) lgkmcnt(0)
	s_barrier
	v_mfma_f32_16x16x32_bf16 v[62:65], v[130:133], v[188:191], v[62:65]
	v_mfma_f32_16x16x32_bf16 v[58:61], v[138:141], v[188:191], v[58:61]
	v_mfma_f32_16x16x32_bf16 v[46:49], v[130:133], v[196:199], v[46:49]
	v_mfma_f32_16x16x32_bf16 v[42:45], v[138:141], v[196:199], v[42:45]
	v_mfma_f32_16x16x32_bf16 v[30:33], v[130:133], v[204:207], v[30:33]
	v_mfma_f32_16x16x32_bf16 v[26:29], v[138:141], v[204:207], v[26:29]
	v_mfma_f32_16x16x32_bf16 v[14:17], v[130:133], v[212:215], v[14:17]
	v_mfma_f32_16x16x32_bf16 v[10:13], v[138:141], v[212:215], v[10:13]
	v_mfma_f32_16x16x32_bf16 v[62:65], v[134:137], v[192:195], v[62:65]
	v_mfma_f32_16x16x32_bf16 v[58:61], v[142:145], v[192:195], v[58:61]
	v_mfma_f32_16x16x32_bf16 v[46:49], v[134:137], v[200:203], v[46:49]
	v_mfma_f32_16x16x32_bf16 v[42:45], v[142:145], v[200:203], v[42:45]
	v_mfma_f32_16x16x32_bf16 v[30:33], v[134:137], v[208:211], v[30:33]
	v_mfma_f32_16x16x32_bf16 v[26:29], v[142:145], v[208:211], v[26:29]
	v_mfma_f32_16x16x32_bf16 v[14:17], v[134:137], v[216:219], v[14:17]
	v_mfma_f32_16x16x32_bf16 v[10:13], v[142:145], v[216:219], v[10:13]
	s_setprio 0
	s_setprio 1
	v_mfma_f32_16x16x32_bf16 v[54:57], v[162:165], v[188:191], v[54:57]
	v_mfma_f32_16x16x32_bf16 v[50:53], v[170:173], v[188:191], v[50:53]
	v_mfma_f32_16x16x32_bf16 v[38:41], v[162:165], v[196:199], v[38:41]
	v_mfma_f32_16x16x32_bf16 v[34:37], v[170:173], v[196:199], v[34:37]
	v_mfma_f32_16x16x32_bf16 v[22:25], v[162:165], v[204:207], v[22:25]
	v_mfma_f32_16x16x32_bf16 v[18:21], v[170:173], v[204:207], v[18:21]
	v_mfma_f32_16x16x32_bf16 v[6:9], v[162:165], v[212:215], v[6:9]
	v_mfma_f32_16x16x32_bf16 v[2:5], v[170:173], v[212:215], v[2:5]
	v_mfma_f32_16x16x32_bf16 v[54:57], v[166:169], v[192:195], v[54:57]
	v_mfma_f32_16x16x32_bf16 v[50:53], v[174:177], v[192:195], v[50:53]
	v_mfma_f32_16x16x32_bf16 v[38:41], v[166:169], v[200:203], v[38:41]
	v_mfma_f32_16x16x32_bf16 v[34:37], v[174:177], v[200:203], v[34:37]
	v_mfma_f32_16x16x32_bf16 v[22:25], v[166:169], v[208:211], v[22:25]
	v_mfma_f32_16x16x32_bf16 v[18:21], v[174:177], v[208:211], v[18:21]
	v_mfma_f32_16x16x32_bf16 v[6:9], v[166:169], v[216:219], v[6:9]
	v_mfma_f32_16x16x32_bf16 v[2:5], v[174:177], v[216:219], v[2:5]
	s_barrier
	s_setprio 0
	s_add_i32 s70, s70, 2
	s_add_u32 s46, s46, 0x100
	s_addc_u32 s47, s47, 0
	s_add_u32 s68, s68, 0x100
	s_addc_u32 s69, s69, 0
	s_cmp_gt_u32 s70, 29
.LBB0_1408:
	ds_read_b128 v[130:133], v183
	ds_read_b128 v[134:137], v183 offset:1024
	ds_read_b128 v[138:141], v183 offset:2048
	ds_read_b128 v[142:145], v183 offset:3072
	ds_read_b128 v[162:165], v184
	ds_read_b128 v[166:169], v184 offset:1024
	ds_read_b128 v[170:173], v184 offset:2048
	ds_read_b128 v[174:177], v184 offset:3072
	s_add_u32 s48, s46, 0xfff80080
	s_addc_u32 s49, s47, -1
	s_cmp_eq_u32 s70, 28
	s_cselect_b32 s53, s39, s49
	s_cselect_b32 s52, s66, s48
	s_cselect_b32 s49, s37, s69
	s_cselect_b32 s48, s67, s68
	s_add_i32 m0, s45, 0xc000
	ds_read_b128 v[188:191], v185
	ds_read_b128 v[192:195], v185 offset:1024
	ds_read_b128 v[196:199], v185 offset:2048
	ds_read_b128 v[200:203], v185 offset:3072
	ds_read_b128 v[204:207], v185 offset:4096
	ds_read_b128 v[208:211], v185 offset:5120
	ds_read_b128 v[212:215], v185 offset:6144
	ds_read_b128 v[216:219], v185 offset:7168
	global_load_lds_dwordx4 v154, s[46:47]
	s_add_i32 m0, s45, 0xe000
	s_nop 0
	global_load_lds_dwordx4 v156, s[46:47]
	s_setprio 1
	s_waitcnt vmcnt(8) lgkmcnt(0)
	s_barrier
	v_mfma_f32_16x16x32_bf16 v[126:129], v[130:133], v[188:191], v[126:129]
	v_mfma_f32_16x16x32_bf16 v[122:125], v[138:141], v[188:191], v[122:125]
	v_mfma_f32_16x16x32_bf16 v[110:113], v[130:133], v[196:199], v[110:113]
	v_mfma_f32_16x16x32_bf16 v[106:109], v[138:141], v[196:199], v[106:109]
	v_mfma_f32_16x16x32_bf16 v[94:97], v[130:133], v[204:207], v[94:97]
	v_mfma_f32_16x16x32_bf16 v[90:93], v[138:141], v[204:207], v[90:93]
	v_mfma_f32_16x16x32_bf16 v[78:81], v[130:133], v[212:215], v[78:81]
	v_mfma_f32_16x16x32_bf16 v[74:77], v[138:141], v[212:215], v[74:77]
	v_mfma_f32_16x16x32_bf16 v[126:129], v[134:137], v[192:195], v[126:129]
	v_mfma_f32_16x16x32_bf16 v[122:125], v[142:145], v[192:195], v[122:125]
	v_mfma_f32_16x16x32_bf16 v[110:113], v[134:137], v[200:203], v[110:113]
	v_mfma_f32_16x16x32_bf16 v[106:109], v[142:145], v[200:203], v[106:109]
	v_mfma_f32_16x16x32_bf16 v[94:97], v[134:137], v[208:211], v[94:97]
	v_mfma_f32_16x16x32_bf16 v[90:93], v[142:145], v[208:211], v[90:93]
	v_mfma_f32_16x16x32_bf16 v[78:81], v[134:137], v[216:219], v[78:81]
	v_mfma_f32_16x16x32_bf16 v[74:77], v[142:145], v[216:219], v[74:77]
	s_setprio 0
	s_setprio 1
	v_mfma_f32_16x16x32_bf16 v[118:121], v[162:165], v[188:191], v[118:121]
	v_mfma_f32_16x16x32_bf16 v[114:117], v[170:173], v[188:191], v[114:117]
	v_mfma_f32_16x16x32_bf16 v[102:105], v[162:165], v[196:199], v[102:105]
	v_mfma_f32_16x16x32_bf16 v[98:101], v[170:173], v[196:199], v[98:101]
	v_mfma_f32_16x16x32_bf16 v[86:89], v[162:165], v[204:207], v[86:89]
	v_mfma_f32_16x16x32_bf16 v[82:85], v[170:173], v[204:207], v[82:85]
	v_mfma_f32_16x16x32_bf16 v[70:73], v[162:165], v[212:215], v[70:73]
	v_mfma_f32_16x16x32_bf16 v[66:69], v[170:173], v[212:215], v[66:69]
	v_mfma_f32_16x16x32_bf16 v[118:121], v[166:169], v[192:195], v[118:121]
	v_mfma_f32_16x16x32_bf16 v[114:117], v[174:177], v[192:195], v[114:117]
	v_mfma_f32_16x16x32_bf16 v[102:105], v[166:169], v[200:203], v[102:105]
	v_mfma_f32_16x16x32_bf16 v[98:101], v[174:177], v[200:203], v[98:101]
	v_mfma_f32_16x16x32_bf16 v[86:89], v[166:169], v[208:211], v[86:89]
	v_mfma_f32_16x16x32_bf16 v[82:85], v[174:177], v[208:211], v[82:85]
	v_mfma_f32_16x16x32_bf16 v[70:73], v[166:169], v[216:219], v[70:73]
	v_mfma_f32_16x16x32_bf16 v[66:69], v[174:177], v[216:219], v[66:69]
	s_barrier
	s_setprio 0
	s_add_i32 s71, s63, s54
	s_add_u32 s98, s48, 0x80
	s_addc_u32 s99, s49, 0
	s_mov_b32 m0, s71
	ds_read_b128 v[188:191], v185 offset:16384
	ds_read_b128 v[192:195], v185 offset:17408
	ds_read_b128 v[196:199], v185 offset:18432
	ds_read_b128 v[200:203], v185 offset:19456
	ds_read_b128 v[204:207], v185 offset:20480
	ds_read_b128 v[208:211], v185 offset:21504
	ds_read_b128 v[212:215], v185 offset:22528
	ds_read_b128 v[216:219], v185 offset:23552
	global_load_lds_dwordx4 v148, s[48:49]
	s_add_i32 m0, s71, 0x2000
	s_add_u32 s72, s48, 0x80000
	s_addc_u32 s73, s49, 0
	s_add_i32 s71, s64, s54
	global_load_lds_dwordx4 v152, s[48:49]
	s_mov_b32 m0, s71
	s_nop 0
	global_load_lds_dwordx4 v148, s[72:73]
	s_add_i32 m0, s71, 0x2000
	s_nop 0
	global_load_lds_dwordx4 v152, s[72:73]
	s_add_u32 s100, s52, 0x80
	s_addc_u32 s101, s53, 0
	s_mov_b32 m0, s45
	s_nop 0
	global_load_lds_dwordx4 v146, s[52:53]
	s_mov_b32 m0, s55
	s_nop 0
	global_load_lds_dwordx4 v150, s[52:53]
	s_setprio 1
	s_waitcnt vmcnt(8) lgkmcnt(0)
	s_barrier
	v_mfma_f32_16x16x32_bf16 v[62:65], v[130:133], v[188:191], v[62:65]
	v_mfma_f32_16x16x32_bf16 v[58:61], v[138:141], v[188:191], v[58:61]
	v_mfma_f32_16x16x32_bf16 v[46:49], v[130:133], v[196:199], v[46:49]
	v_mfma_f32_16x16x32_bf16 v[42:45], v[138:141], v[196:199], v[42:45]
	v_mfma_f32_16x16x32_bf16 v[30:33], v[130:133], v[204:207], v[30:33]
	v_mfma_f32_16x16x32_bf16 v[26:29], v[138:141], v[204:207], v[26:29]
	v_mfma_f32_16x16x32_bf16 v[14:17], v[130:133], v[212:215], v[14:17]
	v_mfma_f32_16x16x32_bf16 v[10:13], v[138:141], v[212:215], v[10:13]
	v_mfma_f32_16x16x32_bf16 v[62:65], v[134:137], v[192:195], v[62:65]
	v_mfma_f32_16x16x32_bf16 v[58:61], v[142:145], v[192:195], v[58:61]
	v_mfma_f32_16x16x32_bf16 v[46:49], v[134:137], v[200:203], v[46:49]
	v_mfma_f32_16x16x32_bf16 v[42:45], v[142:145], v[200:203], v[42:45]
	v_mfma_f32_16x16x32_bf16 v[30:33], v[134:137], v[208:211], v[30:33]
	v_mfma_f32_16x16x32_bf16 v[26:29], v[142:145], v[208:211], v[26:29]
	v_mfma_f32_16x16x32_bf16 v[14:17], v[134:137], v[216:219], v[14:17]
	v_mfma_f32_16x16x32_bf16 v[10:13], v[142:145], v[216:219], v[10:13]
	s_setprio 0
	s_setprio 1
	v_mfma_f32_16x16x32_bf16 v[54:57], v[162:165], v[188:191], v[54:57]
	v_mfma_f32_16x16x32_bf16 v[50:53], v[170:173], v[188:191], v[50:53]
	v_mfma_f32_16x16x32_bf16 v[38:41], v[162:165], v[196:199], v[38:41]
	v_mfma_f32_16x16x32_bf16 v[34:37], v[170:173], v[196:199], v[34:37]
	v_mfma_f32_16x16x32_bf16 v[22:25], v[162:165], v[204:207], v[22:25]
	v_mfma_f32_16x16x32_bf16 v[18:21], v[170:173], v[204:207], v[18:21]
	v_mfma_f32_16x16x32_bf16 v[6:9], v[162:165], v[212:215], v[6:9]
	v_mfma_f32_16x16x32_bf16 v[2:5], v[170:173], v[212:215], v[2:5]
	v_mfma_f32_16x16x32_bf16 v[54:57], v[166:169], v[192:195], v[54:57]
	v_mfma_f32_16x16x32_bf16 v[50:53], v[174:177], v[192:195], v[50:53]
	v_mfma_f32_16x16x32_bf16 v[38:41], v[166:169], v[200:203], v[38:41]
	v_mfma_f32_16x16x32_bf16 v[34:37], v[174:177], v[200:203], v[34:37]
	v_mfma_f32_16x16x32_bf16 v[22:25], v[166:169], v[208:211], v[22:25]
	v_mfma_f32_16x16x32_bf16 v[18:21], v[174:177], v[208:211], v[18:21]
	v_mfma_f32_16x16x32_bf16 v[6:9], v[166:169], v[216:219], v[6:9]
	v_mfma_f32_16x16x32_bf16 v[2:5], v[174:177], v[216:219], v[2:5]
	s_barrier
	s_setprio 0
	s_add_i32 s71, 0, 0x18000
	s_add_i32 s72, 0, 0x1c000
	ds_read_b128 v[130:133], v183 offset:32768
	ds_read_b128 v[134:137], v183 offset:33792
	ds_read_b128 v[138:141], v183 offset:34816
	ds_read_b128 v[142:145], v183 offset:35840
	ds_read_b128 v[162:165], v184 offset:32768
	ds_read_b128 v[166:169], v184 offset:33792
	ds_read_b128 v[170:173], v184 offset:34816
	ds_read_b128 v[174:177], v184 offset:35840
	s_add_u32 s52, s52, 0x80000
	s_addc_u32 s53, s53, 0
	s_mov_b32 m0, s56
	ds_read_b128 v[188:191], v185 offset:32768
	ds_read_b128 v[192:195], v185 offset:33792
	ds_read_b128 v[196:199], v185 offset:34816
	ds_read_b128 v[200:203], v185 offset:35840
	ds_read_b128 v[204:207], v185 offset:36864
	ds_read_b128 v[208:211], v185 offset:37888
	ds_read_b128 v[212:215], v185 offset:38912
	ds_read_b128 v[216:219], v185 offset:39936
	global_load_lds_dwordx4 v146, s[52:53]
	s_mov_b32 m0, s57
	s_nop 0
	global_load_lds_dwordx4 v150, s[52:53]
	s_setprio 1
	s_waitcnt vmcnt(8) lgkmcnt(0)
	s_barrier
	v_mfma_f32_16x16x32_bf16 v[126:129], v[130:133], v[188:191], v[126:129]
	v_mfma_f32_16x16x32_bf16 v[122:125], v[138:141], v[188:191], v[122:125]
	v_mfma_f32_16x16x32_bf16 v[110:113], v[130:133], v[196:199], v[110:113]
	v_mfma_f32_16x16x32_bf16 v[106:109], v[138:141], v[196:199], v[106:109]
	v_mfma_f32_16x16x32_bf16 v[94:97], v[130:133], v[204:207], v[94:97]
	v_mfma_f32_16x16x32_bf16 v[90:93], v[138:141], v[204:207], v[90:93]
	v_mfma_f32_16x16x32_bf16 v[78:81], v[130:133], v[212:215], v[78:81]
	v_mfma_f32_16x16x32_bf16 v[74:77], v[138:141], v[212:215], v[74:77]
	v_mfma_f32_16x16x32_bf16 v[126:129], v[134:137], v[192:195], v[126:129]
	v_mfma_f32_16x16x32_bf16 v[122:125], v[142:145], v[192:195], v[122:125]
	v_mfma_f32_16x16x32_bf16 v[110:113], v[134:137], v[200:203], v[110:113]
	v_mfma_f32_16x16x32_bf16 v[106:109], v[142:145], v[200:203], v[106:109]
	v_mfma_f32_16x16x32_bf16 v[94:97], v[134:137], v[208:211], v[94:97]
	v_mfma_f32_16x16x32_bf16 v[90:93], v[142:145], v[208:211], v[90:93]
	v_mfma_f32_16x16x32_bf16 v[78:81], v[134:137], v[216:219], v[78:81]
	v_mfma_f32_16x16x32_bf16 v[74:77], v[142:145], v[216:219], v[74:77]
	s_setprio 0
	s_setprio 1
	v_mfma_f32_16x16x32_bf16 v[118:121], v[162:165], v[188:191], v[118:121]
	v_mfma_f32_16x16x32_bf16 v[114:117], v[170:173], v[188:191], v[114:117]
	v_mfma_f32_16x16x32_bf16 v[102:105], v[162:165], v[196:199], v[102:105]
	v_mfma_f32_16x16x32_bf16 v[98:101], v[170:173], v[196:199], v[98:101]
	v_mfma_f32_16x16x32_bf16 v[86:89], v[162:165], v[204:207], v[86:89]
	v_mfma_f32_16x16x32_bf16 v[82:85], v[170:173], v[204:207], v[82:85]
	v_mfma_f32_16x16x32_bf16 v[70:73], v[162:165], v[212:215], v[70:73]
	v_mfma_f32_16x16x32_bf16 v[66:69], v[170:173], v[212:215], v[66:69]
	v_mfma_f32_16x16x32_bf16 v[118:121], v[166:169], v[192:195], v[118:121]
	v_mfma_f32_16x16x32_bf16 v[114:117], v[174:177], v[192:195], v[114:117]
	v_mfma_f32_16x16x32_bf16 v[102:105], v[166:169], v[200:203], v[102:105]
	v_mfma_f32_16x16x32_bf16 v[98:101], v[174:177], v[200:203], v[98:101]
	v_mfma_f32_16x16x32_bf16 v[86:89], v[166:169], v[208:211], v[86:89]
	v_mfma_f32_16x16x32_bf16 v[82:85], v[174:177], v[208:211], v[82:85]
	v_mfma_f32_16x16x32_bf16 v[70:73], v[166:169], v[216:219], v[70:73]
	v_mfma_f32_16x16x32_bf16 v[66:69], v[174:177], v[216:219], v[66:69]
	s_barrier
	s_setprio 0
	s_add_i32 s52, s71, s54
	s_mov_b32 m0, s52
	ds_read_b128 v[188:191], v185 offset:49152
	ds_read_b128 v[192:195], v185 offset:50176
	ds_read_b128 v[196:199], v185 offset:51200
	ds_read_b128 v[200:203], v185 offset:52224
	ds_read_b128 v[204:207], v185 offset:53248
	ds_read_b128 v[208:211], v185 offset:54272
	ds_read_b128 v[212:215], v185 offset:55296
	ds_read_b128 v[216:219], v185 offset:56320
	global_load_lds_dwordx4 v148, s[98:99]
	s_add_i32 m0, s52, 0x2000
	s_add_u32 s48, s48, 0x80080
	s_addc_u32 s49, s49, 0
	s_add_i32 s52, s72, s54
	global_load_lds_dwordx4 v152, s[98:99]
	s_mov_b32 m0, s52
	s_nop 0
	global_load_lds_dwordx4 v148, s[48:49]
	s_add_i32 m0, s52, 0x2000
	s_nop 0
	global_load_lds_dwordx4 v152, s[48:49]
	s_mov_b32 m0, s60
	s_nop 0
	global_load_lds_dwordx4 v146, s[100:101]
	s_mov_b32 m0, s61
	s_nop 0
	global_load_lds_dwordx4 v150, s[100:101]
	s_add_i32 s70, s70, 2
	s_add_u32 s46, s46, 0x100
	s_addc_u32 s47, s47, 0
	s_add_u32 s68, s68, 0x100
	s_addc_u32 s69, s69, 0
	s_cmp_gt_u32 s70, 29
	s_setprio 1
	s_waitcnt vmcnt(8) lgkmcnt(0)
	s_barrier
	v_mfma_f32_16x16x32_bf16 v[62:65], v[130:133], v[188:191], v[62:65]
	v_mfma_f32_16x16x32_bf16 v[58:61], v[138:141], v[188:191], v[58:61]
	v_mfma_f32_16x16x32_bf16 v[46:49], v[130:133], v[196:199], v[46:49]
	v_mfma_f32_16x16x32_bf16 v[42:45], v[138:141], v[196:199], v[42:45]
	v_mfma_f32_16x16x32_bf16 v[30:33], v[130:133], v[204:207], v[30:33]
	v_mfma_f32_16x16x32_bf16 v[26:29], v[138:141], v[204:207], v[26:29]
	v_mfma_f32_16x16x32_bf16 v[14:17], v[130:133], v[212:215], v[14:17]
	v_mfma_f32_16x16x32_bf16 v[10:13], v[138:141], v[212:215], v[10:13]
	v_mfma_f32_16x16x32_bf16 v[62:65], v[134:137], v[192:195], v[62:65]
	v_mfma_f32_16x16x32_bf16 v[58:61], v[142:145], v[192:195], v[58:61]
	v_mfma_f32_16x16x32_bf16 v[46:49], v[134:137], v[200:203], v[46:49]
	v_mfma_f32_16x16x32_bf16 v[42:45], v[142:145], v[200:203], v[42:45]
	v_mfma_f32_16x16x32_bf16 v[30:33], v[134:137], v[208:211], v[30:33]
	v_mfma_f32_16x16x32_bf16 v[26:29], v[142:145], v[208:211], v[26:29]
	v_mfma_f32_16x16x32_bf16 v[14:17], v[134:137], v[216:219], v[14:17]
	v_mfma_f32_16x16x32_bf16 v[10:13], v[142:145], v[216:219], v[10:13]
	s_setprio 0
	s_setprio 1
	v_mfma_f32_16x16x32_bf16 v[54:57], v[162:165], v[188:191], v[54:57]
	v_mfma_f32_16x16x32_bf16 v[50:53], v[170:173], v[188:191], v[50:53]
	v_mfma_f32_16x16x32_bf16 v[38:41], v[162:165], v[196:199], v[38:41]
	v_mfma_f32_16x16x32_bf16 v[34:37], v[170:173], v[196:199], v[34:37]
	v_mfma_f32_16x16x32_bf16 v[22:25], v[162:165], v[204:207], v[22:25]
	v_mfma_f32_16x16x32_bf16 v[18:21], v[170:173], v[204:207], v[18:21]
	v_mfma_f32_16x16x32_bf16 v[6:9], v[162:165], v[212:215], v[6:9]
	v_mfma_f32_16x16x32_bf16 v[2:5], v[170:173], v[212:215], v[2:5]
	v_mfma_f32_16x16x32_bf16 v[54:57], v[166:169], v[192:195], v[54:57]
	v_mfma_f32_16x16x32_bf16 v[50:53], v[174:177], v[192:195], v[50:53]
	v_mfma_f32_16x16x32_bf16 v[38:41], v[166:169], v[200:203], v[38:41]
	v_mfma_f32_16x16x32_bf16 v[34:37], v[174:177], v[200:203], v[34:37]
	v_mfma_f32_16x16x32_bf16 v[22:25], v[166:169], v[208:211], v[22:25]
	v_mfma_f32_16x16x32_bf16 v[18:21], v[174:177], v[208:211], v[18:21]
	v_mfma_f32_16x16x32_bf16 v[6:9], v[166:169], v[216:219], v[6:9]
	v_mfma_f32_16x16x32_bf16 v[2:5], v[174:177], v[216:219], v[2:5]
	s_barrier
	s_setprio 0
	s_cbranch_scc0 .LBB0_1408
	s_and_b64 vcc, exec, s[34:35]
	s_cbranch_vccz .LBB0_1411
	s_barrier

.LBB0_1478:
	s_ashr_i32 s11, s10, 31
	s_lshl_b64 s[6:7], s[10:11], 20
	s_add_u32 s38, s19, s6
	s_addc_u32 s39, s22, s7
	s_and_b64 s[6:7], s[2:3], exec
	s_cselect_b32 s9, s39, s1
	s_cselect_b32 s11, s38, s0
	s_ashr_i32 s37, s36, 31
	s_lshl_b64 s[6:7], s[36:37], 20
	s_add_u32 s40, s23, s6
	s_addc_u32 s41, s28, s7
	s_and_b64 s[6:7], s[2:3], exec
	s_cselect_b32 s37, s41, s5
	s_cselect_b32 s60, s40, s4
	s_add_u32 s0, s0, 0x80080
	s_addc_u32 s1, s1, 0
	s_add_u32 s61, s4, 0x100
	s_addc_u32 s62, s5, 0
	s_mov_b32 s63, -2
	ds_read_b128 v[132:135], v174
	ds_read_b128 v[158:161], v174 offset:1024
	ds_read_b128 v[166:169], v174 offset:2048
	ds_read_b128 v[170:173], v174 offset:3072
	ds_read_b128 v[182:185], v175
	ds_read_b128 v[186:189], v175 offset:1024
	ds_read_b128 v[190:193], v175 offset:2048
	ds_read_b128 v[194:197], v175 offset:3072
	s_add_u32 s4, s0, 0xfff80080
	s_addc_u32 s5, s1, -1
	s_cmp_eq_u32 s63, 28
	s_cselect_b32 s7, s9, s5
	s_cselect_b32 s6, s11, s4
	s_cselect_b32 s5, s37, s62
	s_cselect_b32 s4, s60, s61
	s_add_i32 m0, s44, 0xc000
	ds_read_b128 v[198:201], v176
	ds_read_b128 v[202:205], v176 offset:1024
	ds_read_b128 v[206:209], v176 offset:2048
	ds_read_b128 v[210:213], v176 offset:3072
	ds_read_b128 v[214:217], v176 offset:4096
	ds_read_b128 v[218:221], v176 offset:5120
	ds_read_b128 v[222:225], v176 offset:6144
	ds_read_b128 v[226:229], v176 offset:7168
	global_load_lds_dwordx4 v146, s[0:1]
	s_add_i32 m0, s44, 0xe000
	s_nop 0
	global_load_lds_dwordx4 v148, s[0:1]
	s_setprio 1
	s_waitcnt vmcnt(8) lgkmcnt(0)
	s_barrier
	v_mfma_f32_16x16x32_bf16 v[128:131], v[132:135], v[198:201], 0
	v_mfma_f32_16x16x32_bf16 v[124:127], v[166:169], v[198:201], 0
	v_mfma_f32_16x16x32_bf16 v[112:115], v[132:135], v[206:209], 0
	v_mfma_f32_16x16x32_bf16 v[108:111], v[166:169], v[206:209], 0
	v_mfma_f32_16x16x32_bf16 v[96:99], v[132:135], v[214:217], 0
	v_mfma_f32_16x16x32_bf16 v[92:95], v[166:169], v[214:217], 0
	v_mfma_f32_16x16x32_bf16 v[80:83], v[132:135], v[222:225], 0
	v_mfma_f32_16x16x32_bf16 v[76:79], v[166:169], v[222:225], 0
	v_mfma_f32_16x16x32_bf16 v[128:131], v[158:161], v[202:205], v[128:131]
	v_mfma_f32_16x16x32_bf16 v[124:127], v[170:173], v[202:205], v[124:127]
	v_mfma_f32_16x16x32_bf16 v[112:115], v[158:161], v[210:213], v[112:115]
	v_mfma_f32_16x16x32_bf16 v[108:111], v[170:173], v[210:213], v[108:111]
	v_mfma_f32_16x16x32_bf16 v[96:99], v[158:161], v[218:221], v[96:99]
	v_mfma_f32_16x16x32_bf16 v[92:95], v[170:173], v[218:221], v[92:95]
	v_mfma_f32_16x16x32_bf16 v[80:83], v[158:161], v[226:229], v[80:83]
	v_mfma_f32_16x16x32_bf16 v[76:79], v[170:173], v[226:229], v[76:79]
	s_setprio 0
	s_setprio 1
	v_mfma_f32_16x16x32_bf16 v[120:123], v[182:185], v[198:201], 0
	v_mfma_f32_16x16x32_bf16 v[116:119], v[190:193], v[198:201], 0
	v_mfma_f32_16x16x32_bf16 v[104:107], v[182:185], v[206:209], 0
	v_mfma_f32_16x16x32_bf16 v[100:103], v[190:193], v[206:209], 0
	v_mfma_f32_16x16x32_bf16 v[88:91], v[182:185], v[214:217], 0
	v_mfma_f32_16x16x32_bf16 v[84:87], v[190:193], v[214:217], 0
	v_mfma_f32_16x16x32_bf16 v[72:75], v[182:185], v[222:225], 0
	v_mfma_f32_16x16x32_bf16 v[68:71], v[190:193], v[222:225], 0
	v_mfma_f32_16x16x32_bf16 v[120:123], v[186:189], v[202:205], v[120:123]
	v_mfma_f32_16x16x32_bf16 v[116:119], v[194:197], v[202:205], v[116:119]
	v_mfma_f32_16x16x32_bf16 v[104:107], v[186:189], v[210:213], v[104:107]
	v_mfma_f32_16x16x32_bf16 v[100:103], v[194:197], v[210:213], v[100:103]
	v_mfma_f32_16x16x32_bf16 v[88:91], v[186:189], v[218:221], v[88:91]
	v_mfma_f32_16x16x32_bf16 v[84:87], v[194:197], v[218:221], v[84:87]
	v_mfma_f32_16x16x32_bf16 v[72:75], v[186:189], v[226:229], v[72:75]
	v_mfma_f32_16x16x32_bf16 v[68:71], v[194:197], v[226:229], v[68:71]
	s_barrier
	s_setprio 0
	s_add_i32 s64, s54, s29
	s_add_u32 s98, s4, 0x80
	s_addc_u32 s99, s5, 0
	s_mov_b32 m0, s64
	ds_read_b128 v[198:201], v176 offset:16384
	ds_read_b128 v[202:205], v176 offset:17408
	ds_read_b128 v[206:209], v176 offset:18432
	ds_read_b128 v[210:213], v176 offset:19456
	ds_read_b128 v[214:217], v176 offset:20480
	ds_read_b128 v[218:221], v176 offset:21504
	ds_read_b128 v[222:225], v176 offset:22528
	ds_read_b128 v[226:229], v176 offset:23552
	global_load_lds_dwordx4 v142, s[4:5]
	s_add_i32 m0, s64, 0x2000
	s_add_u32 s64, s4, 0x80000
	s_addc_u32 s65, s5, 0
	s_add_i32 s66, s55, s29
	global_load_lds_dwordx4 v138, s[4:5]
	s_mov_b32 m0, s66
	s_nop 0
	global_load_lds_dwordx4 v142, s[64:65]
	s_add_i32 m0, s66, 0x2000
	s_nop 0
	global_load_lds_dwordx4 v138, s[64:65]
	s_add_u32 s100, s6, 0x80
	s_addc_u32 s101, s7, 0
	s_mov_b32 m0, s44
	s_nop 0
	global_load_lds_dwordx4 v144, s[6:7]
	s_mov_b32 m0, s45
	s_nop 0
	global_load_lds_dwordx4 v140, s[6:7]
	s_setprio 1
	s_waitcnt vmcnt(8) lgkmcnt(0)
	s_barrier
	v_mfma_f32_16x16x32_bf16 v[62:65], v[132:135], v[198:201], 0
	v_mfma_f32_16x16x32_bf16 v[58:61], v[166:169], v[198:201], 0
	v_mfma_f32_16x16x32_bf16 v[46:49], v[132:135], v[206:209], 0
	v_mfma_f32_16x16x32_bf16 v[42:45], v[166:169], v[206:209], 0
	v_mfma_f32_16x16x32_bf16 v[30:33], v[132:135], v[214:217], 0
	v_mfma_f32_16x16x32_bf16 v[26:29], v[166:169], v[214:217], 0
	v_mfma_f32_16x16x32_bf16 v[14:17], v[132:135], v[222:225], 0
	v_mfma_f32_16x16x32_bf16 v[10:13], v[166:169], v[222:225], 0
	v_mfma_f32_16x16x32_bf16 v[62:65], v[158:161], v[202:205], v[62:65]
	v_mfma_f32_16x16x32_bf16 v[58:61], v[170:173], v[202:205], v[58:61]
	v_mfma_f32_16x16x32_bf16 v[46:49], v[158:161], v[210:213], v[46:49]
	v_mfma_f32_16x16x32_bf16 v[42:45], v[170:173], v[210:213], v[42:45]
	v_mfma_f32_16x16x32_bf16 v[30:33], v[158:161], v[218:221], v[30:33]
	v_mfma_f32_16x16x32_bf16 v[26:29], v[170:173], v[218:221], v[26:29]
	v_mfma_f32_16x16x32_bf16 v[14:17], v[158:161], v[226:229], v[14:17]
	v_mfma_f32_16x16x32_bf16 v[10:13], v[170:173], v[226:229], v[10:13]
	s_setprio 0
	s_setprio 1
	v_mfma_f32_16x16x32_bf16 v[54:57], v[182:185], v[198:201], 0
	v_mfma_f32_16x16x32_bf16 v[50:53], v[190:193], v[198:201], 0
	v_mfma_f32_16x16x32_bf16 v[38:41], v[182:185], v[206:209], 0
	v_mfma_f32_16x16x32_bf16 v[34:37], v[190:193], v[206:209], 0
	v_mfma_f32_16x16x32_bf16 v[22:25], v[182:185], v[214:217], 0
	v_mfma_f32_16x16x32_bf16 v[18:21], v[190:193], v[214:217], 0
	v_mfma_f32_16x16x32_bf16 v[6:9], v[182:185], v[222:225], 0
	v_mfma_f32_16x16x32_bf16 v[2:5], v[190:193], v[222:225], 0
	v_mfma_f32_16x16x32_bf16 v[54:57], v[186:189], v[202:205], v[54:57]
	v_mfma_f32_16x16x32_bf16 v[50:53], v[194:197], v[202:205], v[50:53]
	v_mfma_f32_16x16x32_bf16 v[38:41], v[186:189], v[210:213], v[38:41]
	v_mfma_f32_16x16x32_bf16 v[34:37], v[194:197], v[210:213], v[34:37]
	v_mfma_f32_16x16x32_bf16 v[22:25], v[186:189], v[218:221], v[22:25]
	v_mfma_f32_16x16x32_bf16 v[18:21], v[194:197], v[218:221], v[18:21]
	v_mfma_f32_16x16x32_bf16 v[6:9], v[186:189], v[226:229], v[6:9]
	v_mfma_f32_16x16x32_bf16 v[2:5], v[194:197], v[226:229], v[2:5]
	s_barrier
	s_setprio 0
	s_add_i32 s64, 0, 0x18000
	s_add_i32 s65, 0, 0x1c000
	ds_read_b128 v[132:135], v174 offset:32768
	ds_read_b128 v[158:161], v174 offset:33792
	ds_read_b128 v[166:169], v174 offset:34816
	ds_read_b128 v[170:173], v174 offset:35840
	ds_read_b128 v[182:185], v175 offset:32768
	ds_read_b128 v[186:189], v175 offset:33792
	ds_read_b128 v[190:193], v175 offset:34816
	ds_read_b128 v[194:197], v175 offset:35840
	s_add_u32 s6, s6, 0x80000
	s_addc_u32 s7, s7, 0
	s_mov_b32 m0, s46
	ds_read_b128 v[198:201], v176 offset:32768
	ds_read_b128 v[202:205], v176 offset:33792
	ds_read_b128 v[206:209], v176 offset:34816
	ds_read_b128 v[210:213], v176 offset:35840
	ds_read_b128 v[214:217], v176 offset:36864
	ds_read_b128 v[218:221], v176 offset:37888
	ds_read_b128 v[222:225], v176 offset:38912
	ds_read_b128 v[226:229], v176 offset:39936
	global_load_lds_dwordx4 v144, s[6:7]
	s_mov_b32 m0, s47
	s_nop 0
	global_load_lds_dwordx4 v140, s[6:7]
	s_setprio 1
	s_waitcnt vmcnt(8) lgkmcnt(0)
	s_barrier
	v_mfma_f32_16x16x32_bf16 v[128:131], v[132:135], v[198:201], v[128:131]
	v_mfma_f32_16x16x32_bf16 v[124:127], v[166:169], v[198:201], v[124:127]
	v_mfma_f32_16x16x32_bf16 v[112:115], v[132:135], v[206:209], v[112:115]
	v_mfma_f32_16x16x32_bf16 v[108:111], v[166:169], v[206:209], v[108:111]
	v_mfma_f32_16x16x32_bf16 v[96:99], v[132:135], v[214:217], v[96:99]
	v_mfma_f32_16x16x32_bf16 v[92:95], v[166:169], v[214:217], v[92:95]
	v_mfma_f32_16x16x32_bf16 v[80:83], v[132:135], v[222:225], v[80:83]
	v_mfma_f32_16x16x32_bf16 v[76:79], v[166:169], v[222:225], v[76:79]
	v_mfma_f32_16x16x32_bf16 v[128:131], v[158:161], v[202:205], v[128:131]
	v_mfma_f32_16x16x32_bf16 v[124:127], v[170:173], v[202:205], v[124:127]
	v_mfma_f32_16x16x32_bf16 v[112:115], v[158:161], v[210:213], v[112:115]
	v_mfma_f32_16x16x32_bf16 v[108:111], v[170:173], v[210:213], v[108:111]
	v_mfma_f32_16x16x32_bf16 v[96:99], v[158:161], v[218:221], v[96:99]
	v_mfma_f32_16x16x32_bf16 v[92:95], v[170:173], v[218:221], v[92:95]
	v_mfma_f32_16x16x32_bf16 v[80:83], v[158:161], v[226:229], v[80:83]
	v_mfma_f32_16x16x32_bf16 v[76:79], v[170:173], v[226:229], v[76:79]
	s_setprio 0
	s_setprio 1
	v_mfma_f32_16x16x32_bf16 v[120:123], v[182:185], v[198:201], v[120:123]
	v_mfma_f32_16x16x32_bf16 v[116:119], v[190:193], v[198:201], v[116:119]
	v_mfma_f32_16x16x32_bf16 v[104:107], v[182:185], v[206:209], v[104:107]
	v_mfma_f32_16x16x32_bf16 v[100:103], v[190:193], v[206:209], v[100:103]
	v_mfma_f32_16x16x32_bf16 v[88:91], v[182:185], v[214:217], v[88:91]
	v_mfma_f32_16x16x32_bf16 v[84:87], v[190:193], v[214:217], v[84:87]
	v_mfma_f32_16x16x32_bf16 v[72:75], v[182:185], v[222:225], v[72:75]
	v_mfma_f32_16x16x32_bf16 v[68:71], v[190:193], v[222:225], v[68:71]
	v_mfma_f32_16x16x32_bf16 v[120:123], v[186:189], v[202:205], v[120:123]
	v_mfma_f32_16x16x32_bf16 v[116:119], v[194:197], v[202:205], v[116:119]
	v_mfma_f32_16x16x32_bf16 v[104:107], v[186:189], v[210:213], v[104:107]
	v_mfma_f32_16x16x32_bf16 v[100:103], v[194:197], v[210:213], v[100:103]
	v_mfma_f32_16x16x32_bf16 v[88:91], v[186:189], v[218:221], v[88:91]
	v_mfma_f32_16x16x32_bf16 v[84:87], v[194:197], v[218:221], v[84:87]
	v_mfma_f32_16x16x32_bf16 v[72:75], v[186:189], v[226:229], v[72:75]
	v_mfma_f32_16x16x32_bf16 v[68:71], v[194:197], v[226:229], v[68:71]
	s_barrier
	s_setprio 0
	s_add_i32 s6, s64, s29
	s_mov_b32 m0, s6
	ds_read_b128 v[198:201], v176 offset:49152
	ds_read_b128 v[202:205], v176 offset:50176
	ds_read_b128 v[206:209], v176 offset:51200
	ds_read_b128 v[210:213], v176 offset:52224
	ds_read_b128 v[214:217], v176 offset:53248
	ds_read_b128 v[218:221], v176 offset:54272
	ds_read_b128 v[222:225], v176 offset:55296
	ds_read_b128 v[226:229], v176 offset:56320
	global_load_lds_dwordx4 v142, s[98:99]
	s_add_i32 m0, s6, 0x2000
	s_add_u32 s4, s4, 0x80080
	s_addc_u32 s5, s5, 0
	s_add_i32 s6, s65, s29
	global_load_lds_dwordx4 v138, s[98:99]
	s_mov_b32 m0, s6
	s_nop 0
	global_load_lds_dwordx4 v142, s[4:5]
	s_add_i32 m0, s6, 0x2000
	s_nop 0
	global_load_lds_dwordx4 v138, s[4:5]
	s_mov_b32 m0, s48
	s_nop 0
	global_load_lds_dwordx4 v144, s[100:101]
	s_mov_b32 m0, s49
	s_nop 0
	global_load_lds_dwordx4 v140, s[100:101]
	s_setprio 1
	s_waitcnt vmcnt(8) lgkmcnt(0)
	s_barrier
	v_mfma_f32_16x16x32_bf16 v[62:65], v[132:135], v[198:201], v[62:65]
	v_mfma_f32_16x16x32_bf16 v[58:61], v[166:169], v[198:201], v[58:61]
	v_mfma_f32_16x16x32_bf16 v[46:49], v[132:135], v[206:209], v[46:49]
	v_mfma_f32_16x16x32_bf16 v[42:45], v[166:169], v[206:209], v[42:45]
	v_mfma_f32_16x16x32_bf16 v[30:33], v[132:135], v[214:217], v[30:33]
	v_mfma_f32_16x16x32_bf16 v[26:29], v[166:169], v[214:217], v[26:29]
	v_mfma_f32_16x16x32_bf16 v[14:17], v[132:135], v[222:225], v[14:17]
	v_mfma_f32_16x16x32_bf16 v[10:13], v[166:169], v[222:225], v[10:13]
	v_mfma_f32_16x16x32_bf16 v[62:65], v[158:161], v[202:205], v[62:65]
	v_mfma_f32_16x16x32_bf16 v[58:61], v[170:173], v[202:205], v[58:61]
	v_mfma_f32_16x16x32_bf16 v[46:49], v[158:161], v[210:213], v[46:49]
	v_mfma_f32_16x16x32_bf16 v[42:45], v[170:173], v[210:213], v[42:45]
	v_mfma_f32_16x16x32_bf16 v[30:33], v[158:161], v[218:221], v[30:33]
	v_mfma_f32_16x16x32_bf16 v[26:29], v[170:173], v[218:221], v[26:29]
	v_mfma_f32_16x16x32_bf16 v[14:17], v[158:161], v[226:229], v[14:17]
	v_mfma_f32_16x16x32_bf16 v[10:13], v[170:173], v[226:229], v[10:13]
	s_setprio 0
	s_setprio 1
	v_mfma_f32_16x16x32_bf16 v[54:57], v[182:185], v[198:201], v[54:57]
	v_mfma_f32_16x16x32_bf16 v[50:53], v[190:193], v[198:201], v[50:53]
	v_mfma_f32_16x16x32_bf16 v[38:41], v[182:185], v[206:209], v[38:41]
	v_mfma_f32_16x16x32_bf16 v[34:37], v[190:193], v[206:209], v[34:37]
	v_mfma_f32_16x16x32_bf16 v[22:25], v[182:185], v[214:217], v[22:25]
	v_mfma_f32_16x16x32_bf16 v[18:21], v[190:193], v[214:217], v[18:21]
	v_mfma_f32_16x16x32_bf16 v[6:9], v[182:185], v[222:225], v[6:9]
	v_mfma_f32_16x16x32_bf16 v[2:5], v[190:193], v[222:225], v[2:5]
	v_mfma_f32_16x16x32_bf16 v[54:57], v[186:189], v[202:205], v[54:57]
	v_mfma_f32_16x16x32_bf16 v[50:53], v[194:197], v[202:205], v[50:53]
	v_mfma_f32_16x16x32_bf16 v[38:41], v[186:189], v[210:213], v[38:41]
	v_mfma_f32_16x16x32_bf16 v[34:37], v[194:197], v[210:213], v[34:37]
	v_mfma_f32_16x16x32_bf16 v[22:25], v[186:189], v[218:221], v[22:25]
	v_mfma_f32_16x16x32_bf16 v[18:21], v[194:197], v[218:221], v[18:21]
	v_mfma_f32_16x16x32_bf16 v[6:9], v[186:189], v[226:229], v[6:9]
	v_mfma_f32_16x16x32_bf16 v[2:5], v[194:197], v[226:229], v[2:5]
	s_barrier
	s_setprio 0
	s_add_i32 s63, s63, 2
	s_add_u32 s0, s0, 0x100
	s_addc_u32 s1, s1, 0
	s_add_u32 s61, s61, 0x100
	s_addc_u32 s62, s62, 0
	s_cmp_gt_u32 s63, 29
.LBB0_1479:
	ds_read_b128 v[132:135], v174
	ds_read_b128 v[158:161], v174 offset:1024
	ds_read_b128 v[166:169], v174 offset:2048
	ds_read_b128 v[170:173], v174 offset:3072
	ds_read_b128 v[182:185], v175
	ds_read_b128 v[186:189], v175 offset:1024
	ds_read_b128 v[190:193], v175 offset:2048
	ds_read_b128 v[194:197], v175 offset:3072
	s_add_u32 s4, s0, 0xfff80080
	s_addc_u32 s5, s1, -1
	s_cmp_eq_u32 s63, 28
	s_cselect_b32 s7, s9, s5
	s_cselect_b32 s6, s11, s4
	s_cselect_b32 s5, s37, s62
	s_cselect_b32 s4, s60, s61
	s_add_i32 m0, s44, 0xc000
	ds_read_b128 v[198:201], v176
	ds_read_b128 v[202:205], v176 offset:1024
	ds_read_b128 v[206:209], v176 offset:2048
	ds_read_b128 v[210:213], v176 offset:3072
	ds_read_b128 v[214:217], v176 offset:4096
	ds_read_b128 v[218:221], v176 offset:5120
	ds_read_b128 v[222:225], v176 offset:6144
	ds_read_b128 v[226:229], v176 offset:7168
	global_load_lds_dwordx4 v146, s[0:1]
	s_add_i32 m0, s44, 0xe000
	s_nop 0
	global_load_lds_dwordx4 v148, s[0:1]
	s_setprio 1
	s_waitcnt vmcnt(8) lgkmcnt(0)
	s_barrier
	v_mfma_f32_16x16x32_bf16 v[128:131], v[132:135], v[198:201], v[128:131]
	v_mfma_f32_16x16x32_bf16 v[124:127], v[166:169], v[198:201], v[124:127]
	v_mfma_f32_16x16x32_bf16 v[112:115], v[132:135], v[206:209], v[112:115]
	v_mfma_f32_16x16x32_bf16 v[108:111], v[166:169], v[206:209], v[108:111]
	v_mfma_f32_16x16x32_bf16 v[96:99], v[132:135], v[214:217], v[96:99]
	v_mfma_f32_16x16x32_bf16 v[92:95], v[166:169], v[214:217], v[92:95]
	v_mfma_f32_16x16x32_bf16 v[80:83], v[132:135], v[222:225], v[80:83]
	v_mfma_f32_16x16x32_bf16 v[76:79], v[166:169], v[222:225], v[76:79]
	v_mfma_f32_16x16x32_bf16 v[128:131], v[158:161], v[202:205], v[128:131]
	v_mfma_f32_16x16x32_bf16 v[124:127], v[170:173], v[202:205], v[124:127]
	v_mfma_f32_16x16x32_bf16 v[112:115], v[158:161], v[210:213], v[112:115]
	v_mfma_f32_16x16x32_bf16 v[108:111], v[170:173], v[210:213], v[108:111]
	v_mfma_f32_16x16x32_bf16 v[96:99], v[158:161], v[218:221], v[96:99]
	v_mfma_f32_16x16x32_bf16 v[92:95], v[170:173], v[218:221], v[92:95]
	v_mfma_f32_16x16x32_bf16 v[80:83], v[158:161], v[226:229], v[80:83]
	v_mfma_f32_16x16x32_bf16 v[76:79], v[170:173], v[226:229], v[76:79]
	s_setprio 0
	s_setprio 1
	v_mfma_f32_16x16x32_bf16 v[120:123], v[182:185], v[198:201], v[120:123]
	v_mfma_f32_16x16x32_bf16 v[116:119], v[190:193], v[198:201], v[116:119]
	v_mfma_f32_16x16x32_bf16 v[104:107], v[182:185], v[206:209], v[104:107]
	v_mfma_f32_16x16x32_bf16 v[100:103], v[190:193], v[206:209], v[100:103]
	v_mfma_f32_16x16x32_bf16 v[88:91], v[182:185], v[214:217], v[88:91]
	v_mfma_f32_16x16x32_bf16 v[84:87], v[190:193], v[214:217], v[84:87]
	v_mfma_f32_16x16x32_bf16 v[72:75], v[182:185], v[222:225], v[72:75]
	v_mfma_f32_16x16x32_bf16 v[68:71], v[190:193], v[222:225], v[68:71]
	v_mfma_f32_16x16x32_bf16 v[120:123], v[186:189], v[202:205], v[120:123]
	v_mfma_f32_16x16x32_bf16 v[116:119], v[194:197], v[202:205], v[116:119]
	v_mfma_f32_16x16x32_bf16 v[104:107], v[186:189], v[210:213], v[104:107]
	v_mfma_f32_16x16x32_bf16 v[100:103], v[194:197], v[210:213], v[100:103]
	v_mfma_f32_16x16x32_bf16 v[88:91], v[186:189], v[218:221], v[88:91]
	v_mfma_f32_16x16x32_bf16 v[84:87], v[194:197], v[218:221], v[84:87]
	v_mfma_f32_16x16x32_bf16 v[72:75], v[186:189], v[226:229], v[72:75]
	v_mfma_f32_16x16x32_bf16 v[68:71], v[194:197], v[226:229], v[68:71]
	s_barrier
	s_setprio 0
	s_add_i32 s64, s54, s29
	s_add_u32 s98, s4, 0x80
	s_addc_u32 s99, s5, 0
	s_mov_b32 m0, s64
	ds_read_b128 v[198:201], v176 offset:16384
	ds_read_b128 v[202:205], v176 offset:17408
	ds_read_b128 v[206:209], v176 offset:18432
	ds_read_b128 v[210:213], v176 offset:19456
	ds_read_b128 v[214:217], v176 offset:20480
	ds_read_b128 v[218:221], v176 offset:21504
	ds_read_b128 v[222:225], v176 offset:22528
	ds_read_b128 v[226:229], v176 offset:23552
	global_load_lds_dwordx4 v142, s[4:5]
	s_add_i32 m0, s64, 0x2000
	s_add_u32 s64, s4, 0x80000
	s_addc_u32 s65, s5, 0
	s_add_i32 s66, s55, s29
	global_load_lds_dwordx4 v138, s[4:5]
	s_mov_b32 m0, s66
	s_nop 0
	global_load_lds_dwordx4 v142, s[64:65]
	s_add_i32 m0, s66, 0x2000
	s_nop 0
	global_load_lds_dwordx4 v138, s[64:65]
	s_add_u32 s100, s6, 0x80
	s_addc_u32 s101, s7, 0
	s_mov_b32 m0, s44
	s_nop 0
	global_load_lds_dwordx4 v144, s[6:7]
	s_mov_b32 m0, s45
	s_nop 0
	global_load_lds_dwordx4 v140, s[6:7]
	s_setprio 1
	s_waitcnt vmcnt(8) lgkmcnt(0)
	s_barrier
	v_mfma_f32_16x16x32_bf16 v[62:65], v[132:135], v[198:201], v[62:65]
	v_mfma_f32_16x16x32_bf16 v[58:61], v[166:169], v[198:201], v[58:61]
	v_mfma_f32_16x16x32_bf16 v[46:49], v[132:135], v[206:209], v[46:49]
	v_mfma_f32_16x16x32_bf16 v[42:45], v[166:169], v[206:209], v[42:45]
	v_mfma_f32_16x16x32_bf16 v[30:33], v[132:135], v[214:217], v[30:33]
	v_mfma_f32_16x16x32_bf16 v[26:29], v[166:169], v[214:217], v[26:29]
	v_mfma_f32_16x16x32_bf16 v[14:17], v[132:135], v[222:225], v[14:17]
	v_mfma_f32_16x16x32_bf16 v[10:13], v[166:169], v[222:225], v[10:13]
	v_mfma_f32_16x16x32_bf16 v[62:65], v[158:161], v[202:205], v[62:65]
	v_mfma_f32_16x16x32_bf16 v[58:61], v[170:173], v[202:205], v[58:61]
	v_mfma_f32_16x16x32_bf16 v[46:49], v[158:161], v[210:213], v[46:49]
	v_mfma_f32_16x16x32_bf16 v[42:45], v[170:173], v[210:213], v[42:45]
	v_mfma_f32_16x16x32_bf16 v[30:33], v[158:161], v[218:221], v[30:33]
	v_mfma_f32_16x16x32_bf16 v[26:29], v[170:173], v[218:221], v[26:29]
	v_mfma_f32_16x16x32_bf16 v[14:17], v[158:161], v[226:229], v[14:17]
	v_mfma_f32_16x16x32_bf16 v[10:13], v[170:173], v[226:229], v[10:13]
	s_setprio 0
	s_setprio 1
	v_mfma_f32_16x16x32_bf16 v[54:57], v[182:185], v[198:201], v[54:57]
	v_mfma_f32_16x16x32_bf16 v[50:53], v[190:193], v[198:201], v[50:53]
	v_mfma_f32_16x16x32_bf16 v[38:41], v[182:185], v[206:209], v[38:41]
	v_mfma_f32_16x16x32_bf16 v[34:37], v[190:193], v[206:209], v[34:37]
	v_mfma_f32_16x16x32_bf16 v[22:25], v[182:185], v[214:217], v[22:25]
	v_mfma_f32_16x16x32_bf16 v[18:21], v[190:193], v[214:217], v[18:21]
	v_mfma_f32_16x16x32_bf16 v[6:9], v[182:185], v[222:225], v[6:9]
	v_mfma_f32_16x16x32_bf16 v[2:5], v[190:193], v[222:225], v[2:5]
	v_mfma_f32_16x16x32_bf16 v[54:57], v[186:189], v[202:205], v[54:57]
	v_mfma_f32_16x16x32_bf16 v[50:53], v[194:197], v[202:205], v[50:53]
	v_mfma_f32_16x16x32_bf16 v[38:41], v[186:189], v[210:213], v[38:41]
	v_mfma_f32_16x16x32_bf16 v[34:37], v[194:197], v[210:213], v[34:37]
	v_mfma_f32_16x16x32_bf16 v[22:25], v[186:189], v[218:221], v[22:25]
	v_mfma_f32_16x16x32_bf16 v[18:21], v[194:197], v[218:221], v[18:21]
	v_mfma_f32_16x16x32_bf16 v[6:9], v[186:189], v[226:229], v[6:9]
	v_mfma_f32_16x16x32_bf16 v[2:5], v[194:197], v[226:229], v[2:5]
	s_barrier
	s_setprio 0
	s_add_i32 s64, 0, 0x18000
	s_add_i32 s65, 0, 0x1c000
	ds_read_b128 v[132:135], v174 offset:32768
	ds_read_b128 v[158:161], v174 offset:33792
	ds_read_b128 v[166:169], v174 offset:34816
	ds_read_b128 v[170:173], v174 offset:35840
	ds_read_b128 v[182:185], v175 offset:32768
	ds_read_b128 v[186:189], v175 offset:33792
	ds_read_b128 v[190:193], v175 offset:34816
	ds_read_b128 v[194:197], v175 offset:35840
	s_add_u32 s6, s6, 0x80000
	s_addc_u32 s7, s7, 0
	s_mov_b32 m0, s46
	ds_read_b128 v[198:201], v176 offset:32768
	ds_read_b128 v[202:205], v176 offset:33792
	ds_read_b128 v[206:209], v176 offset:34816
	ds_read_b128 v[210:213], v176 offset:35840
	ds_read_b128 v[214:217], v176 offset:36864
	ds_read_b128 v[218:221], v176 offset:37888
	ds_read_b128 v[222:225], v176 offset:38912
	ds_read_b128 v[226:229], v176 offset:39936
	global_load_lds_dwordx4 v144, s[6:7]
	s_mov_b32 m0, s47
	s_nop 0
	global_load_lds_dwordx4 v140, s[6:7]
	s_setprio 1
	s_waitcnt vmcnt(8) lgkmcnt(0)
	s_barrier
	v_mfma_f32_16x16x32_bf16 v[128:131], v[132:135], v[198:201], v[128:131]
	v_mfma_f32_16x16x32_bf16 v[124:127], v[166:169], v[198:201], v[124:127]
	v_mfma_f32_16x16x32_bf16 v[112:115], v[132:135], v[206:209], v[112:115]
	v_mfma_f32_16x16x32_bf16 v[108:111], v[166:169], v[206:209], v[108:111]
	v_mfma_f32_16x16x32_bf16 v[96:99], v[132:135], v[214:217], v[96:99]
	v_mfma_f32_16x16x32_bf16 v[92:95], v[166:169], v[214:217], v[92:95]
	v_mfma_f32_16x16x32_bf16 v[80:83], v[132:135], v[222:225], v[80:83]
	v_mfma_f32_16x16x32_bf16 v[76:79], v[166:169], v[222:225], v[76:79]
	v_mfma_f32_16x16x32_bf16 v[128:131], v[158:161], v[202:205], v[128:131]
	v_mfma_f32_16x16x32_bf16 v[124:127], v[170:173], v[202:205], v[124:127]
	v_mfma_f32_16x16x32_bf16 v[112:115], v[158:161], v[210:213], v[112:115]
	v_mfma_f32_16x16x32_bf16 v[108:111], v[170:173], v[210:213], v[108:111]
	v_mfma_f32_16x16x32_bf16 v[96:99], v[158:161], v[218:221], v[96:99]
	v_mfma_f32_16x16x32_bf16 v[92:95], v[170:173], v[218:221], v[92:95]
	v_mfma_f32_16x16x32_bf16 v[80:83], v[158:161], v[226:229], v[80:83]
	v_mfma_f32_16x16x32_bf16 v[76:79], v[170:173], v[226:229], v[76:79]
	s_setprio 0
	s_setprio 1
	v_mfma_f32_16x16x32_bf16 v[120:123], v[182:185], v[198:201], v[120:123]
	v_mfma_f32_16x16x32_bf16 v[116:119], v[190:193], v[198:201], v[116:119]
	v_mfma_f32_16x16x32_bf16 v[104:107], v[182:185], v[206:209], v[104:107]
	v_mfma_f32_16x16x32_bf16 v[100:103], v[190:193], v[206:209], v[100:103]
	v_mfma_f32_16x16x32_bf16 v[88:91], v[182:185], v[214:217], v[88:91]
	v_mfma_f32_16x16x32_bf16 v[84:87], v[190:193], v[214:217], v[84:87]
	v_mfma_f32_16x16x32_bf16 v[72:75], v[182:185], v[222:225], v[72:75]
	v_mfma_f32_16x16x32_bf16 v[68:71], v[190:193], v[222:225], v[68:71]
	v_mfma_f32_16x16x32_bf16 v[120:123], v[186:189], v[202:205], v[120:123]
	v_mfma_f32_16x16x32_bf16 v[116:119], v[194:197], v[202:205], v[116:119]
	v_mfma_f32_16x16x32_bf16 v[104:107], v[186:189], v[210:213], v[104:107]
	v_mfma_f32_16x16x32_bf16 v[100:103], v[194:197], v[210:213], v[100:103]
	v_mfma_f32_16x16x32_bf16 v[88:91], v[186:189], v[218:221], v[88:91]
	v_mfma_f32_16x16x32_bf16 v[84:87], v[194:197], v[218:221], v[84:87]
	v_mfma_f32_16x16x32_bf16 v[72:75], v[186:189], v[226:229], v[72:75]
	v_mfma_f32_16x16x32_bf16 v[68:71], v[194:197], v[226:229], v[68:71]
	s_barrier
	s_setprio 0
	s_add_i32 s6, s64, s29
	s_mov_b32 m0, s6
	ds_read_b128 v[198:201], v176 offset:49152
	ds_read_b128 v[202:205], v176 offset:50176
	ds_read_b128 v[206:209], v176 offset:51200
	ds_read_b128 v[210:213], v176 offset:52224
	ds_read_b128 v[214:217], v176 offset:53248
	ds_read_b128 v[218:221], v176 offset:54272
	ds_read_b128 v[222:225], v176 offset:55296
	ds_read_b128 v[226:229], v176 offset:56320
	global_load_lds_dwordx4 v142, s[98:99]
	s_add_i32 m0, s6, 0x2000
	s_add_u32 s4, s4, 0x80080
	s_addc_u32 s5, s5, 0
	s_add_i32 s6, s65, s29
	global_load_lds_dwordx4 v138, s[98:99]
	s_mov_b32 m0, s6
	s_nop 0
	global_load_lds_dwordx4 v142, s[4:5]
	s_add_i32 m0, s6, 0x2000
	s_nop 0
	global_load_lds_dwordx4 v138, s[4:5]
	s_mov_b32 m0, s48
	s_nop 0
	global_load_lds_dwordx4 v144, s[100:101]
	s_mov_b32 m0, s49
	s_nop 0
	global_load_lds_dwordx4 v140, s[100:101]
	s_add_i32 s63, s63, 2
	s_add_u32 s0, s0, 0x100
	s_addc_u32 s1, s1, 0
	s_add_u32 s61, s61, 0x100
	s_addc_u32 s62, s62, 0
	s_cmp_gt_u32 s63, 29
	s_setprio 1
	s_waitcnt vmcnt(8) lgkmcnt(0)
	s_barrier
	v_mfma_f32_16x16x32_bf16 v[62:65], v[132:135], v[198:201], v[62:65]
	v_mfma_f32_16x16x32_bf16 v[58:61], v[166:169], v[198:201], v[58:61]
	v_mfma_f32_16x16x32_bf16 v[46:49], v[132:135], v[206:209], v[46:49]
	v_mfma_f32_16x16x32_bf16 v[42:45], v[166:169], v[206:209], v[42:45]
	v_mfma_f32_16x16x32_bf16 v[30:33], v[132:135], v[214:217], v[30:33]
	v_mfma_f32_16x16x32_bf16 v[26:29], v[166:169], v[214:217], v[26:29]
	v_mfma_f32_16x16x32_bf16 v[14:17], v[132:135], v[222:225], v[14:17]
	v_mfma_f32_16x16x32_bf16 v[10:13], v[166:169], v[222:225], v[10:13]
	v_mfma_f32_16x16x32_bf16 v[62:65], v[158:161], v[202:205], v[62:65]
	v_mfma_f32_16x16x32_bf16 v[58:61], v[170:173], v[202:205], v[58:61]
	v_mfma_f32_16x16x32_bf16 v[46:49], v[158:161], v[210:213], v[46:49]
	v_mfma_f32_16x16x32_bf16 v[42:45], v[170:173], v[210:213], v[42:45]
	v_mfma_f32_16x16x32_bf16 v[30:33], v[158:161], v[218:221], v[30:33]
	v_mfma_f32_16x16x32_bf16 v[26:29], v[170:173], v[218:221], v[26:29]
	v_mfma_f32_16x16x32_bf16 v[14:17], v[158:161], v[226:229], v[14:17]
	v_mfma_f32_16x16x32_bf16 v[10:13], v[170:173], v[226:229], v[10:13]
	s_setprio 0
	s_setprio 1
	v_mfma_f32_16x16x32_bf16 v[54:57], v[182:185], v[198:201], v[54:57]
	v_mfma_f32_16x16x32_bf16 v[50:53], v[190:193], v[198:201], v[50:53]
	v_mfma_f32_16x16x32_bf16 v[38:41], v[182:185], v[206:209], v[38:41]
	v_mfma_f32_16x16x32_bf16 v[34:37], v[190:193], v[206:209], v[34:37]
	v_mfma_f32_16x16x32_bf16 v[22:25], v[182:185], v[214:217], v[22:25]
	v_mfma_f32_16x16x32_bf16 v[18:21], v[190:193], v[214:217], v[18:21]
	v_mfma_f32_16x16x32_bf16 v[6:9], v[182:185], v[222:225], v[6:9]
	v_mfma_f32_16x16x32_bf16 v[2:5], v[190:193], v[222:225], v[2:5]
	v_mfma_f32_16x16x32_bf16 v[54:57], v[186:189], v[202:205], v[54:57]
	v_mfma_f32_16x16x32_bf16 v[50:53], v[194:197], v[202:205], v[50:53]
	v_mfma_f32_16x16x32_bf16 v[38:41], v[186:189], v[210:213], v[38:41]
	v_mfma_f32_16x16x32_bf16 v[34:37], v[194:197], v[210:213], v[34:37]
	v_mfma_f32_16x16x32_bf16 v[22:25], v[186:189], v[218:221], v[22:25]
	v_mfma_f32_16x16x32_bf16 v[18:21], v[194:197], v[218:221], v[18:21]
	v_mfma_f32_16x16x32_bf16 v[6:9], v[186:189], v[226:229], v[6:9]
	v_mfma_f32_16x16x32_bf16 v[2:5], v[194:197], v[226:229], v[2:5]
	s_barrier
	s_setprio 0
	s_cbranch_scc0 .LBB0_1479
	s_and_b64 vcc, exec, s[34:35]
	s_cbranch_vccz .LBB0_1482
	s_barrier

.LBB0_1565:
	s_add_u32 s16, s16, 0x160080
	s_addc_u32 s17, s17, 0
	s_add_u32 s46, s20, 0x100
	s_addc_u32 s47, s21, 0
	s_mov_b32 s48, -2
	ds_read_b128 v[144:147], v151
	ds_read_b128 v[154:157], v151 offset:1024
	ds_read_b128 v[158:161], v151 offset:2048
	ds_read_b128 v[162:165], v151 offset:3072
	ds_read_b128 v[166:169], v152
	ds_read_b128 v[170:173], v152 offset:1024
	ds_read_b128 v[174:177], v152 offset:2048
	ds_read_b128 v[178:181], v152 offset:3072
	s_add_u32 s20, s16, 0xffea0080
	s_addc_u32 s21, s17, -1
	s_cmpk_eq_i32 s48, 0x54
	s_cselect_b32 s27, s5, s21
	s_cselect_b32 s26, s4, s20
	s_cselect_b32 s21, s15, s47
	s_cselect_b32 s20, s14, s46
	s_add_i32 m0, s30, 0xc000
	ds_read_b128 v[182:185], v153
	ds_read_b128 v[186:189], v153 offset:1024
	ds_read_b128 v[190:193], v153 offset:2048
	ds_read_b128 v[194:197], v153 offset:3072
	ds_read_b128 v[198:201], v153 offset:4096
	ds_read_b128 v[202:205], v153 offset:5120
	ds_read_b128 v[206:209], v153 offset:6144
	ds_read_b128 v[210:213], v153 offset:7168
	global_load_lds_dwordx4 v136, s[16:17]
	s_add_i32 m0, s30, 0xe000
	s_nop 0
	global_load_lds_dwordx4 v138, s[16:17]
	s_setprio 1
	s_waitcnt vmcnt(8) lgkmcnt(0)
	s_barrier
	v_mfma_f32_16x16x32_bf16 v[124:127], v[144:147], v[182:185], 0
	v_mfma_f32_16x16x32_bf16 v[120:123], v[158:161], v[182:185], 0
	v_mfma_f32_16x16x32_bf16 v[108:111], v[144:147], v[190:193], 0
	v_mfma_f32_16x16x32_bf16 v[104:107], v[158:161], v[190:193], 0
	v_mfma_f32_16x16x32_bf16 v[88:91], v[144:147], v[198:201], 0
	v_mfma_f32_16x16x32_bf16 v[92:95], v[158:161], v[198:201], 0
	v_mfma_f32_16x16x32_bf16 v[72:75], v[144:147], v[206:209], 0
	v_mfma_f32_16x16x32_bf16 v[76:79], v[158:161], v[206:209], 0
	v_mfma_f32_16x16x32_bf16 v[124:127], v[154:157], v[186:189], v[124:127]
	v_mfma_f32_16x16x32_bf16 v[120:123], v[162:165], v[186:189], v[120:123]
	v_mfma_f32_16x16x32_bf16 v[108:111], v[154:157], v[194:197], v[108:111]
	v_mfma_f32_16x16x32_bf16 v[104:107], v[162:165], v[194:197], v[104:107]
	v_mfma_f32_16x16x32_bf16 v[88:91], v[154:157], v[202:205], v[88:91]
	v_mfma_f32_16x16x32_bf16 v[92:95], v[162:165], v[202:205], v[92:95]
	v_mfma_f32_16x16x32_bf16 v[72:75], v[154:157], v[210:213], v[72:75]
	v_mfma_f32_16x16x32_bf16 v[76:79], v[162:165], v[210:213], v[76:79]
	s_setprio 0
	s_setprio 1
	v_mfma_f32_16x16x32_bf16 v[116:119], v[166:169], v[182:185], 0
	v_mfma_f32_16x16x32_bf16 v[112:115], v[174:177], v[182:185], 0
	v_mfma_f32_16x16x32_bf16 v[96:99], v[166:169], v[190:193], 0
	v_mfma_f32_16x16x32_bf16 v[100:103], v[174:177], v[190:193], 0
	v_mfma_f32_16x16x32_bf16 v[80:83], v[166:169], v[198:201], 0
	v_mfma_f32_16x16x32_bf16 v[84:87], v[174:177], v[198:201], 0
	v_mfma_f32_16x16x32_bf16 v[64:67], v[166:169], v[206:209], 0
	v_mfma_f32_16x16x32_bf16 v[68:71], v[174:177], v[206:209], 0
	v_mfma_f32_16x16x32_bf16 v[116:119], v[170:173], v[186:189], v[116:119]
	v_mfma_f32_16x16x32_bf16 v[112:115], v[178:181], v[186:189], v[112:115]
	v_mfma_f32_16x16x32_bf16 v[96:99], v[170:173], v[194:197], v[96:99]
	v_mfma_f32_16x16x32_bf16 v[100:103], v[178:181], v[194:197], v[100:103]
	v_mfma_f32_16x16x32_bf16 v[80:83], v[170:173], v[202:205], v[80:83]
	v_mfma_f32_16x16x32_bf16 v[84:87], v[178:181], v[202:205], v[84:87]
	v_mfma_f32_16x16x32_bf16 v[64:67], v[170:173], v[210:213], v[64:67]
	v_mfma_f32_16x16x32_bf16 v[68:71], v[178:181], v[210:213], v[68:71]
	s_barrier
	s_setprio 0
	s_add_i32 s49, s40, s29
	s_add_u32 s98, s20, 0x80
	s_addc_u32 s99, s21, 0
	s_mov_b32 m0, s49
	ds_read_b128 v[182:185], v153 offset:16384
	ds_read_b128 v[186:189], v153 offset:17408
	ds_read_b128 v[190:193], v153 offset:18432
	ds_read_b128 v[194:197], v153 offset:19456
	ds_read_b128 v[198:201], v153 offset:20480
	ds_read_b128 v[202:205], v153 offset:21504
	ds_read_b128 v[206:209], v153 offset:22528
	ds_read_b128 v[210:213], v153 offset:23552
	global_load_lds_dwordx4 v130, s[20:21]
	s_add_i32 m0, s49, 0x2000
	s_add_u32 s52, s20, 0x160000
	s_addc_u32 s53, s21, 0
	s_add_i32 s49, s41, s29
	global_load_lds_dwordx4 v134, s[20:21]
	s_mov_b32 m0, s49
	s_nop 0
	global_load_lds_dwordx4 v130, s[52:53]
	s_add_i32 m0, s49, 0x2000
	s_nop 0
	global_load_lds_dwordx4 v134, s[52:53]
	s_add_u32 s100, s26, 0x80
	s_addc_u32 s101, s27, 0
	s_mov_b32 m0, s30
	s_nop 0
	global_load_lds_dwordx4 v128, s[26:27]
	s_mov_b32 m0, s31
	s_nop 0
	global_load_lds_dwordx4 v132, s[26:27]
	s_setprio 1
	s_waitcnt vmcnt(8) lgkmcnt(0)
	s_barrier
	v_mfma_f32_16x16x32_bf16 v[56:59], v[144:147], v[182:185], 0
	v_mfma_f32_16x16x32_bf16 v[60:63], v[158:161], v[182:185], 0
	v_mfma_f32_16x16x32_bf16 v[40:43], v[144:147], v[190:193], 0
	v_mfma_f32_16x16x32_bf16 v[44:47], v[158:161], v[190:193], 0
	v_mfma_f32_16x16x32_bf16 v[24:27], v[144:147], v[198:201], 0
	v_mfma_f32_16x16x32_bf16 v[28:31], v[158:161], v[198:201], 0
	v_mfma_f32_16x16x32_bf16 v[8:11], v[144:147], v[206:209], 0
	v_mfma_f32_16x16x32_bf16 v[12:15], v[158:161], v[206:209], 0
	v_mfma_f32_16x16x32_bf16 v[56:59], v[154:157], v[186:189], v[56:59]
	v_mfma_f32_16x16x32_bf16 v[60:63], v[162:165], v[186:189], v[60:63]
	v_mfma_f32_16x16x32_bf16 v[40:43], v[154:157], v[194:197], v[40:43]
	v_mfma_f32_16x16x32_bf16 v[44:47], v[162:165], v[194:197], v[44:47]
	v_mfma_f32_16x16x32_bf16 v[24:27], v[154:157], v[202:205], v[24:27]
	v_mfma_f32_16x16x32_bf16 v[28:31], v[162:165], v[202:205], v[28:31]
	v_mfma_f32_16x16x32_bf16 v[8:11], v[154:157], v[210:213], v[8:11]
	v_mfma_f32_16x16x32_bf16 v[12:15], v[162:165], v[210:213], v[12:15]
	s_setprio 0
	s_setprio 1
	v_mfma_f32_16x16x32_bf16 v[48:51], v[166:169], v[182:185], 0
	v_mfma_f32_16x16x32_bf16 v[52:55], v[174:177], v[182:185], 0
	v_mfma_f32_16x16x32_bf16 v[32:35], v[166:169], v[190:193], 0
	v_mfma_f32_16x16x32_bf16 v[36:39], v[174:177], v[190:193], 0
	v_mfma_f32_16x16x32_bf16 v[16:19], v[166:169], v[198:201], 0
	v_mfma_f32_16x16x32_bf16 v[20:23], v[174:177], v[198:201], 0
	v_mfma_f32_16x16x32_bf16 v[0:3], v[166:169], v[206:209], 0
	v_mfma_f32_16x16x32_bf16 v[4:7], v[174:177], v[206:209], 0
	v_mfma_f32_16x16x32_bf16 v[48:51], v[170:173], v[186:189], v[48:51]
	v_mfma_f32_16x16x32_bf16 v[52:55], v[178:181], v[186:189], v[52:55]
	v_mfma_f32_16x16x32_bf16 v[32:35], v[170:173], v[194:197], v[32:35]
	v_mfma_f32_16x16x32_bf16 v[36:39], v[178:181], v[194:197], v[36:39]
	v_mfma_f32_16x16x32_bf16 v[16:19], v[170:173], v[202:205], v[16:19]
	v_mfma_f32_16x16x32_bf16 v[20:23], v[178:181], v[202:205], v[20:23]
	v_mfma_f32_16x16x32_bf16 v[0:3], v[170:173], v[210:213], v[0:3]
	v_mfma_f32_16x16x32_bf16 v[4:7], v[178:181], v[210:213], v[4:7]
	s_barrier
	s_setprio 0
	s_add_i32 s49, 0, 0x18000
	s_add_i32 s52, 0, 0x1c000
	ds_read_b128 v[144:147], v151 offset:32768
	ds_read_b128 v[154:157], v151 offset:33792
	ds_read_b128 v[158:161], v151 offset:34816
	ds_read_b128 v[162:165], v151 offset:35840
	ds_read_b128 v[166:169], v152 offset:32768
	ds_read_b128 v[170:173], v152 offset:33792
	ds_read_b128 v[174:177], v152 offset:34816
	ds_read_b128 v[178:181], v152 offset:35840
	s_add_u32 s26, s26, 0x160000
	s_addc_u32 s27, s27, 0
	s_mov_b32 m0, s34
	ds_read_b128 v[182:185], v153 offset:32768
	ds_read_b128 v[186:189], v153 offset:33792
	ds_read_b128 v[190:193], v153 offset:34816
	ds_read_b128 v[194:197], v153 offset:35840
	ds_read_b128 v[198:201], v153 offset:36864
	ds_read_b128 v[202:205], v153 offset:37888
	ds_read_b128 v[206:209], v153 offset:38912
	ds_read_b128 v[210:213], v153 offset:39936
	global_load_lds_dwordx4 v128, s[26:27]
	s_mov_b32 m0, s35
	s_nop 0
	global_load_lds_dwordx4 v132, s[26:27]
	s_setprio 1
	s_waitcnt vmcnt(8) lgkmcnt(0)
	s_barrier
	v_mfma_f32_16x16x32_bf16 v[124:127], v[144:147], v[182:185], v[124:127]
	v_mfma_f32_16x16x32_bf16 v[120:123], v[158:161], v[182:185], v[120:123]
	v_mfma_f32_16x16x32_bf16 v[108:111], v[144:147], v[190:193], v[108:111]
	v_mfma_f32_16x16x32_bf16 v[104:107], v[158:161], v[190:193], v[104:107]
	v_mfma_f32_16x16x32_bf16 v[88:91], v[144:147], v[198:201], v[88:91]
	v_mfma_f32_16x16x32_bf16 v[92:95], v[158:161], v[198:201], v[92:95]
	v_mfma_f32_16x16x32_bf16 v[72:75], v[144:147], v[206:209], v[72:75]
	v_mfma_f32_16x16x32_bf16 v[76:79], v[158:161], v[206:209], v[76:79]
	v_mfma_f32_16x16x32_bf16 v[124:127], v[154:157], v[186:189], v[124:127]
	v_mfma_f32_16x16x32_bf16 v[120:123], v[162:165], v[186:189], v[120:123]
	v_mfma_f32_16x16x32_bf16 v[108:111], v[154:157], v[194:197], v[108:111]
	v_mfma_f32_16x16x32_bf16 v[104:107], v[162:165], v[194:197], v[104:107]
	v_mfma_f32_16x16x32_bf16 v[88:91], v[154:157], v[202:205], v[88:91]
	v_mfma_f32_16x16x32_bf16 v[92:95], v[162:165], v[202:205], v[92:95]
	v_mfma_f32_16x16x32_bf16 v[72:75], v[154:157], v[210:213], v[72:75]
	v_mfma_f32_16x16x32_bf16 v[76:79], v[162:165], v[210:213], v[76:79]
	s_setprio 0
	s_setprio 1
	v_mfma_f32_16x16x32_bf16 v[116:119], v[166:169], v[182:185], v[116:119]
	v_mfma_f32_16x16x32_bf16 v[112:115], v[174:177], v[182:185], v[112:115]
	v_mfma_f32_16x16x32_bf16 v[96:99], v[166:169], v[190:193], v[96:99]
	v_mfma_f32_16x16x32_bf16 v[100:103], v[174:177], v[190:193], v[100:103]
	v_mfma_f32_16x16x32_bf16 v[80:83], v[166:169], v[198:201], v[80:83]
	v_mfma_f32_16x16x32_bf16 v[84:87], v[174:177], v[198:201], v[84:87]
	v_mfma_f32_16x16x32_bf16 v[64:67], v[166:169], v[206:209], v[64:67]
	v_mfma_f32_16x16x32_bf16 v[68:71], v[174:177], v[206:209], v[68:71]
	v_mfma_f32_16x16x32_bf16 v[116:119], v[170:173], v[186:189], v[116:119]
	v_mfma_f32_16x16x32_bf16 v[112:115], v[178:181], v[186:189], v[112:115]
	v_mfma_f32_16x16x32_bf16 v[96:99], v[170:173], v[194:197], v[96:99]
	v_mfma_f32_16x16x32_bf16 v[100:103], v[178:181], v[194:197], v[100:103]
	v_mfma_f32_16x16x32_bf16 v[80:83], v[170:173], v[202:205], v[80:83]
	v_mfma_f32_16x16x32_bf16 v[84:87], v[178:181], v[202:205], v[84:87]
	v_mfma_f32_16x16x32_bf16 v[64:67], v[170:173], v[210:213], v[64:67]
	v_mfma_f32_16x16x32_bf16 v[68:71], v[178:181], v[210:213], v[68:71]
	s_barrier
	s_setprio 0
	s_add_i32 s26, s49, s29
	s_mov_b32 m0, s26
	ds_read_b128 v[182:185], v153 offset:49152
	ds_read_b128 v[186:189], v153 offset:50176
	ds_read_b128 v[190:193], v153 offset:51200
	ds_read_b128 v[194:197], v153 offset:52224
	ds_read_b128 v[198:201], v153 offset:53248
	ds_read_b128 v[202:205], v153 offset:54272
	ds_read_b128 v[206:209], v153 offset:55296
	ds_read_b128 v[210:213], v153 offset:56320
	global_load_lds_dwordx4 v130, s[98:99]
	s_add_i32 m0, s26, 0x2000
	s_add_u32 s20, s20, 0x160080
	s_addc_u32 s21, s21, 0
	s_add_i32 s26, s52, s29
	global_load_lds_dwordx4 v134, s[98:99]
	s_mov_b32 m0, s26
	s_nop 0
	global_load_lds_dwordx4 v130, s[20:21]
	s_add_i32 m0, s26, 0x2000
	s_nop 0
	global_load_lds_dwordx4 v134, s[20:21]
	s_mov_b32 m0, s37
	s_nop 0
	global_load_lds_dwordx4 v128, s[100:101]
	s_mov_b32 m0, s38
	s_nop 0
	global_load_lds_dwordx4 v132, s[100:101]
	s_setprio 1
	s_waitcnt vmcnt(8) lgkmcnt(0)
	s_barrier
	v_mfma_f32_16x16x32_bf16 v[56:59], v[144:147], v[182:185], v[56:59]
	v_mfma_f32_16x16x32_bf16 v[60:63], v[158:161], v[182:185], v[60:63]
	v_mfma_f32_16x16x32_bf16 v[40:43], v[144:147], v[190:193], v[40:43]
	v_mfma_f32_16x16x32_bf16 v[44:47], v[158:161], v[190:193], v[44:47]
	v_mfma_f32_16x16x32_bf16 v[24:27], v[144:147], v[198:201], v[24:27]
	v_mfma_f32_16x16x32_bf16 v[28:31], v[158:161], v[198:201], v[28:31]
	v_mfma_f32_16x16x32_bf16 v[8:11], v[144:147], v[206:209], v[8:11]
	v_mfma_f32_16x16x32_bf16 v[12:15], v[158:161], v[206:209], v[12:15]
	v_mfma_f32_16x16x32_bf16 v[56:59], v[154:157], v[186:189], v[56:59]
	v_mfma_f32_16x16x32_bf16 v[60:63], v[162:165], v[186:189], v[60:63]
	v_mfma_f32_16x16x32_bf16 v[40:43], v[154:157], v[194:197], v[40:43]
	v_mfma_f32_16x16x32_bf16 v[44:47], v[162:165], v[194:197], v[44:47]
	v_mfma_f32_16x16x32_bf16 v[24:27], v[154:157], v[202:205], v[24:27]
	v_mfma_f32_16x16x32_bf16 v[28:31], v[162:165], v[202:205], v[28:31]
	v_mfma_f32_16x16x32_bf16 v[8:11], v[154:157], v[210:213], v[8:11]
	v_mfma_f32_16x16x32_bf16 v[12:15], v[162:165], v[210:213], v[12:15]
	s_setprio 0
	s_setprio 1
	v_mfma_f32_16x16x32_bf16 v[48:51], v[166:169], v[182:185], v[48:51]
	v_mfma_f32_16x16x32_bf16 v[52:55], v[174:177], v[182:185], v[52:55]
	v_mfma_f32_16x16x32_bf16 v[32:35], v[166:169], v[190:193], v[32:35]
	v_mfma_f32_16x16x32_bf16 v[36:39], v[174:177], v[190:193], v[36:39]
	v_mfma_f32_16x16x32_bf16 v[16:19], v[166:169], v[198:201], v[16:19]
	v_mfma_f32_16x16x32_bf16 v[20:23], v[174:177], v[198:201], v[20:23]
	v_mfma_f32_16x16x32_bf16 v[0:3], v[166:169], v[206:209], v[0:3]
	v_mfma_f32_16x16x32_bf16 v[4:7], v[174:177], v[206:209], v[4:7]
	v_mfma_f32_16x16x32_bf16 v[48:51], v[170:173], v[186:189], v[48:51]
	v_mfma_f32_16x16x32_bf16 v[52:55], v[178:181], v[186:189], v[52:55]
	v_mfma_f32_16x16x32_bf16 v[32:35], v[170:173], v[194:197], v[32:35]
	v_mfma_f32_16x16x32_bf16 v[36:39], v[178:181], v[194:197], v[36:39]
	v_mfma_f32_16x16x32_bf16 v[16:19], v[170:173], v[202:205], v[16:19]
	v_mfma_f32_16x16x32_bf16 v[20:23], v[178:181], v[202:205], v[20:23]
	v_mfma_f32_16x16x32_bf16 v[0:3], v[170:173], v[210:213], v[0:3]
	v_mfma_f32_16x16x32_bf16 v[4:7], v[178:181], v[210:213], v[4:7]
	s_barrier
	s_setprio 0
	s_add_i32 s48, s48, 2
	s_add_u32 s16, s16, 0x100
	s_addc_u32 s17, s17, 0
	s_add_u32 s46, s46, 0x100
	s_addc_u32 s47, s47, 0
	s_cmpk_gt_u32 s48, 0x55
.LBB0_1566:
	ds_read_b128 v[144:147], v151
	ds_read_b128 v[154:157], v151 offset:1024
	ds_read_b128 v[158:161], v151 offset:2048
	ds_read_b128 v[162:165], v151 offset:3072
	ds_read_b128 v[166:169], v152
	ds_read_b128 v[170:173], v152 offset:1024
	ds_read_b128 v[174:177], v152 offset:2048
	ds_read_b128 v[178:181], v152 offset:3072
	s_add_u32 s20, s16, 0xffea0080
	s_addc_u32 s21, s17, -1
	s_cmpk_eq_i32 s48, 0x54
	s_cselect_b32 s27, s5, s21
	s_cselect_b32 s26, s4, s20
	s_cselect_b32 s21, s15, s47
	s_cselect_b32 s20, s14, s46
	s_add_i32 m0, s30, 0xc000
	ds_read_b128 v[182:185], v153
	ds_read_b128 v[186:189], v153 offset:1024
	ds_read_b128 v[190:193], v153 offset:2048
	ds_read_b128 v[194:197], v153 offset:3072
	ds_read_b128 v[198:201], v153 offset:4096
	ds_read_b128 v[202:205], v153 offset:5120
	ds_read_b128 v[206:209], v153 offset:6144
	ds_read_b128 v[210:213], v153 offset:7168
	global_load_lds_dwordx4 v136, s[16:17]
	s_add_i32 m0, s30, 0xe000
	s_nop 0
	global_load_lds_dwordx4 v138, s[16:17]
	s_setprio 1
	s_waitcnt vmcnt(8) lgkmcnt(0)
	s_barrier
	v_mfma_f32_16x16x32_bf16 v[124:127], v[144:147], v[182:185], v[124:127]
	v_mfma_f32_16x16x32_bf16 v[120:123], v[158:161], v[182:185], v[120:123]
	v_mfma_f32_16x16x32_bf16 v[108:111], v[144:147], v[190:193], v[108:111]
	v_mfma_f32_16x16x32_bf16 v[104:107], v[158:161], v[190:193], v[104:107]
	v_mfma_f32_16x16x32_bf16 v[88:91], v[144:147], v[198:201], v[88:91]
	v_mfma_f32_16x16x32_bf16 v[92:95], v[158:161], v[198:201], v[92:95]
	v_mfma_f32_16x16x32_bf16 v[72:75], v[144:147], v[206:209], v[72:75]
	v_mfma_f32_16x16x32_bf16 v[76:79], v[158:161], v[206:209], v[76:79]
	v_mfma_f32_16x16x32_bf16 v[124:127], v[154:157], v[186:189], v[124:127]
	v_mfma_f32_16x16x32_bf16 v[120:123], v[162:165], v[186:189], v[120:123]
	v_mfma_f32_16x16x32_bf16 v[108:111], v[154:157], v[194:197], v[108:111]
	v_mfma_f32_16x16x32_bf16 v[104:107], v[162:165], v[194:197], v[104:107]
	v_mfma_f32_16x16x32_bf16 v[88:91], v[154:157], v[202:205], v[88:91]
	v_mfma_f32_16x16x32_bf16 v[92:95], v[162:165], v[202:205], v[92:95]
	v_mfma_f32_16x16x32_bf16 v[72:75], v[154:157], v[210:213], v[72:75]
	v_mfma_f32_16x16x32_bf16 v[76:79], v[162:165], v[210:213], v[76:79]
	s_setprio 0
	s_setprio 1
	v_mfma_f32_16x16x32_bf16 v[116:119], v[166:169], v[182:185], v[116:119]
	v_mfma_f32_16x16x32_bf16 v[112:115], v[174:177], v[182:185], v[112:115]
	v_mfma_f32_16x16x32_bf16 v[96:99], v[166:169], v[190:193], v[96:99]
	v_mfma_f32_16x16x32_bf16 v[100:103], v[174:177], v[190:193], v[100:103]
	v_mfma_f32_16x16x32_bf16 v[80:83], v[166:169], v[198:201], v[80:83]
	v_mfma_f32_16x16x32_bf16 v[84:87], v[174:177], v[198:201], v[84:87]
	v_mfma_f32_16x16x32_bf16 v[64:67], v[166:169], v[206:209], v[64:67]
	v_mfma_f32_16x16x32_bf16 v[68:71], v[174:177], v[206:209], v[68:71]
	v_mfma_f32_16x16x32_bf16 v[116:119], v[170:173], v[186:189], v[116:119]
	v_mfma_f32_16x16x32_bf16 v[112:115], v[178:181], v[186:189], v[112:115]
	v_mfma_f32_16x16x32_bf16 v[96:99], v[170:173], v[194:197], v[96:99]
	v_mfma_f32_16x16x32_bf16 v[100:103], v[178:181], v[194:197], v[100:103]
	v_mfma_f32_16x16x32_bf16 v[80:83], v[170:173], v[202:205], v[80:83]
	v_mfma_f32_16x16x32_bf16 v[84:87], v[178:181], v[202:205], v[84:87]
	v_mfma_f32_16x16x32_bf16 v[64:67], v[170:173], v[210:213], v[64:67]
	v_mfma_f32_16x16x32_bf16 v[68:71], v[178:181], v[210:213], v[68:71]
	s_barrier
	s_setprio 0
	s_add_i32 s49, s40, s29
	s_add_u32 s98, s20, 0x80
	s_addc_u32 s99, s21, 0
	s_mov_b32 m0, s49
	ds_read_b128 v[182:185], v153 offset:16384
	ds_read_b128 v[186:189], v153 offset:17408
	ds_read_b128 v[190:193], v153 offset:18432
	ds_read_b128 v[194:197], v153 offset:19456
	ds_read_b128 v[198:201], v153 offset:20480
	ds_read_b128 v[202:205], v153 offset:21504
	ds_read_b128 v[206:209], v153 offset:22528
	ds_read_b128 v[210:213], v153 offset:23552
	global_load_lds_dwordx4 v130, s[20:21]
	s_add_i32 m0, s49, 0x2000
	s_add_u32 s52, s20, 0x160000
	s_addc_u32 s53, s21, 0
	s_add_i32 s49, s41, s29
	global_load_lds_dwordx4 v134, s[20:21]
	s_mov_b32 m0, s49
	s_nop 0
	global_load_lds_dwordx4 v130, s[52:53]
	s_add_i32 m0, s49, 0x2000
	s_nop 0
	global_load_lds_dwordx4 v134, s[52:53]
	s_add_u32 s100, s26, 0x80
	s_addc_u32 s101, s27, 0
	s_mov_b32 m0, s30
	s_nop 0
	global_load_lds_dwordx4 v128, s[26:27]
	s_mov_b32 m0, s31
	s_nop 0
	global_load_lds_dwordx4 v132, s[26:27]
	s_setprio 1
	s_waitcnt vmcnt(8) lgkmcnt(0)
	s_barrier
	v_mfma_f32_16x16x32_bf16 v[56:59], v[144:147], v[182:185], v[56:59]
	v_mfma_f32_16x16x32_bf16 v[60:63], v[158:161], v[182:185], v[60:63]
	v_mfma_f32_16x16x32_bf16 v[40:43], v[144:147], v[190:193], v[40:43]
	v_mfma_f32_16x16x32_bf16 v[44:47], v[158:161], v[190:193], v[44:47]
	v_mfma_f32_16x16x32_bf16 v[24:27], v[144:147], v[198:201], v[24:27]
	v_mfma_f32_16x16x32_bf16 v[28:31], v[158:161], v[198:201], v[28:31]
	v_mfma_f32_16x16x32_bf16 v[8:11], v[144:147], v[206:209], v[8:11]
	v_mfma_f32_16x16x32_bf16 v[12:15], v[158:161], v[206:209], v[12:15]
	v_mfma_f32_16x16x32_bf16 v[56:59], v[154:157], v[186:189], v[56:59]
	v_mfma_f32_16x16x32_bf16 v[60:63], v[162:165], v[186:189], v[60:63]
	v_mfma_f32_16x16x32_bf16 v[40:43], v[154:157], v[194:197], v[40:43]
	v_mfma_f32_16x16x32_bf16 v[44:47], v[162:165], v[194:197], v[44:47]
	v_mfma_f32_16x16x32_bf16 v[24:27], v[154:157], v[202:205], v[24:27]
	v_mfma_f32_16x16x32_bf16 v[28:31], v[162:165], v[202:205], v[28:31]
	v_mfma_f32_16x16x32_bf16 v[8:11], v[154:157], v[210:213], v[8:11]
	v_mfma_f32_16x16x32_bf16 v[12:15], v[162:165], v[210:213], v[12:15]
	s_setprio 0
	s_setprio 1
	v_mfma_f32_16x16x32_bf16 v[48:51], v[166:169], v[182:185], v[48:51]
	v_mfma_f32_16x16x32_bf16 v[52:55], v[174:177], v[182:185], v[52:55]
	v_mfma_f32_16x16x32_bf16 v[32:35], v[166:169], v[190:193], v[32:35]
	v_mfma_f32_16x16x32_bf16 v[36:39], v[174:177], v[190:193], v[36:39]
	v_mfma_f32_16x16x32_bf16 v[16:19], v[166:169], v[198:201], v[16:19]
	v_mfma_f32_16x16x32_bf16 v[20:23], v[174:177], v[198:201], v[20:23]
	v_mfma_f32_16x16x32_bf16 v[0:3], v[166:169], v[206:209], v[0:3]
	v_mfma_f32_16x16x32_bf16 v[4:7], v[174:177], v[206:209], v[4:7]
	v_mfma_f32_16x16x32_bf16 v[48:51], v[170:173], v[186:189], v[48:51]
	v_mfma_f32_16x16x32_bf16 v[52:55], v[178:181], v[186:189], v[52:55]
	v_mfma_f32_16x16x32_bf16 v[32:35], v[170:173], v[194:197], v[32:35]
	v_mfma_f32_16x16x32_bf16 v[36:39], v[178:181], v[194:197], v[36:39]
	v_mfma_f32_16x16x32_bf16 v[16:19], v[170:173], v[202:205], v[16:19]
	v_mfma_f32_16x16x32_bf16 v[20:23], v[178:181], v[202:205], v[20:23]
	v_mfma_f32_16x16x32_bf16 v[0:3], v[170:173], v[210:213], v[0:3]
	v_mfma_f32_16x16x32_bf16 v[4:7], v[178:181], v[210:213], v[4:7]
	s_barrier
	s_setprio 0
	s_add_i32 s49, 0, 0x18000
	s_add_i32 s52, 0, 0x1c000
	ds_read_b128 v[144:147], v151 offset:32768
	ds_read_b128 v[154:157], v151 offset:33792
	ds_read_b128 v[158:161], v151 offset:34816
	ds_read_b128 v[162:165], v151 offset:35840
	ds_read_b128 v[166:169], v152 offset:32768
	ds_read_b128 v[170:173], v152 offset:33792
	ds_read_b128 v[174:177], v152 offset:34816
	ds_read_b128 v[178:181], v152 offset:35840
	s_add_u32 s26, s26, 0x160000
	s_addc_u32 s27, s27, 0
	s_mov_b32 m0, s34
	ds_read_b128 v[182:185], v153 offset:32768
	ds_read_b128 v[186:189], v153 offset:33792
	ds_read_b128 v[190:193], v153 offset:34816
	ds_read_b128 v[194:197], v153 offset:35840
	ds_read_b128 v[198:201], v153 offset:36864
	ds_read_b128 v[202:205], v153 offset:37888
	ds_read_b128 v[206:209], v153 offset:38912
	ds_read_b128 v[210:213], v153 offset:39936
	global_load_lds_dwordx4 v128, s[26:27]
	s_mov_b32 m0, s35
	s_nop 0
	global_load_lds_dwordx4 v132, s[26:27]
	s_setprio 1
	s_waitcnt vmcnt(8) lgkmcnt(0)
	s_barrier
	v_mfma_f32_16x16x32_bf16 v[124:127], v[144:147], v[182:185], v[124:127]
	v_mfma_f32_16x16x32_bf16 v[120:123], v[158:161], v[182:185], v[120:123]
	v_mfma_f32_16x16x32_bf16 v[108:111], v[144:147], v[190:193], v[108:111]
	v_mfma_f32_16x16x32_bf16 v[104:107], v[158:161], v[190:193], v[104:107]
	v_mfma_f32_16x16x32_bf16 v[88:91], v[144:147], v[198:201], v[88:91]
	v_mfma_f32_16x16x32_bf16 v[92:95], v[158:161], v[198:201], v[92:95]
	v_mfma_f32_16x16x32_bf16 v[72:75], v[144:147], v[206:209], v[72:75]
	v_mfma_f32_16x16x32_bf16 v[76:79], v[158:161], v[206:209], v[76:79]
	v_mfma_f32_16x16x32_bf16 v[124:127], v[154:157], v[186:189], v[124:127]
	v_mfma_f32_16x16x32_bf16 v[120:123], v[162:165], v[186:189], v[120:123]
	v_mfma_f32_16x16x32_bf16 v[108:111], v[154:157], v[194:197], v[108:111]
	v_mfma_f32_16x16x32_bf16 v[104:107], v[162:165], v[194:197], v[104:107]
	v_mfma_f32_16x16x32_bf16 v[88:91], v[154:157], v[202:205], v[88:91]
	v_mfma_f32_16x16x32_bf16 v[92:95], v[162:165], v[202:205], v[92:95]
	v_mfma_f32_16x16x32_bf16 v[72:75], v[154:157], v[210:213], v[72:75]
	v_mfma_f32_16x16x32_bf16 v[76:79], v[162:165], v[210:213], v[76:79]
	s_setprio 0
	s_setprio 1
	v_mfma_f32_16x16x32_bf16 v[116:119], v[166:169], v[182:185], v[116:119]
	v_mfma_f32_16x16x32_bf16 v[112:115], v[174:177], v[182:185], v[112:115]
	v_mfma_f32_16x16x32_bf16 v[96:99], v[166:169], v[190:193], v[96:99]
	v_mfma_f32_16x16x32_bf16 v[100:103], v[174:177], v[190:193], v[100:103]
	v_mfma_f32_16x16x32_bf16 v[80:83], v[166:169], v[198:201], v[80:83]
	v_mfma_f32_16x16x32_bf16 v[84:87], v[174:177], v[198:201], v[84:87]
	v_mfma_f32_16x16x32_bf16 v[64:67], v[166:169], v[206:209], v[64:67]
	v_mfma_f32_16x16x32_bf16 v[68:71], v[174:177], v[206:209], v[68:71]
	v_mfma_f32_16x16x32_bf16 v[116:119], v[170:173], v[186:189], v[116:119]
	v_mfma_f32_16x16x32_bf16 v[112:115], v[178:181], v[186:189], v[112:115]
	v_mfma_f32_16x16x32_bf16 v[96:99], v[170:173], v[194:197], v[96:99]
	v_mfma_f32_16x16x32_bf16 v[100:103], v[178:181], v[194:197], v[100:103]
	v_mfma_f32_16x16x32_bf16 v[80:83], v[170:173], v[202:205], v[80:83]
	v_mfma_f32_16x16x32_bf16 v[84:87], v[178:181], v[202:205], v[84:87]
	v_mfma_f32_16x16x32_bf16 v[64:67], v[170:173], v[210:213], v[64:67]
	v_mfma_f32_16x16x32_bf16 v[68:71], v[178:181], v[210:213], v[68:71]
	s_barrier
	s_setprio 0
	s_add_i32 s26, s49, s29
	s_mov_b32 m0, s26
	ds_read_b128 v[182:185], v153 offset:49152
	ds_read_b128 v[186:189], v153 offset:50176
	ds_read_b128 v[190:193], v153 offset:51200
	ds_read_b128 v[194:197], v153 offset:52224
	ds_read_b128 v[198:201], v153 offset:53248
	ds_read_b128 v[202:205], v153 offset:54272
	ds_read_b128 v[206:209], v153 offset:55296
	ds_read_b128 v[210:213], v153 offset:56320
	global_load_lds_dwordx4 v130, s[98:99]
	s_add_i32 m0, s26, 0x2000
	s_add_u32 s20, s20, 0x160080
	s_addc_u32 s21, s21, 0
	s_add_i32 s26, s52, s29
	global_load_lds_dwordx4 v134, s[98:99]
	s_mov_b32 m0, s26
	s_nop 0
	global_load_lds_dwordx4 v130, s[20:21]
	s_add_i32 m0, s26, 0x2000
	s_nop 0
	global_load_lds_dwordx4 v134, s[20:21]
	s_mov_b32 m0, s37
	s_nop 0
	global_load_lds_dwordx4 v128, s[100:101]
	s_mov_b32 m0, s38
	s_nop 0
	global_load_lds_dwordx4 v132, s[100:101]
	s_add_i32 s48, s48, 2
	s_add_u32 s16, s16, 0x100
	s_addc_u32 s17, s17, 0
	s_add_u32 s46, s46, 0x100
	s_addc_u32 s47, s47, 0
	s_cmpk_gt_u32 s48, 0x55
	s_setprio 1
	s_waitcnt vmcnt(8) lgkmcnt(0)
	s_barrier
	v_mfma_f32_16x16x32_bf16 v[56:59], v[144:147], v[182:185], v[56:59]
	v_mfma_f32_16x16x32_bf16 v[60:63], v[158:161], v[182:185], v[60:63]
	v_mfma_f32_16x16x32_bf16 v[40:43], v[144:147], v[190:193], v[40:43]
	v_mfma_f32_16x16x32_bf16 v[44:47], v[158:161], v[190:193], v[44:47]
	v_mfma_f32_16x16x32_bf16 v[24:27], v[144:147], v[198:201], v[24:27]
	v_mfma_f32_16x16x32_bf16 v[28:31], v[158:161], v[198:201], v[28:31]
	v_mfma_f32_16x16x32_bf16 v[8:11], v[144:147], v[206:209], v[8:11]
	v_mfma_f32_16x16x32_bf16 v[12:15], v[158:161], v[206:209], v[12:15]
	v_mfma_f32_16x16x32_bf16 v[56:59], v[154:157], v[186:189], v[56:59]
	v_mfma_f32_16x16x32_bf16 v[60:63], v[162:165], v[186:189], v[60:63]
	v_mfma_f32_16x16x32_bf16 v[40:43], v[154:157], v[194:197], v[40:43]
	v_mfma_f32_16x16x32_bf16 v[44:47], v[162:165], v[194:197], v[44:47]
	v_mfma_f32_16x16x32_bf16 v[24:27], v[154:157], v[202:205], v[24:27]
	v_mfma_f32_16x16x32_bf16 v[28:31], v[162:165], v[202:205], v[28:31]
	v_mfma_f32_16x16x32_bf16 v[8:11], v[154:157], v[210:213], v[8:11]
	v_mfma_f32_16x16x32_bf16 v[12:15], v[162:165], v[210:213], v[12:15]
	s_setprio 0
	s_setprio 1
	v_mfma_f32_16x16x32_bf16 v[48:51], v[166:169], v[182:185], v[48:51]
	v_mfma_f32_16x16x32_bf16 v[52:55], v[174:177], v[182:185], v[52:55]
	v_mfma_f32_16x16x32_bf16 v[32:35], v[166:169], v[190:193], v[32:35]
	v_mfma_f32_16x16x32_bf16 v[36:39], v[174:177], v[190:193], v[36:39]
	v_mfma_f32_16x16x32_bf16 v[16:19], v[166:169], v[198:201], v[16:19]
	v_mfma_f32_16x16x32_bf16 v[20:23], v[174:177], v[198:201], v[20:23]
	v_mfma_f32_16x16x32_bf16 v[0:3], v[166:169], v[206:209], v[0:3]
	v_mfma_f32_16x16x32_bf16 v[4:7], v[174:177], v[206:209], v[4:7]
	v_mfma_f32_16x16x32_bf16 v[48:51], v[170:173], v[186:189], v[48:51]
	v_mfma_f32_16x16x32_bf16 v[52:55], v[178:181], v[186:189], v[52:55]
	v_mfma_f32_16x16x32_bf16 v[32:35], v[170:173], v[194:197], v[32:35]
	v_mfma_f32_16x16x32_bf16 v[36:39], v[178:181], v[194:197], v[36:39]
	v_mfma_f32_16x16x32_bf16 v[16:19], v[170:173], v[202:205], v[16:19]
	v_mfma_f32_16x16x32_bf16 v[20:23], v[178:181], v[202:205], v[20:23]
	v_mfma_f32_16x16x32_bf16 v[0:3], v[170:173], v[210:213], v[0:3]
	v_mfma_f32_16x16x32_bf16 v[4:7], v[178:181], v[210:213], v[4:7]
	s_barrier
	s_setprio 0
	s_cbranch_scc0 .LBB0_1566
	s_and_b64 vcc, exec, s[10:11]
	s_cbranch_vccz .LBB0_1569
	s_barrier
